# comb21 + tile-boundary overlap: the next tile's first LDS fragment reads are issued at the tile-loop header, ahead of the tile scheduler's scalar decode (8 of 19 GEMM instances incl. both gate/up GEMM
# baseline (speedup 1.0000x reference)
; #define PG8_STAGE(bufoff, gbase, voff) do { _Pragma("unroll") for (int _i = 0; _i < 2; ++_i) \
;         __builtin_amdgcn_global_load_lds((const unsigned*)((const char*)(gbase) + (voff)[_i]), (LAS unsigned*)(lds + (bufoff) + ldsw + _i * 8192), 16, 0, 0); } while (0)
; #define PG8_LDA(dst, b, h) do { _Pragma("unroll") for (int m = 0; m < 4; ++m) _Pragma("unroll") for (int k = 0; k < 2; ++k) dst[m][k] = *(const LAS bf16x8*)(lds + PG8_SA(b, h) + aoff + m * 2048 + k * 1024); } while (0)
; #define PG8_LDB(dst, b, h) do { _Pragma("unroll") for (int n = 0; n < 2; ++n) _Pragma("unroll") for (int k = 0; k < 2; ++k) dst[n][k] = *(const LAS bf16x8*)(lds + PG8_SB(b, h) + boff + n * 2048 + k * 1024); } while (0)
; #define PG8_SCHED __builtin_amdgcn_sched_barrier(0)
;     __device__ __forceinline__ bool next(int i, Unit& u) const {
;         const long L = (long)i * G + c; if (L >= nwg) return false;
;         int w = (int)L; { const int q = nwg / NXCD, r = nwg % NXCD, xcd = w % NXCD, off = w / NXCD; w = (xcd < r ? xcd * (q + 1) : r * (q + 1) + (xcd - r) * q) + off; }
;         u.pb = w / per; w -= u.pb * per;
;         const int nig = WGM * nN, gid = w / nig, fm = gid * WGM, gsz = (nM - fm) < WGM ? (nM - fm) : WGM;
;         u.pm = fm + ((w % nig) % gsz); u.pn = (w % nig) / gsz; return true;
; template <class Epi>
; __device__ __forceinline__ void gemm_phase(LAS unsigned char* lds, const Gemm g, int G, int c, const Epi& E) {
;     ...
;             PG8_LDB(B0, 0, 0); PG8_LDB(B1, 0, 1); PG8_SCHED; PG8_LDA(At, 0, 0); PG8_STAGE(PG8_SA(1, 1), a1 + hstepA, voffA);
.LBB0_361:
	ds_read_b128 v[142:145], v148
	ds_read_b128 v[152:155], v148 offset:1024
	ds_read_b128 v[156:159], v148 offset:2048
	ds_read_b128 v[160:163], v148 offset:3072
	ds_read_b128 v[164:167], v149
	ds_read_b128 v[168:171], v149 offset:1024
	ds_read_b128 v[172:175], v149 offset:2048
	ds_read_b128 v[176:179], v149 offset:3072
	ds_read_b128 v[180:183], v150
	ds_read_b128 v[184:187], v150 offset:1024
	ds_read_b128 v[188:191], v150 offset:2048
	ds_read_b128 v[192:195], v150 offset:3072
	ds_read_b128 v[196:199], v150 offset:4096
	ds_read_b128 v[200:203], v150 offset:5120
	ds_read_b128 v[204:207], v150 offset:6144
	ds_read_b128 v[208:211], v150 offset:7168
	s_add_i32 s61, s61, 1
	s_mul_i32 s2, s61, s70
	s_mul_hi_u32 s3, s61, s27
	s_add_i32 s3, s3, s2
	s_mul_i32 s2, s61, s27
	s_add_u32 s2, s2, s26
	s_addc_u32 s3, s3, s71
	v_cmp_gt_i64_e32 vcc, s[2:3], v[140:141]
	v_cmp_lt_i64_e64 s[4:5], s[2:3], v[138:139]
	s_cbranch_vccnz .LBB0_363
	s_ashr_i32 s3, s2, 31
	s_lshr_b32 s3, s3, 29
	s_add_i32 s3, s2, s3
	s_ashr_i32 s13, s3, 3
	s_and_b32 s3, s3, -8
	s_sub_i32 s2, s2, s3
	s_lshr_b32 s3, s2, 31
	s_or_b32 s3, s3, 0x48
	s_mul_i32 s2, s3, s2
	s_add_i32 s2, s2, s13
	s_mul_hi_i32 s3, s2, 0x38e38e39
	s_lshr_b32 s13, s3, 31
	s_ashr_i32 s3, s3, 2
	s_add_i32 s83, s3, s13
	s_mul_i32 s3, s83, 0xffffffee
	s_add_i32 s3, s3, s2
	s_mul_hi_i32 s2, s3, 0x38e38e39
	s_lshr_b32 s13, s2, 31
	s_ashr_i32 s2, s2, 4
	s_add_i32 s2, s2, s13
	s_lshl_b32 s13, s2, 3
	s_sub_i32 s16, 2, s13
	s_min_i32 s16, s16, 8
	s_abs_i32 s17, s16
	v_cvt_f32_u32_e32 v2, s17
	s_sub_i32 s23, 0, s17
	s_mulk_i32 s2, 0x48
	s_sub_i32 s2, s3, s2
	v_rcp_iflag_f32_e32 v2, v2
	s_abs_i32 s3, s2
	s_xor_b32 s22, s2, s16
	s_ashr_i32 s22, s22, 31
	v_mul_f32_e32 v2, 0x4f7ffffe, v2
	v_cvt_u32_f32_e32 v2, v2
	s_nop 0
	v_readfirstlane_b32 s24, v2
	s_mul_i32 s23, s23, s24
	s_mul_hi_u32 s23, s24, s23
	s_add_i32 s24, s24, s23
	s_mul_hi_u32 s23, s3, s24
	s_mul_i32 s24, s23, s17
	s_sub_i32 s3, s3, s24
	s_add_i32 s24, s23, 1
	s_sub_i32 s25, s3, s17
	s_cmp_ge_u32 s3, s17
	s_cselect_b32 s23, s24, s23
	s_cselect_b32 s3, s25, s3
	s_add_i32 s24, s23, 1
	s_cmp_ge_u32 s3, s17
	s_cselect_b32 s3, s24, s23
	s_xor_b32 s3, s3, s22
	s_sub_i32 s84, s3, s22
	s_mul_i32 s3, s84, s16
	s_sub_i32 s2, s2, s3
	s_add_i32 s85, s2, s13

; #define PG8_STAGE(bufoff, gbase, voff) do { _Pragma("unroll") for (int _i = 0; _i < 2; ++_i) \
;         __builtin_amdgcn_global_load_lds((const unsigned*)((const char*)(gbase) + (voff)[_i]), (LAS unsigned*)(lds + (bufoff) + ldsw + _i * 8192), 16, 0, 0); } while (0)
; #define PG8_LDA(dst, b, h) do { _Pragma("unroll") for (int m = 0; m < 4; ++m) _Pragma("unroll") for (int k = 0; k < 2; ++k) dst[m][k] = *(const LAS bf16x8*)(lds + PG8_SA(b, h) + aoff + m * 2048 + k * 1024); } while (0)
; #define PG8_LDB(dst, b, h) do { _Pragma("unroll") for (int n = 0; n < 2; ++n) _Pragma("unroll") for (int k = 0; k < 2; ++k) dst[n][k] = *(const LAS bf16x8*)(lds + PG8_SB(b, h) + boff + n * 2048 + k * 1024); } while (0)
; #define PG8_MMA(ai, bj, At, Bt) do { __builtin_amdgcn_s_setprio(1); _Pragma("unroll") for (int m = 0; m < 4; ++m) _Pragma("unroll") for (int n = 0; n < 2; ++n) _Pragma("unroll") for (int k = 0; k < 2; ++k) \
;         acc[ai][bj][m][n] = __builtin_amdgcn_mfma_f32_16x16x32_bf16(Bt[n][k], At[m][k], acc[ai][bj][m][n], 0, 0, 0); __builtin_amdgcn_s_setprio(0); } while (0)
; #define PG8_WAIT_V(n) asm volatile("s_waitcnt vmcnt(" #n ")" ::: "memory")
; #define PG8_WAIT_L(n) asm volatile("s_waitcnt lgkmcnt(" #n ")" ::: "memory")
; #define PG8_BAR __builtin_amdgcn_s_barrier()
; #define PG8_SCHED __builtin_amdgcn_sched_barrier(0)
; template <class Epi>
; __device__ __forceinline__ void gemm_phase(LAS unsigned char* lds, const Gemm g, int G, int c, const Epi& E) {
;     ...
;             const char* a1 = cA + (size_t)(t + 1) * kstep;
;             const char* a2 = last ? nA : cA + (size_t)(t + 2) * kstep; const char* b2 = last ? nB : cB + (size_t)(t + 2) * kstep;
;             const char* a3 = a2 + kstep; const char* b3 = b2 + kstep;
;             PG8_LDB(B0, 0, 0); PG8_LDB(B1, 0, 1); PG8_SCHED; PG8_LDA(At, 0, 0); PG8_STAGE(PG8_SA(1, 1), a1 + hstepA, voffA);
;             PG8_WAIT_V(8); PG8_WAIT_L(0); PG8_BAR; PG8_MMA(0, 0, At, B0); PG8_MMA(0, 1, At, B1); PG8_BAR; PG8_SCHED;
;             PG8_LDA(At, 0, 1); PG8_STAGE(PG8_SB(0, 0), b2, voffB); PG8_STAGE(PG8_SB(0, 1), b2 + hstepB, voffB); PG8_STAGE(PG8_SA(0, 0), a2, voffA);
;             PG8_WAIT_V(8); PG8_WAIT_L(0); PG8_BAR; PG8_MMA(1, 0, At, B0); PG8_MMA(1, 1, At, B1); PG8_BAR; PG8_SCHED;
.LBB0_367:
	s_mov_b32 s13, 0
	s_mov_b64 s[22:23], -1
	s_mov_b64 s[24:25], 0
	s_add_u32 s33, s20, s13
	s_addc_u32 s42, s21, 0
	s_add_u32 s43, s33, 0x100
	s_addc_u32 s44, s42, 0
	s_and_b64 s[38:39], s[24:25], exec
	s_cselect_b32 s45, s5, s44
	s_cselect_b32 s44, s4, s43
	s_add_u32 s13, s18, s13
	s_addc_u32 s38, s19, 0
	s_add_u32 s13, s13, 0x100
	s_addc_u32 s38, s38, 0
	s_and_b64 s[24:25], s[24:25], exec
	s_cselect_b32 s47, s17, s38
	s_cselect_b32 s46, s16, s13
	s_add_u32 s54, s33, 0xb0080
	s_addc_u32 s55, s42, 0
	s_add_i32 s65, s81, s56
	s_add_i32 m0, s57, 0xc000
	s_add_i32 s74, s57, 0xe000
	s_add_i32 s62, s65, 0x2000
	s_add_u32 s52, s46, 0xb0000
	s_addc_u32 s53, s47, 0
	s_add_i32 s64, s82, s56
	s_add_i32 s63, s64, 0x2000
	s_add_i32 s73, 0, 0x18000
	s_add_i32 s33, 0, 0x1c000
	s_add_u32 s42, s44, 0xb0000
	s_addc_u32 s43, s45, 0
	s_add_i32 s88, s73, s56
	s_add_i32 s38, s88, 0x2000
	s_add_u32 s24, s46, 0xb0080
	s_addc_u32 s25, s47, 0
	s_add_i32 s39, s33, s56
	s_add_i32 s13, s39, 0x2000
	v_lshl_add_u64 v[212:213], s[54:55], 0, v[136:137]
	global_load_lds_dwordx4 v[212:213], off
	v_lshl_add_u64 v[212:213], s[54:55], 0, v[132:133]
	s_mov_b32 m0, s74
	s_nop 0
	global_load_lds_dwordx4 v[212:213], off
	s_waitcnt vmcnt(8)
	s_waitcnt lgkmcnt(0)
	s_barrier
	s_setprio 0
	v_mfma_f32_16x16x32_bf16 v[126:129], v[142:145], v[180:183], 0
	v_mfma_f32_16x16x32_bf16 v[122:125], v[156:159], v[180:183], 0
	v_mfma_f32_16x16x32_bf16 v[118:121], v[142:145], v[188:191], 0
	v_mfma_f32_16x16x32_bf16 v[110:113], v[156:159], v[188:191], 0
	v_mfma_f32_16x16x32_bf16 v[102:105], v[142:145], v[196:199], 0
	v_mfma_f32_16x16x32_bf16 v[94:97], v[156:159], v[196:199], 0
	v_mfma_f32_16x16x32_bf16 v[86:89], v[142:145], v[204:207], 0
	v_mfma_f32_16x16x32_bf16 v[78:81], v[156:159], v[204:207], 0
	v_mfma_f32_16x16x32_bf16 v[126:129], v[152:155], v[184:187], v[126:129]
	v_mfma_f32_16x16x32_bf16 v[122:125], v[160:163], v[184:187], v[122:125]
	v_mfma_f32_16x16x32_bf16 v[118:121], v[152:155], v[192:195], v[118:121]
	v_mfma_f32_16x16x32_bf16 v[110:113], v[160:163], v[192:195], v[110:113]
	v_mfma_f32_16x16x32_bf16 v[102:105], v[152:155], v[200:203], v[102:105]
	v_mfma_f32_16x16x32_bf16 v[94:97], v[160:163], v[200:203], v[94:97]
	v_mfma_f32_16x16x32_bf16 v[86:89], v[152:155], v[208:211], v[86:89]
	v_mfma_f32_16x16x32_bf16 v[78:81], v[160:163], v[208:211], v[78:81]
	s_setprio 2
	s_setprio 0
	v_mfma_f32_16x16x32_bf16 v[114:117], v[164:167], v[180:183], 0
	v_mfma_f32_16x16x32_bf16 v[106:109], v[172:175], v[180:183], 0
	v_mfma_f32_16x16x32_bf16 v[98:101], v[164:167], v[188:191], 0
	v_mfma_f32_16x16x32_bf16 v[90:93], v[172:175], v[188:191], 0
	v_mfma_f32_16x16x32_bf16 v[82:85], v[164:167], v[196:199], 0
	v_mfma_f32_16x16x32_bf16 v[74:77], v[172:175], v[196:199], 0
	v_mfma_f32_16x16x32_bf16 v[70:73], v[164:167], v[204:207], 0
	v_mfma_f32_16x16x32_bf16 v[66:69], v[172:175], v[204:207], 0
	v_mfma_f32_16x16x32_bf16 v[114:117], v[168:171], v[184:187], v[114:117]
	v_mfma_f32_16x16x32_bf16 v[106:109], v[176:179], v[184:187], v[106:109]
	v_mfma_f32_16x16x32_bf16 v[98:101], v[168:171], v[192:195], v[98:101]
	v_mfma_f32_16x16x32_bf16 v[90:93], v[176:179], v[192:195], v[90:93]
	v_mfma_f32_16x16x32_bf16 v[82:85], v[168:171], v[200:203], v[82:85]
	v_mfma_f32_16x16x32_bf16 v[74:77], v[176:179], v[200:203], v[74:77]
	v_mfma_f32_16x16x32_bf16 v[70:73], v[168:171], v[208:211], v[70:73]
	v_mfma_f32_16x16x32_bf16 v[66:69], v[176:179], v[208:211], v[66:69]
	s_setprio 2
	s_barrier
	s_mov_b32 m0, s65
	v_lshl_add_u64 v[212:213], s[46:47], 0, v[134:135]
	ds_read_b128 v[180:183], v150 offset:16384
	ds_read_b128 v[184:187], v150 offset:17408
	ds_read_b128 v[188:191], v150 offset:18432
	ds_read_b128 v[192:195], v150 offset:19456
	ds_read_b128 v[196:199], v150 offset:20480
	ds_read_b128 v[200:203], v150 offset:21504
	ds_read_b128 v[204:207], v150 offset:22528
	ds_read_b128 v[208:211], v150 offset:23552
	global_load_lds_dwordx4 v[212:213], off
	v_lshl_add_u64 v[214:215], s[46:47], 0, v[130:131]
	s_mov_b32 m0, s62
	v_lshl_add_u64 v[216:217], s[52:53], 0, v[134:135]
	global_load_lds_dwordx4 v[214:215], off
	s_mov_b32 m0, s64
	v_lshl_add_u64 v[218:219], s[44:45], 0, v[132:133]
	global_load_lds_dwordx4 v[216:217], off
	v_lshl_add_u64 v[216:217], s[52:53], 0, v[130:131]
	s_mov_b32 m0, s63
	s_nop 0
	global_load_lds_dwordx4 v[216:217], off
	v_lshl_add_u64 v[216:217], s[44:45], 0, v[136:137]
	s_mov_b32 m0, s57
	s_nop 0
	global_load_lds_dwordx4 v[216:217], off
	s_mov_b32 m0, s58
	s_nop 0
	global_load_lds_dwordx4 v[218:219], off
	s_waitcnt vmcnt(8)
	s_waitcnt lgkmcnt(0)
	s_barrier
; #define PG8_STAGE(bufoff, gbase, voff) do { _Pragma("unroll") for (int _i = 0; _i < 2; ++_i) \
;         __builtin_amdgcn_global_load_lds((const unsigned*)((const char*)(gbase) + (voff)[_i]), (LAS unsigned*)(lds + (bufoff) + ldsw + _i * 8192), 16, 0, 0); } while (0)
; #define PG8_LDA(dst, b, h) do { _Pragma("unroll") for (int m = 0; m < 4; ++m) _Pragma("unroll") for (int k = 0; k < 2; ++k) dst[m][k] = *(const LAS bf16x8*)(lds + PG8_SA(b, h) + aoff + m * 2048 + k * 1024); } while (0)
; #define PG8_LDB(dst, b, h) do { _Pragma("unroll") for (int n = 0; n < 2; ++n) _Pragma("unroll") for (int k = 0; k < 2; ++k) dst[n][k] = *(const LAS bf16x8*)(lds + PG8_SB(b, h) + boff + n * 2048 + k * 1024); } while (0)
; #define PG8_MMA(ai, bj, At, Bt) do { __builtin_amdgcn_s_setprio(1); _Pragma("unroll") for (int m = 0; m < 4; ++m) _Pragma("unroll") for (int n = 0; n < 2; ++n) _Pragma("unroll") for (int k = 0; k < 2; ++k) \
;         acc[ai][bj][m][n] = __builtin_amdgcn_mfma_f32_16x16x32_bf16(Bt[n][k], At[m][k], acc[ai][bj][m][n], 0, 0, 0); __builtin_amdgcn_s_setprio(0); } while (0)
; #define PG8_WAIT_V(n) asm volatile("s_waitcnt vmcnt(" #n ")" ::: "memory")
; #define PG8_WAIT_L(n) asm volatile("s_waitcnt lgkmcnt(" #n ")" ::: "memory")
; #define PG8_BAR __builtin_amdgcn_s_barrier()
; #define PG8_SCHED __builtin_amdgcn_sched_barrier(0)
; template <class Epi>
; __device__ __forceinline__ void gemm_phase(LAS unsigned char* lds, const Gemm g, int G, int c, const Epi& E) {
;     ...
;             PG8_WAIT_V(8); PG8_WAIT_L(0); PG8_BAR; PG8_MMA(1, 0, At, B0); PG8_MMA(1, 1, At, B1); PG8_BAR; PG8_SCHED;
;             PG8_LDB(B0, 1, 0); PG8_LDB(B1, 1, 1); PG8_SCHED; PG8_LDA(At, 1, 0); PG8_STAGE(PG8_SA(0, 1), a2 + hstepA, voffA);
;             PG8_WAIT_V(8); PG8_WAIT_L(0); PG8_BAR; PG8_MMA(0, 0, At, B0); PG8_MMA(0, 1, At, B1); PG8_BAR; PG8_SCHED;
	s_setprio 0
	v_mfma_f32_16x16x32_bf16 v[62:65], v[142:145], v[180:183], 0
	v_mfma_f32_16x16x32_bf16 v[58:61], v[156:159], v[180:183], 0
	v_mfma_f32_16x16x32_bf16 v[54:57], v[142:145], v[188:191], 0
	v_mfma_f32_16x16x32_bf16 v[46:49], v[156:159], v[188:191], 0
	v_mfma_f32_16x16x32_bf16 v[38:41], v[142:145], v[196:199], 0
	v_mfma_f32_16x16x32_bf16 v[30:33], v[156:159], v[196:199], 0
	v_mfma_f32_16x16x32_bf16 v[22:25], v[142:145], v[204:207], 0
	v_mfma_f32_16x16x32_bf16 v[14:17], v[156:159], v[204:207], 0
	v_mfma_f32_16x16x32_bf16 v[62:65], v[152:155], v[184:187], v[62:65]
	v_mfma_f32_16x16x32_bf16 v[58:61], v[160:163], v[184:187], v[58:61]
	v_mfma_f32_16x16x32_bf16 v[54:57], v[152:155], v[192:195], v[54:57]
	v_mfma_f32_16x16x32_bf16 v[46:49], v[160:163], v[192:195], v[46:49]
	v_mfma_f32_16x16x32_bf16 v[38:41], v[152:155], v[200:203], v[38:41]
	v_mfma_f32_16x16x32_bf16 v[30:33], v[160:163], v[200:203], v[30:33]
	v_mfma_f32_16x16x32_bf16 v[22:25], v[152:155], v[208:211], v[22:25]
	v_mfma_f32_16x16x32_bf16 v[14:17], v[160:163], v[208:211], v[14:17]
	s_setprio 2
	s_setprio 0
	v_mfma_f32_16x16x32_bf16 v[50:53], v[164:167], v[180:183], 0
	v_mfma_f32_16x16x32_bf16 v[42:45], v[172:175], v[180:183], 0
	v_mfma_f32_16x16x32_bf16 v[34:37], v[164:167], v[188:191], 0
	v_mfma_f32_16x16x32_bf16 v[26:29], v[172:175], v[188:191], 0
	v_mfma_f32_16x16x32_bf16 v[18:21], v[164:167], v[196:199], 0
	v_mfma_f32_16x16x32_bf16 v[10:13], v[172:175], v[196:199], 0
	v_mfma_f32_16x16x32_bf16 v[6:9], v[164:167], v[204:207], 0
	v_mfma_f32_16x16x32_bf16 v[2:5], v[172:175], v[204:207], 0
	v_mfma_f32_16x16x32_bf16 v[50:53], v[168:171], v[184:187], v[50:53]
	v_mfma_f32_16x16x32_bf16 v[42:45], v[176:179], v[184:187], v[42:45]
	v_mfma_f32_16x16x32_bf16 v[34:37], v[168:171], v[192:195], v[34:37]
	v_mfma_f32_16x16x32_bf16 v[26:29], v[176:179], v[192:195], v[26:29]
	v_mfma_f32_16x16x32_bf16 v[18:21], v[168:171], v[200:203], v[18:21]
	v_mfma_f32_16x16x32_bf16 v[10:13], v[176:179], v[200:203], v[10:13]
	v_mfma_f32_16x16x32_bf16 v[6:9], v[168:171], v[208:211], v[6:9]
	v_mfma_f32_16x16x32_bf16 v[2:5], v[176:179], v[208:211], v[2:5]
	s_setprio 2
	s_barrier
	v_add_u32_e32 v151, s73, v147
	ds_read_b128 v[142:145], v151
	ds_read_b128 v[152:155], v151 offset:1024
	ds_read_b128 v[156:159], v151 offset:2048
	ds_read_b128 v[160:163], v151 offset:3072
	v_add_u32_e32 v151, s33, v147
	ds_read_b128 v[164:167], v151
	ds_read_b128 v[168:171], v151 offset:1024
	ds_read_b128 v[172:175], v151 offset:2048
	ds_read_b128 v[176:179], v151 offset:3072
	s_mov_b32 m0, s59
	v_lshl_add_u64 v[220:221], s[42:43], 0, v[136:137]
	ds_read_b128 v[180:183], v150 offset:32768
	ds_read_b128 v[184:187], v150 offset:33792
	ds_read_b128 v[188:191], v150 offset:34816
	ds_read_b128 v[192:195], v150 offset:35840
	ds_read_b128 v[196:199], v150 offset:36864
	ds_read_b128 v[200:203], v150 offset:37888
	ds_read_b128 v[204:207], v150 offset:38912
	ds_read_b128 v[208:211], v150 offset:39936
	global_load_lds_dwordx4 v[220:221], off
	v_lshl_add_u64 v[220:221], s[42:43], 0, v[132:133]
	s_mov_b32 m0, s60
	s_nop 0
	global_load_lds_dwordx4 v[220:221], off
	s_waitcnt vmcnt(8)
	s_waitcnt lgkmcnt(0)
	s_barrier
	s_setprio 0
	v_mfma_f32_16x16x32_bf16 v[126:129], v[142:145], v[180:183], v[126:129]
	v_mfma_f32_16x16x32_bf16 v[122:125], v[156:159], v[180:183], v[122:125]
	v_mfma_f32_16x16x32_bf16 v[118:121], v[142:145], v[188:191], v[118:121]
	v_mfma_f32_16x16x32_bf16 v[110:113], v[156:159], v[188:191], v[110:113]
	v_mfma_f32_16x16x32_bf16 v[102:105], v[142:145], v[196:199], v[102:105]
	v_mfma_f32_16x16x32_bf16 v[94:97], v[156:159], v[196:199], v[94:97]
	v_mfma_f32_16x16x32_bf16 v[86:89], v[142:145], v[204:207], v[86:89]
	v_mfma_f32_16x16x32_bf16 v[78:81], v[156:159], v[204:207], v[78:81]
	v_mfma_f32_16x16x32_bf16 v[126:129], v[152:155], v[184:187], v[126:129]
	v_mfma_f32_16x16x32_bf16 v[122:125], v[160:163], v[184:187], v[122:125]
	v_mfma_f32_16x16x32_bf16 v[118:121], v[152:155], v[192:195], v[118:121]
	v_mfma_f32_16x16x32_bf16 v[110:113], v[160:163], v[192:195], v[110:113]
	v_mfma_f32_16x16x32_bf16 v[102:105], v[152:155], v[200:203], v[102:105]
	v_mfma_f32_16x16x32_bf16 v[94:97], v[160:163], v[200:203], v[94:97]
	v_mfma_f32_16x16x32_bf16 v[86:89], v[152:155], v[208:211], v[86:89]
	v_mfma_f32_16x16x32_bf16 v[78:81], v[160:163], v[208:211], v[78:81]
	s_setprio 2
	s_setprio 0
	v_mfma_f32_16x16x32_bf16 v[114:117], v[164:167], v[180:183], v[114:117]
	v_mfma_f32_16x16x32_bf16 v[106:109], v[172:175], v[180:183], v[106:109]
	v_mfma_f32_16x16x32_bf16 v[98:101], v[164:167], v[188:191], v[98:101]
	v_mfma_f32_16x16x32_bf16 v[90:93], v[172:175], v[188:191], v[90:93]
	v_mfma_f32_16x16x32_bf16 v[82:85], v[164:167], v[196:199], v[82:85]
	v_mfma_f32_16x16x32_bf16 v[74:77], v[172:175], v[196:199], v[74:77]
	v_mfma_f32_16x16x32_bf16 v[70:73], v[164:167], v[204:207], v[70:73]
	v_mfma_f32_16x16x32_bf16 v[66:69], v[172:175], v[204:207], v[66:69]
	v_mfma_f32_16x16x32_bf16 v[114:117], v[168:171], v[184:187], v[114:117]
	v_mfma_f32_16x16x32_bf16 v[106:109], v[176:179], v[184:187], v[106:109]
	v_mfma_f32_16x16x32_bf16 v[98:101], v[168:171], v[192:195], v[98:101]
	v_mfma_f32_16x16x32_bf16 v[90:93], v[176:179], v[192:195], v[90:93]
	v_mfma_f32_16x16x32_bf16 v[82:85], v[168:171], v[200:203], v[82:85]
	v_mfma_f32_16x16x32_bf16 v[74:77], v[176:179], v[200:203], v[74:77]
	v_mfma_f32_16x16x32_bf16 v[70:73], v[168:171], v[208:211], v[70:73]
	v_mfma_f32_16x16x32_bf16 v[66:69], v[176:179], v[208:211], v[66:69]
	s_setprio 2
	s_barrier
; #define PG8_STAGE(bufoff, gbase, voff) do { _Pragma("unroll") for (int _i = 0; _i < 2; ++_i) \
;         __builtin_amdgcn_global_load_lds((const unsigned*)((const char*)(gbase) + (voff)[_i]), (LAS unsigned*)(lds + (bufoff) + ldsw + _i * 8192), 16, 0, 0); } while (0)
; #define PG8_LDA(dst, b, h) do { _Pragma("unroll") for (int m = 0; m < 4; ++m) _Pragma("unroll") for (int k = 0; k < 2; ++k) dst[m][k] = *(const LAS bf16x8*)(lds + PG8_SA(b, h) + aoff + m * 2048 + k * 1024); } while (0)
; #define PG8_MMA(ai, bj, At, Bt) do { __builtin_amdgcn_s_setprio(1); _Pragma("unroll") for (int m = 0; m < 4; ++m) _Pragma("unroll") for (int n = 0; n < 2; ++n) _Pragma("unroll") for (int k = 0; k < 2; ++k) \
;         acc[ai][bj][m][n] = __builtin_amdgcn_mfma_f32_16x16x32_bf16(Bt[n][k], At[m][k], acc[ai][bj][m][n], 0, 0, 0); __builtin_amdgcn_s_setprio(0); } while (0)
; #define PG8_WAIT_V(n) asm volatile("s_waitcnt vmcnt(" #n ")" ::: "memory")
; #define PG8_WAIT_L(n) asm volatile("s_waitcnt lgkmcnt(" #n ")" ::: "memory")
; #define PG8_BAR __builtin_amdgcn_s_barrier()
; #define PG8_SCHED __builtin_amdgcn_sched_barrier(0)
; template <class Epi>
; __device__ __forceinline__ void gemm_phase(LAS unsigned char* lds, const Gemm g, int G, int c, const Epi& E) {
;     ...
;             PG8_LDA(At, 1, 1); PG8_STAGE(PG8_SB(1, 0), b3, voffB); PG8_STAGE(PG8_SB(1, 1), b3 + hstepB, voffB); PG8_STAGE(PG8_SA(1, 0), a3, voffA);
;             PG8_WAIT_V(8); PG8_WAIT_L(0); PG8_BAR; PG8_MMA(1, 0, At, B0); PG8_MMA(1, 1, At, B1); PG8_BAR; PG8_SCHED;
;         }
	s_mov_b32 m0, s88
	v_lshl_add_u64 v[212:213], v[212:213], 0, s[8:9]
	ds_read_b128 v[180:183], v150 offset:49152
	ds_read_b128 v[184:187], v150 offset:50176
	ds_read_b128 v[188:191], v150 offset:51200
	ds_read_b128 v[192:195], v150 offset:52224
	ds_read_b128 v[196:199], v150 offset:53248
	ds_read_b128 v[200:203], v150 offset:54272
	ds_read_b128 v[204:207], v150 offset:55296
	ds_read_b128 v[208:211], v150 offset:56320
	global_load_lds_dwordx4 v[212:213], off
	v_lshl_add_u64 v[212:213], v[214:215], 0, s[8:9]
	s_mov_b32 m0, s38
	s_nop 0
	global_load_lds_dwordx4 v[212:213], off
	v_lshl_add_u64 v[212:213], s[24:25], 0, v[134:135]
	s_mov_b32 m0, s39
	s_nop 0
	global_load_lds_dwordx4 v[212:213], off
	v_lshl_add_u64 v[212:213], s[24:25], 0, v[130:131]
	s_mov_b32 m0, s13
	s_nop 0
	global_load_lds_dwordx4 v[212:213], off
	v_lshl_add_u64 v[212:213], v[216:217], 0, s[8:9]
	s_mov_b32 m0, s79
	s_nop 0
	global_load_lds_dwordx4 v[212:213], off
	v_lshl_add_u64 v[212:213], v[218:219], 0, s[8:9]
	s_mov_b32 m0, s80
	s_nop 0
	global_load_lds_dwordx4 v[212:213], off
	s_waitcnt vmcnt(8)
	s_waitcnt lgkmcnt(0)
	s_barrier
	s_setprio 0
	v_mfma_f32_16x16x32_bf16 v[62:65], v[142:145], v[180:183], v[62:65]
	v_mfma_f32_16x16x32_bf16 v[58:61], v[156:159], v[180:183], v[58:61]
	v_mfma_f32_16x16x32_bf16 v[54:57], v[142:145], v[188:191], v[54:57]
	v_mfma_f32_16x16x32_bf16 v[46:49], v[156:159], v[188:191], v[46:49]
	v_mfma_f32_16x16x32_bf16 v[38:41], v[142:145], v[196:199], v[38:41]
	v_mfma_f32_16x16x32_bf16 v[30:33], v[156:159], v[196:199], v[30:33]
	v_mfma_f32_16x16x32_bf16 v[22:25], v[142:145], v[204:207], v[22:25]
	v_mfma_f32_16x16x32_bf16 v[14:17], v[156:159], v[204:207], v[14:17]
	v_mfma_f32_16x16x32_bf16 v[62:65], v[152:155], v[184:187], v[62:65]
	v_mfma_f32_16x16x32_bf16 v[58:61], v[160:163], v[184:187], v[58:61]
	v_mfma_f32_16x16x32_bf16 v[54:57], v[152:155], v[192:195], v[54:57]
	v_mfma_f32_16x16x32_bf16 v[46:49], v[160:163], v[192:195], v[46:49]
	v_mfma_f32_16x16x32_bf16 v[38:41], v[152:155], v[200:203], v[38:41]
	v_mfma_f32_16x16x32_bf16 v[30:33], v[160:163], v[200:203], v[30:33]
	v_mfma_f32_16x16x32_bf16 v[22:25], v[152:155], v[208:211], v[22:25]
	v_mfma_f32_16x16x32_bf16 v[14:17], v[160:163], v[208:211], v[14:17]
	s_setprio 2
	s_setprio 0
	v_mfma_f32_16x16x32_bf16 v[50:53], v[164:167], v[180:183], v[50:53]
	v_mfma_f32_16x16x32_bf16 v[42:45], v[172:175], v[180:183], v[42:45]
	v_mfma_f32_16x16x32_bf16 v[34:37], v[164:167], v[188:191], v[34:37]
	v_mfma_f32_16x16x32_bf16 v[26:29], v[172:175], v[188:191], v[26:29]
	v_mfma_f32_16x16x32_bf16 v[18:21], v[164:167], v[196:199], v[18:21]
	v_mfma_f32_16x16x32_bf16 v[10:13], v[172:175], v[196:199], v[10:13]
	v_mfma_f32_16x16x32_bf16 v[6:9], v[164:167], v[204:207], v[6:9]
	v_mfma_f32_16x16x32_bf16 v[2:5], v[172:175], v[204:207], v[2:5]
	v_mfma_f32_16x16x32_bf16 v[50:53], v[168:171], v[184:187], v[50:53]
	v_mfma_f32_16x16x32_bf16 v[42:45], v[176:179], v[184:187], v[42:45]
	v_mfma_f32_16x16x32_bf16 v[34:37], v[168:171], v[192:195], v[34:37]
	v_mfma_f32_16x16x32_bf16 v[26:29], v[176:179], v[192:195], v[26:29]
	v_mfma_f32_16x16x32_bf16 v[18:21], v[168:171], v[200:203], v[18:21]
	v_mfma_f32_16x16x32_bf16 v[10:13], v[176:179], v[200:203], v[10:13]
	v_mfma_f32_16x16x32_bf16 v[6:9], v[168:171], v[208:211], v[6:9]
	v_mfma_f32_16x16x32_bf16 v[2:5], v[176:179], v[208:211], v[2:5]
	s_setprio 2
	s_barrier
	s_movk_i32 s13, 0x100
	s_andn2_b64 vcc, exec, s[22:23]
	s_mov_b64 s[24:25], -1
	s_mov_b64 s[22:23], 0
	s_cbranch_vccz .LBB0_368

; #define PG8_STAGE(bufoff, gbase, voff) do { _Pragma("unroll") for (int _i = 0; _i < 2; ++_i) \
;         __builtin_amdgcn_global_load_lds((const unsigned*)((const char*)(gbase) + (voff)[_i]), (LAS unsigned*)(lds + (bufoff) + ldsw + _i * 8192), 16, 0, 0); } while (0)
; #define PG8_LDA(dst, b, h) do { _Pragma("unroll") for (int m = 0; m < 4; ++m) _Pragma("unroll") for (int k = 0; k < 2; ++k) dst[m][k] = *(const LAS bf16x8*)(lds + PG8_SA(b, h) + aoff + m * 2048 + k * 1024); } while (0)
; #define PG8_LDB(dst, b, h) do { _Pragma("unroll") for (int n = 0; n < 2; ++n) _Pragma("unroll") for (int k = 0; k < 2; ++k) dst[n][k] = *(const LAS bf16x8*)(lds + PG8_SB(b, h) + boff + n * 2048 + k * 1024); } while (0)
; #define PG8_SCHED __builtin_amdgcn_sched_barrier(0)
;     __device__ __forceinline__ bool next(int i, Unit& u) const {
;         const long L = (long)i * G + c; if (L >= nwg) return false;
;         int w = (int)L; { const int q = nwg / NXCD, r = nwg % NXCD, xcd = w % NXCD, off = w / NXCD; w = (xcd < r ? xcd * (q + 1) : r * (q + 1) + (xcd - r) * q) + off; }
;         u.pb = w / per; w -= u.pb * per;
;         const int nig = WGM * nN, gid = w / nig, fm = gid * WGM, gsz = (nM - fm) < WGM ? (nM - fm) : WGM;
;         u.pm = fm + ((w % nig) % gsz); u.pn = (w % nig) / gsz; return true;
; template <class Epi>
; __device__ __forceinline__ void gemm_phase(LAS unsigned char* lds, const Gemm g, int G, int c, const Epi& E) {
;     ...
;             PG8_LDB(B0, 0, 0); PG8_LDB(B1, 0, 1); PG8_SCHED; PG8_LDA(At, 0, 0); PG8_STAGE(PG8_SA(1, 1), a1 + hstepA, voffA);
.LBB0_383:
	ds_read_b128 v[142:145], v160
	ds_read_b128 v[146:149], v160 offset:1024
	ds_read_b128 v[150:153], v160 offset:2048
	ds_read_b128 v[154:157], v160 offset:3072
	ds_read_b128 v[166:169], v161
	ds_read_b128 v[170:173], v161 offset:1024
	ds_read_b128 v[174:177], v161 offset:2048
	ds_read_b128 v[178:181], v161 offset:3072
	ds_read_b128 v[182:185], v162
	ds_read_b128 v[186:189], v162 offset:1024
	ds_read_b128 v[190:193], v162 offset:2048
	ds_read_b128 v[194:197], v162 offset:3072
	ds_read_b128 v[198:201], v162 offset:4096
	ds_read_b128 v[202:205], v162 offset:5120
	ds_read_b128 v[206:209], v162 offset:6144
	ds_read_b128 v[210:213], v162 offset:7168
	s_add_i32 s82, s82, 1
	s_mul_i32 s2, s82, s70
	s_mul_hi_u32 s3, s82, s27
	s_add_i32 s3, s3, s2
	s_mul_i32 s2, s82, s27
	s_add_u32 s2, s2, s35
	s_addc_u32 s3, s3, s69
	v_cmp_gt_i64_e32 vcc, s[2:3], v[140:141]
	v_cmp_lt_i64_e64 s[4:5], s[2:3], v[138:139]
	s_cbranch_vccnz .LBB0_385
	s_ashr_i32 s3, s2, 31
	s_lshr_b32 s3, s3, 29
	s_add_i32 s3, s2, s3
	s_ashr_i32 s10, s3, 3
	s_and_b32 s3, s3, -8
	s_sub_i32 s2, s2, s3
	s_lshr_b32 s3, s2, 31
	s_or_b32 s3, s3, 0x6c
	s_mul_i32 s2, s3, s2
	s_add_i32 s2, s2, s10
	s_mul_hi_i32 s3, s2, 0x4bda12f7
	s_lshr_b32 s10, s3, 31
	s_ashr_i32 s3, s3, 3
	s_add_i32 s92, s3, s10
	s_mul_i32 s3, s92, 0xffffffe5
	s_add_i32 s3, s3, s2
	s_mul_hi_i32 s2, s3, 0x2aaaaaab
	s_lshr_b32 s10, s2, 31
	s_ashr_i32 s2, s2, 2
	s_add_i32 s2, s2, s10
	s_lshl_b32 s10, s2, 3
	s_sub_i32 s11, 9, s10
	s_min_i32 s11, s11, 8
	s_abs_i32 s33, s11
	v_cvt_f32_u32_e32 v2, s33
	s_sub_i32 s39, 0, s33
	s_mul_i32 s2, s2, 24
	s_sub_i32 s2, s3, s2
	v_rcp_iflag_f32_e32 v2, v2
	s_abs_i32 s3, s2
	s_xor_b32 s38, s2, s11
	s_ashr_i32 s38, s38, 31
	v_mul_f32_e32 v2, 0x4f7ffffe, v2
	v_cvt_u32_f32_e32 v2, v2
	s_nop 0
	v_readfirstlane_b32 s46, v2
	s_mul_i32 s39, s39, s46
	s_mul_hi_u32 s39, s46, s39
	s_add_i32 s46, s46, s39
	s_mul_hi_u32 s39, s3, s46
	s_mul_i32 s46, s39, s33
	s_sub_i32 s3, s3, s46
	s_add_i32 s46, s39, 1
	s_sub_i32 s47, s3, s33
	s_cmp_ge_u32 s3, s33
	s_cselect_b32 s39, s46, s39
	s_cselect_b32 s3, s47, s3
	s_add_i32 s46, s39, 1
	s_cmp_ge_u32 s3, s33
	s_cselect_b32 s3, s46, s39
	s_xor_b32 s3, s3, s38
	s_sub_i32 s93, s3, s38
	s_mul_i32 s3, s93, s11
	s_sub_i32 s2, s2, s3
	s_add_i32 s94, s2, s10

; #define PG8_STAGE(bufoff, gbase, voff) do { _Pragma("unroll") for (int _i = 0; _i < 2; ++_i) \
;         __builtin_amdgcn_global_load_lds((const unsigned*)((const char*)(gbase) + (voff)[_i]), (LAS unsigned*)(lds + (bufoff) + ldsw + _i * 8192), 16, 0, 0); } while (0)
; #define PG8_LDA(dst, b, h) do { _Pragma("unroll") for (int m = 0; m < 4; ++m) _Pragma("unroll") for (int k = 0; k < 2; ++k) dst[m][k] = *(const LAS bf16x8*)(lds + PG8_SA(b, h) + aoff + m * 2048 + k * 1024); } while (0)
; #define PG8_LDB(dst, b, h) do { _Pragma("unroll") for (int n = 0; n < 2; ++n) _Pragma("unroll") for (int k = 0; k < 2; ++k) dst[n][k] = *(const LAS bf16x8*)(lds + PG8_SB(b, h) + boff + n * 2048 + k * 1024); } while (0)
; #define PG8_MMA(ai, bj, At, Bt) do { __builtin_amdgcn_s_setprio(1); _Pragma("unroll") for (int m = 0; m < 4; ++m) _Pragma("unroll") for (int n = 0; n < 2; ++n) _Pragma("unroll") for (int k = 0; k < 2; ++k) \
;         acc[ai][bj][m][n] = __builtin_amdgcn_mfma_f32_16x16x32_bf16(Bt[n][k], At[m][k], acc[ai][bj][m][n], 0, 0, 0); __builtin_amdgcn_s_setprio(0); } while (0)
; #define PG8_WAIT_V(n) asm volatile("s_waitcnt vmcnt(" #n ")" ::: "memory")
; #define PG8_WAIT_L(n) asm volatile("s_waitcnt lgkmcnt(" #n ")" ::: "memory")
; #define PG8_BAR __builtin_amdgcn_s_barrier()
; #define PG8_SCHED __builtin_amdgcn_sched_barrier(0)
; template <class Epi>
; __device__ __forceinline__ void gemm_phase(LAS unsigned char* lds, const Gemm g, int G, int c, const Epi& E) {
;     ...
;             const char* a1 = cA + (size_t)(t + 1) * kstep;
;             const char* a2 = last ? nA : cA + (size_t)(t + 2) * kstep; const char* b2 = last ? nB : cB + (size_t)(t + 2) * kstep;
;             const char* a3 = a2 + kstep; const char* b3 = b2 + kstep;
;             PG8_LDB(B0, 0, 0); PG8_LDB(B1, 0, 1); PG8_SCHED; PG8_LDA(At, 0, 0); PG8_STAGE(PG8_SA(1, 1), a1 + hstepA, voffA);
;             PG8_WAIT_V(8); PG8_WAIT_L(0); PG8_BAR; PG8_MMA(0, 0, At, B0); PG8_MMA(0, 1, At, B1); PG8_BAR; PG8_SCHED;
;             PG8_LDA(At, 0, 1); PG8_STAGE(PG8_SB(0, 0), b2, voffB); PG8_STAGE(PG8_SB(0, 1), b2 + hstepB, voffB); PG8_STAGE(PG8_SA(0, 0), a2, voffA);
;             PG8_WAIT_V(8); PG8_WAIT_L(0); PG8_BAR; PG8_MMA(1, 0, At, B0); PG8_MMA(1, 1, At, B1); PG8_BAR; PG8_SCHED;
.LBB0_389:
	s_mov_b32 s38, 0
	s_mov_b64 s[4:5], -1
	s_mov_b64 s[10:11], 0
	s_add_u32 s33, s8, s38
	s_addc_u32 s39, s9, 0
	s_add_u32 s56, s33, 0x100
	s_addc_u32 s57, s39, 0
	s_and_b64 s[54:55], s[10:11], exec
	s_cselect_b32 s57, s47, s57
	s_cselect_b32 s56, s46, s56
	s_add_u32 s38, s6, s38
	s_addc_u32 s54, s7, 0
	s_add_u32 s38, s38, 0x100
	s_addc_u32 s54, s54, 0
	s_and_b64 s[10:11], s[10:11], exec
	s_cselect_b32 s59, s53, s54
	s_cselect_b32 s58, s52, s38
	s_add_u32 s66, s33, 0xb0080
	s_addc_u32 s67, s39, 0
	s_add_i32 s65, s87, s14
	s_add_i32 m0, s78, 0xc000
	s_add_i32 s74, s78, 0xe000
	s_add_i32 s62, s65, 0x2000
	s_add_u32 s60, s58, 0xb0000
	s_addc_u32 s61, s59, 0
	s_add_i32 s64, s88, s14
	s_add_i32 s63, s64, 0x2000
	s_add_i32 s73, 0, 0x18000
	s_add_i32 s33, 0, 0x1c000
	s_add_u32 s54, s56, 0xb0000
	s_addc_u32 s55, s57, 0
	s_add_i32 vcc_hi, s73, s14
	s_add_i32 s39, vcc_hi, 0x2000
	s_add_u32 s10, s58, 0xb0080
	s_addc_u32 s11, s59, 0
	s_add_i32 vcc_lo, s33, s14
	s_add_i32 s38, vcc_lo, 0x2000
	v_lshl_add_u64 v[214:215], s[66:67], 0, v[130:131]
	global_load_lds_dwordx4 v[214:215], off
	v_lshl_add_u64 v[214:215], s[66:67], 0, v[134:135]
	s_mov_b32 m0, s74
	s_nop 0
	global_load_lds_dwordx4 v[214:215], off
	s_waitcnt vmcnt(8)
	s_waitcnt lgkmcnt(0)
	s_barrier
	s_setprio 0
	v_mfma_f32_16x16x32_bf16 v[126:129], v[142:145], v[182:185], 0
	v_mfma_f32_16x16x32_bf16 v[122:125], v[150:153], v[182:185], 0
	v_mfma_f32_16x16x32_bf16 v[110:113], v[142:145], v[190:193], 0
	v_mfma_f32_16x16x32_bf16 v[106:109], v[150:153], v[190:193], 0
	v_mfma_f32_16x16x32_bf16 v[94:97], v[142:145], v[198:201], 0
	v_mfma_f32_16x16x32_bf16 v[90:93], v[150:153], v[198:201], 0
	v_mfma_f32_16x16x32_bf16 v[78:81], v[142:145], v[206:209], 0
	v_mfma_f32_16x16x32_bf16 v[74:77], v[150:153], v[206:209], 0
	v_mfma_f32_16x16x32_bf16 v[126:129], v[146:149], v[186:189], v[126:129]
	v_mfma_f32_16x16x32_bf16 v[122:125], v[154:157], v[186:189], v[122:125]
	v_mfma_f32_16x16x32_bf16 v[110:113], v[146:149], v[194:197], v[110:113]
	v_mfma_f32_16x16x32_bf16 v[106:109], v[154:157], v[194:197], v[106:109]
	v_mfma_f32_16x16x32_bf16 v[94:97], v[146:149], v[202:205], v[94:97]
	v_mfma_f32_16x16x32_bf16 v[90:93], v[154:157], v[202:205], v[90:93]
	v_mfma_f32_16x16x32_bf16 v[78:81], v[146:149], v[210:213], v[78:81]
	v_mfma_f32_16x16x32_bf16 v[74:77], v[154:157], v[210:213], v[74:77]
	s_setprio 2
	s_setprio 0
	v_mfma_f32_16x16x32_bf16 v[118:121], v[166:169], v[182:185], 0
	v_mfma_f32_16x16x32_bf16 v[114:117], v[174:177], v[182:185], 0
	v_mfma_f32_16x16x32_bf16 v[102:105], v[166:169], v[190:193], 0
	v_mfma_f32_16x16x32_bf16 v[98:101], v[174:177], v[190:193], 0
	v_mfma_f32_16x16x32_bf16 v[86:89], v[166:169], v[198:201], 0
	v_mfma_f32_16x16x32_bf16 v[82:85], v[174:177], v[198:201], 0
	v_mfma_f32_16x16x32_bf16 v[70:73], v[166:169], v[206:209], 0
	v_mfma_f32_16x16x32_bf16 v[66:69], v[174:177], v[206:209], 0
	v_mfma_f32_16x16x32_bf16 v[118:121], v[170:173], v[186:189], v[118:121]
	v_mfma_f32_16x16x32_bf16 v[114:117], v[178:181], v[186:189], v[114:117]
	v_mfma_f32_16x16x32_bf16 v[102:105], v[170:173], v[194:197], v[102:105]
	v_mfma_f32_16x16x32_bf16 v[98:101], v[178:181], v[194:197], v[98:101]
	v_mfma_f32_16x16x32_bf16 v[86:89], v[170:173], v[202:205], v[86:89]
	v_mfma_f32_16x16x32_bf16 v[82:85], v[178:181], v[202:205], v[82:85]
	v_mfma_f32_16x16x32_bf16 v[70:73], v[170:173], v[210:213], v[70:73]
	v_mfma_f32_16x16x32_bf16 v[66:69], v[178:181], v[210:213], v[66:69]
	s_setprio 2
	s_barrier
	s_mov_b32 m0, s65
	v_lshl_add_u64 v[214:215], s[58:59], 0, v[132:133]
	ds_read_b128 v[182:185], v162 offset:16384
	ds_read_b128 v[186:189], v162 offset:17408
	ds_read_b128 v[190:193], v162 offset:18432
	ds_read_b128 v[194:197], v162 offset:19456
	ds_read_b128 v[198:201], v162 offset:20480
	ds_read_b128 v[202:205], v162 offset:21504
	ds_read_b128 v[206:209], v162 offset:22528
	ds_read_b128 v[210:213], v162 offset:23552
	global_load_lds_dwordx4 v[214:215], off
	v_lshl_add_u64 v[216:217], s[58:59], 0, v[136:137]
	s_mov_b32 m0, s62
	v_lshl_add_u64 v[218:219], s[60:61], 0, v[132:133]
	global_load_lds_dwordx4 v[216:217], off
	s_mov_b32 m0, s64
	v_lshl_add_u64 v[220:221], s[56:57], 0, v[134:135]
	global_load_lds_dwordx4 v[218:219], off
	v_lshl_add_u64 v[218:219], s[60:61], 0, v[136:137]
	s_mov_b32 m0, s63
	s_nop 0
	global_load_lds_dwordx4 v[218:219], off
	v_lshl_add_u64 v[218:219], s[56:57], 0, v[130:131]
	s_mov_b32 m0, s78
	s_nop 0
	global_load_lds_dwordx4 v[218:219], off
	s_mov_b32 m0, s79
	s_nop 0
	global_load_lds_dwordx4 v[220:221], off
	s_waitcnt vmcnt(8)
	s_waitcnt lgkmcnt(0)
	s_barrier
; #define PG8_STAGE(bufoff, gbase, voff) do { _Pragma("unroll") for (int _i = 0; _i < 2; ++_i) \
;         __builtin_amdgcn_global_load_lds((const unsigned*)((const char*)(gbase) + (voff)[_i]), (LAS unsigned*)(lds + (bufoff) + ldsw + _i * 8192), 16, 0, 0); } while (0)
; #define PG8_LDA(dst, b, h) do { _Pragma("unroll") for (int m = 0; m < 4; ++m) _Pragma("unroll") for (int k = 0; k < 2; ++k) dst[m][k] = *(const LAS bf16x8*)(lds + PG8_SA(b, h) + aoff + m * 2048 + k * 1024); } while (0)
; #define PG8_LDB(dst, b, h) do { _Pragma("unroll") for (int n = 0; n < 2; ++n) _Pragma("unroll") for (int k = 0; k < 2; ++k) dst[n][k] = *(const LAS bf16x8*)(lds + PG8_SB(b, h) + boff + n * 2048 + k * 1024); } while (0)
; #define PG8_MMA(ai, bj, At, Bt) do { __builtin_amdgcn_s_setprio(1); _Pragma("unroll") for (int m = 0; m < 4; ++m) _Pragma("unroll") for (int n = 0; n < 2; ++n) _Pragma("unroll") for (int k = 0; k < 2; ++k) \
;         acc[ai][bj][m][n] = __builtin_amdgcn_mfma_f32_16x16x32_bf16(Bt[n][k], At[m][k], acc[ai][bj][m][n], 0, 0, 0); __builtin_amdgcn_s_setprio(0); } while (0)
; #define PG8_WAIT_V(n) asm volatile("s_waitcnt vmcnt(" #n ")" ::: "memory")
; #define PG8_WAIT_L(n) asm volatile("s_waitcnt lgkmcnt(" #n ")" ::: "memory")
; #define PG8_BAR __builtin_amdgcn_s_barrier()
; #define PG8_SCHED __builtin_amdgcn_sched_barrier(0)
; template <class Epi>
; __device__ __forceinline__ void gemm_phase(LAS unsigned char* lds, const Gemm g, int G, int c, const Epi& E) {
;     ...
;             PG8_WAIT_V(8); PG8_WAIT_L(0); PG8_BAR; PG8_MMA(1, 0, At, B0); PG8_MMA(1, 1, At, B1); PG8_BAR; PG8_SCHED;
;             PG8_LDB(B0, 1, 0); PG8_LDB(B1, 1, 1); PG8_SCHED; PG8_LDA(At, 1, 0); PG8_STAGE(PG8_SA(0, 1), a2 + hstepA, voffA);
;             PG8_WAIT_V(8); PG8_WAIT_L(0); PG8_BAR; PG8_MMA(0, 0, At, B0); PG8_MMA(0, 1, At, B1); PG8_BAR; PG8_SCHED;
	s_setprio 0
	v_mfma_f32_16x16x32_bf16 v[62:65], v[142:145], v[182:185], 0
	v_mfma_f32_16x16x32_bf16 v[58:61], v[150:153], v[182:185], 0
	v_mfma_f32_16x16x32_bf16 v[46:49], v[142:145], v[190:193], 0
	v_mfma_f32_16x16x32_bf16 v[42:45], v[150:153], v[190:193], 0
	v_mfma_f32_16x16x32_bf16 v[30:33], v[142:145], v[198:201], 0
	v_mfma_f32_16x16x32_bf16 v[26:29], v[150:153], v[198:201], 0
	v_mfma_f32_16x16x32_bf16 v[14:17], v[142:145], v[206:209], 0
	v_mfma_f32_16x16x32_bf16 v[10:13], v[150:153], v[206:209], 0
	v_mfma_f32_16x16x32_bf16 v[62:65], v[146:149], v[186:189], v[62:65]
	v_mfma_f32_16x16x32_bf16 v[58:61], v[154:157], v[186:189], v[58:61]
	v_mfma_f32_16x16x32_bf16 v[46:49], v[146:149], v[194:197], v[46:49]
	v_mfma_f32_16x16x32_bf16 v[42:45], v[154:157], v[194:197], v[42:45]
	v_mfma_f32_16x16x32_bf16 v[30:33], v[146:149], v[202:205], v[30:33]
	v_mfma_f32_16x16x32_bf16 v[26:29], v[154:157], v[202:205], v[26:29]
	v_mfma_f32_16x16x32_bf16 v[14:17], v[146:149], v[210:213], v[14:17]
	v_mfma_f32_16x16x32_bf16 v[10:13], v[154:157], v[210:213], v[10:13]
	s_setprio 2
	s_setprio 0
	v_mfma_f32_16x16x32_bf16 v[54:57], v[166:169], v[182:185], 0
	v_mfma_f32_16x16x32_bf16 v[50:53], v[174:177], v[182:185], 0
	v_mfma_f32_16x16x32_bf16 v[38:41], v[166:169], v[190:193], 0
	v_mfma_f32_16x16x32_bf16 v[34:37], v[174:177], v[190:193], 0
	v_mfma_f32_16x16x32_bf16 v[22:25], v[166:169], v[198:201], 0
	v_mfma_f32_16x16x32_bf16 v[18:21], v[174:177], v[198:201], 0
	v_mfma_f32_16x16x32_bf16 v[6:9], v[166:169], v[206:209], 0
	v_mfma_f32_16x16x32_bf16 v[2:5], v[174:177], v[206:209], 0
	v_mfma_f32_16x16x32_bf16 v[54:57], v[170:173], v[186:189], v[54:57]
	v_mfma_f32_16x16x32_bf16 v[50:53], v[178:181], v[186:189], v[50:53]
	v_mfma_f32_16x16x32_bf16 v[38:41], v[170:173], v[194:197], v[38:41]
	v_mfma_f32_16x16x32_bf16 v[34:37], v[178:181], v[194:197], v[34:37]
	v_mfma_f32_16x16x32_bf16 v[22:25], v[170:173], v[202:205], v[22:25]
	v_mfma_f32_16x16x32_bf16 v[18:21], v[178:181], v[202:205], v[18:21]
	v_mfma_f32_16x16x32_bf16 v[6:9], v[170:173], v[210:213], v[6:9]
	v_mfma_f32_16x16x32_bf16 v[2:5], v[178:181], v[210:213], v[2:5]
	s_setprio 2
	s_barrier
	v_add_u32_e32 v154, s73, v159
	v_add_u32_e32 v178, s33, v159
	ds_read_b128 v[142:145], v154
	ds_read_b128 v[146:149], v154 offset:1024
	ds_read_b128 v[150:153], v154 offset:2048
	ds_read_b128 v[154:157], v154 offset:3072
	ds_read_b128 v[166:169], v178
	ds_read_b128 v[170:173], v178 offset:1024
	ds_read_b128 v[174:177], v178 offset:2048
	ds_read_b128 v[178:181], v178 offset:3072
	s_mov_b32 m0, s80
	v_lshl_add_u64 v[222:223], s[54:55], 0, v[130:131]
	ds_read_b128 v[182:185], v162 offset:32768
	ds_read_b128 v[186:189], v162 offset:33792
	ds_read_b128 v[190:193], v162 offset:34816
	ds_read_b128 v[194:197], v162 offset:35840
	ds_read_b128 v[198:201], v162 offset:36864
	ds_read_b128 v[202:205], v162 offset:37888
	ds_read_b128 v[206:209], v162 offset:38912
	ds_read_b128 v[210:213], v162 offset:39936
	global_load_lds_dwordx4 v[222:223], off
	v_lshl_add_u64 v[222:223], s[54:55], 0, v[134:135]
	s_mov_b32 m0, s81
	s_nop 0
	global_load_lds_dwordx4 v[222:223], off
	s_waitcnt vmcnt(8)
	s_waitcnt lgkmcnt(0)
	s_barrier
	s_setprio 0
	v_mfma_f32_16x16x32_bf16 v[126:129], v[142:145], v[182:185], v[126:129]
	v_mfma_f32_16x16x32_bf16 v[122:125], v[150:153], v[182:185], v[122:125]
	v_mfma_f32_16x16x32_bf16 v[110:113], v[142:145], v[190:193], v[110:113]
	v_mfma_f32_16x16x32_bf16 v[106:109], v[150:153], v[190:193], v[106:109]
	v_mfma_f32_16x16x32_bf16 v[94:97], v[142:145], v[198:201], v[94:97]
	v_mfma_f32_16x16x32_bf16 v[90:93], v[150:153], v[198:201], v[90:93]
	v_mfma_f32_16x16x32_bf16 v[78:81], v[142:145], v[206:209], v[78:81]
	v_mfma_f32_16x16x32_bf16 v[74:77], v[150:153], v[206:209], v[74:77]
	v_mfma_f32_16x16x32_bf16 v[126:129], v[146:149], v[186:189], v[126:129]
	v_mfma_f32_16x16x32_bf16 v[122:125], v[154:157], v[186:189], v[122:125]
	v_mfma_f32_16x16x32_bf16 v[110:113], v[146:149], v[194:197], v[110:113]
	v_mfma_f32_16x16x32_bf16 v[106:109], v[154:157], v[194:197], v[106:109]
	v_mfma_f32_16x16x32_bf16 v[94:97], v[146:149], v[202:205], v[94:97]
	v_mfma_f32_16x16x32_bf16 v[90:93], v[154:157], v[202:205], v[90:93]
	v_mfma_f32_16x16x32_bf16 v[78:81], v[146:149], v[210:213], v[78:81]
	v_mfma_f32_16x16x32_bf16 v[74:77], v[154:157], v[210:213], v[74:77]
	s_setprio 2
	s_setprio 0
	v_mfma_f32_16x16x32_bf16 v[118:121], v[166:169], v[182:185], v[118:121]
	v_mfma_f32_16x16x32_bf16 v[114:117], v[174:177], v[182:185], v[114:117]
	v_mfma_f32_16x16x32_bf16 v[102:105], v[166:169], v[190:193], v[102:105]
	v_mfma_f32_16x16x32_bf16 v[98:101], v[174:177], v[190:193], v[98:101]
	v_mfma_f32_16x16x32_bf16 v[86:89], v[166:169], v[198:201], v[86:89]
	v_mfma_f32_16x16x32_bf16 v[82:85], v[174:177], v[198:201], v[82:85]
	v_mfma_f32_16x16x32_bf16 v[70:73], v[166:169], v[206:209], v[70:73]
	v_mfma_f32_16x16x32_bf16 v[66:69], v[174:177], v[206:209], v[66:69]
	v_mfma_f32_16x16x32_bf16 v[118:121], v[170:173], v[186:189], v[118:121]
	v_mfma_f32_16x16x32_bf16 v[114:117], v[178:181], v[186:189], v[114:117]
	v_mfma_f32_16x16x32_bf16 v[102:105], v[170:173], v[194:197], v[102:105]
	v_mfma_f32_16x16x32_bf16 v[98:101], v[178:181], v[194:197], v[98:101]
	v_mfma_f32_16x16x32_bf16 v[86:89], v[170:173], v[202:205], v[86:89]
	v_mfma_f32_16x16x32_bf16 v[82:85], v[178:181], v[202:205], v[82:85]
	v_mfma_f32_16x16x32_bf16 v[70:73], v[170:173], v[210:213], v[70:73]
	v_mfma_f32_16x16x32_bf16 v[66:69], v[178:181], v[210:213], v[66:69]
	s_setprio 2
	s_barrier
; #define PG8_STAGE(bufoff, gbase, voff) do { _Pragma("unroll") for (int _i = 0; _i < 2; ++_i) \
;         __builtin_amdgcn_global_load_lds((const unsigned*)((const char*)(gbase) + (voff)[_i]), (LAS unsigned*)(lds + (bufoff) + ldsw + _i * 8192), 16, 0, 0); } while (0)
; #define PG8_LDA(dst, b, h) do { _Pragma("unroll") for (int m = 0; m < 4; ++m) _Pragma("unroll") for (int k = 0; k < 2; ++k) dst[m][k] = *(const LAS bf16x8*)(lds + PG8_SA(b, h) + aoff + m * 2048 + k * 1024); } while (0)
; #define PG8_MMA(ai, bj, At, Bt) do { __builtin_amdgcn_s_setprio(1); _Pragma("unroll") for (int m = 0; m < 4; ++m) _Pragma("unroll") for (int n = 0; n < 2; ++n) _Pragma("unroll") for (int k = 0; k < 2; ++k) \
;         acc[ai][bj][m][n] = __builtin_amdgcn_mfma_f32_16x16x32_bf16(Bt[n][k], At[m][k], acc[ai][bj][m][n], 0, 0, 0); __builtin_amdgcn_s_setprio(0); } while (0)
; #define PG8_WAIT_V(n) asm volatile("s_waitcnt vmcnt(" #n ")" ::: "memory")
; #define PG8_WAIT_L(n) asm volatile("s_waitcnt lgkmcnt(" #n ")" ::: "memory")
; #define PG8_BAR __builtin_amdgcn_s_barrier()
; #define PG8_SCHED __builtin_amdgcn_sched_barrier(0)
; template <class Epi>
; __device__ __forceinline__ void gemm_phase(LAS unsigned char* lds, const Gemm g, int G, int c, const Epi& E) {
;     ...
;             PG8_LDA(At, 1, 1); PG8_STAGE(PG8_SB(1, 0), b3, voffB); PG8_STAGE(PG8_SB(1, 1), b3 + hstepB, voffB); PG8_STAGE(PG8_SA(1, 0), a3, voffA);
;             PG8_WAIT_V(8); PG8_WAIT_L(0); PG8_BAR; PG8_MMA(1, 0, At, B0); PG8_MMA(1, 1, At, B1); PG8_BAR; PG8_SCHED;
;         }
	s_mov_b32 m0, vcc_hi
	v_lshl_add_u64 v[214:215], v[214:215], 0, s[24:25]
	ds_read_b128 v[182:185], v162 offset:49152
	ds_read_b128 v[186:189], v162 offset:50176
	ds_read_b128 v[190:193], v162 offset:51200
	ds_read_b128 v[194:197], v162 offset:52224
	ds_read_b128 v[198:201], v162 offset:53248
	ds_read_b128 v[202:205], v162 offset:54272
	ds_read_b128 v[206:209], v162 offset:55296
	ds_read_b128 v[210:213], v162 offset:56320
	global_load_lds_dwordx4 v[214:215], off
	v_lshl_add_u64 v[214:215], v[216:217], 0, s[24:25]
	s_mov_b32 m0, s39
	s_nop 0
	global_load_lds_dwordx4 v[214:215], off
	v_lshl_add_u64 v[214:215], s[10:11], 0, v[132:133]
	s_mov_b32 m0, vcc_lo
	s_nop 0
	global_load_lds_dwordx4 v[214:215], off
	v_lshl_add_u64 v[214:215], s[10:11], 0, v[136:137]
	s_mov_b32 m0, s38
	s_nop 0
	global_load_lds_dwordx4 v[214:215], off
	v_lshl_add_u64 v[214:215], v[218:219], 0, s[24:25]
	s_mov_b32 m0, s85
	s_nop 0
	global_load_lds_dwordx4 v[214:215], off
	v_lshl_add_u64 v[214:215], v[220:221], 0, s[24:25]
	s_mov_b32 m0, s86
	s_nop 0
	global_load_lds_dwordx4 v[214:215], off
	s_waitcnt vmcnt(8)
	s_waitcnt lgkmcnt(0)
	s_barrier
	s_setprio 0
	v_mfma_f32_16x16x32_bf16 v[62:65], v[142:145], v[182:185], v[62:65]
	v_mfma_f32_16x16x32_bf16 v[58:61], v[150:153], v[182:185], v[58:61]
	v_mfma_f32_16x16x32_bf16 v[46:49], v[142:145], v[190:193], v[46:49]
	v_mfma_f32_16x16x32_bf16 v[42:45], v[150:153], v[190:193], v[42:45]
	v_mfma_f32_16x16x32_bf16 v[30:33], v[142:145], v[198:201], v[30:33]
	v_mfma_f32_16x16x32_bf16 v[26:29], v[150:153], v[198:201], v[26:29]
	v_mfma_f32_16x16x32_bf16 v[14:17], v[142:145], v[206:209], v[14:17]
	v_mfma_f32_16x16x32_bf16 v[10:13], v[150:153], v[206:209], v[10:13]
	v_mfma_f32_16x16x32_bf16 v[62:65], v[146:149], v[186:189], v[62:65]
	v_mfma_f32_16x16x32_bf16 v[58:61], v[154:157], v[186:189], v[58:61]
	v_mfma_f32_16x16x32_bf16 v[46:49], v[146:149], v[194:197], v[46:49]
	v_mfma_f32_16x16x32_bf16 v[42:45], v[154:157], v[194:197], v[42:45]
	v_mfma_f32_16x16x32_bf16 v[30:33], v[146:149], v[202:205], v[30:33]
	v_mfma_f32_16x16x32_bf16 v[26:29], v[154:157], v[202:205], v[26:29]
	v_mfma_f32_16x16x32_bf16 v[14:17], v[146:149], v[210:213], v[14:17]
	v_mfma_f32_16x16x32_bf16 v[10:13], v[154:157], v[210:213], v[10:13]
	s_setprio 2
	s_setprio 0
	v_mfma_f32_16x16x32_bf16 v[54:57], v[166:169], v[182:185], v[54:57]
	v_mfma_f32_16x16x32_bf16 v[50:53], v[174:177], v[182:185], v[50:53]
	v_mfma_f32_16x16x32_bf16 v[38:41], v[166:169], v[190:193], v[38:41]
	v_mfma_f32_16x16x32_bf16 v[34:37], v[174:177], v[190:193], v[34:37]
	v_mfma_f32_16x16x32_bf16 v[22:25], v[166:169], v[198:201], v[22:25]
	v_mfma_f32_16x16x32_bf16 v[18:21], v[174:177], v[198:201], v[18:21]
	v_mfma_f32_16x16x32_bf16 v[6:9], v[166:169], v[206:209], v[6:9]
	v_mfma_f32_16x16x32_bf16 v[2:5], v[174:177], v[206:209], v[2:5]
	v_mfma_f32_16x16x32_bf16 v[54:57], v[170:173], v[186:189], v[54:57]
	v_mfma_f32_16x16x32_bf16 v[50:53], v[178:181], v[186:189], v[50:53]
	v_mfma_f32_16x16x32_bf16 v[38:41], v[170:173], v[194:197], v[38:41]
	v_mfma_f32_16x16x32_bf16 v[34:37], v[178:181], v[194:197], v[34:37]
	v_mfma_f32_16x16x32_bf16 v[22:25], v[170:173], v[202:205], v[22:25]
	v_mfma_f32_16x16x32_bf16 v[18:21], v[178:181], v[202:205], v[18:21]
	v_mfma_f32_16x16x32_bf16 v[6:9], v[170:173], v[210:213], v[6:9]
	v_mfma_f32_16x16x32_bf16 v[2:5], v[178:181], v[210:213], v[2:5]
	s_setprio 2
	s_barrier
	s_movk_i32 s38, 0x100
	s_andn2_b64 vcc, exec, s[4:5]
	s_mov_b64 s[10:11], -1
	s_mov_b64 s[4:5], 0
	s_cbranch_vccz .LBB0_390

; #define PG8_STAGE(bufoff, gbase, voff) do { _Pragma("unroll") for (int _i = 0; _i < 2; ++_i) \
;         __builtin_amdgcn_global_load_lds((const unsigned*)((const char*)(gbase) + (voff)[_i]), (LAS unsigned*)(lds + (bufoff) + ldsw + _i * 8192), 16, 0, 0); } while (0)
; #define PG8_LDA(dst, b, h) do { _Pragma("unroll") for (int m = 0; m < 4; ++m) _Pragma("unroll") for (int k = 0; k < 2; ++k) dst[m][k] = *(const LAS bf16x8*)(lds + PG8_SA(b, h) + aoff + m * 2048 + k * 1024); } while (0)
; #define PG8_LDB(dst, b, h) do { _Pragma("unroll") for (int n = 0; n < 2; ++n) _Pragma("unroll") for (int k = 0; k < 2; ++k) dst[n][k] = *(const LAS bf16x8*)(lds + PG8_SB(b, h) + boff + n * 2048 + k * 1024); } while (0)
; #define PG8_WAIT_V(n) asm volatile("s_waitcnt vmcnt(" #n ")" ::: "memory")
;     __device__ __forceinline__ bool next(int i, Unit& u) const {
;         const long L = (long)i * G + c; if (L >= nwg) return false;
;         int w = (int)L; { const int q = nwg / NXCD, r = nwg % NXCD, xcd = w % NXCD, off = w / NXCD; w = (xcd < r ? xcd * (q + 1) : r * (q + 1) + (xcd - r) * q) + off; }
;         u.pb = w / per; w -= u.pb * per;
;         const int nig = WGM * nN, gid = w / nig, fm = gid * WGM, gsz = (nM - fm) < WGM ? (nM - fm) : WGM;
;         u.pm = fm + ((w % nig) % gsz); u.pn = (w % nig) / gsz; return true;
; template <class Epi>
; __device__ __forceinline__ void gemm_phase(LAS unsigned char* lds, const Gemm g, int G, int c, const Epi& E) {
;     ...
;         const bool has_next = S.next(ui + 1, nxt);
;         const char* nA = has_next ? (const char*)(g.A + (size_t)nxt.pb * g.sA) + (size_t)nxt.pm * 2 * hstepA : cA;
;         const char* nB = has_next ? (const char*)(g.Bt + (size_t)nxt.pb * g.sB) + (size_t)nxt.pn * 2 * hstepB : cB;
; #pragma nounroll
;         for (int t = 0; t < nt; t += 2) {
;             const bool last = (t == nt - 2);
;             const char* a1 = cA + (size_t)(t + 1) * kstep;
;             const char* a2 = last ? nA : cA + (size_t)(t + 2) * kstep; const char* b2 = last ? nB : cB + (size_t)(t + 2) * kstep;
;             const char* a3 = a2 + kstep; const char* b3 = b2 + kstep;
;             PG8_LDB(B0, 0, 0); PG8_LDB(B1, 0, 1); PG8_SCHED; PG8_LDA(At, 0, 0); PG8_STAGE(PG8_SA(1, 1), a1 + hstepA, voffA);
;             PG8_WAIT_V(8); PG8_WAIT_L(0); PG8_BAR; PG8_MMA(0, 0, At, B0); PG8_MMA(0, 1, At, B1); PG8_BAR; PG8_SCHED;
.LBB0_762:
	ds_read_b128 v[146:149], v152
	ds_read_b128 v[156:159], v152 offset:1024
	ds_read_b128 v[160:163], v152 offset:2048
	ds_read_b128 v[164:167], v152 offset:3072
	ds_read_b128 v[168:171], v153
	ds_read_b128 v[172:175], v153 offset:1024
	ds_read_b128 v[176:179], v153 offset:2048
	ds_read_b128 v[180:183], v153 offset:3072
	ds_read_b128 v[184:187], v154
	ds_read_b128 v[188:191], v154 offset:1024
	ds_read_b128 v[192:195], v154 offset:2048
	ds_read_b128 v[196:199], v154 offset:3072
	ds_read_b128 v[200:203], v154 offset:4096
	ds_read_b128 v[204:207], v154 offset:5120
	ds_read_b128 v[208:211], v154 offset:6144
	ds_read_b128 v[212:215], v154 offset:7168
	s_add_i32 s67, s67, 1
	s_mul_i32 s2, s67, s35
	s_mul_hi_u32 s3, s67, s27
	s_add_i32 s3, s3, s2
	s_mul_i32 s2, s67, s27
	s_add_u32 s18, s2, s26
	s_addc_u32 s19, s3, s34
	v_cmp_gt_i64_e32 vcc, s[18:19], v[144:145]
	v_cmp_lt_i64_e64 s[2:3], s[18:19], v[142:143]
	s_cbranch_vccnz .LBB0_764
	s_ashr_i32 s10, s18, 31
	s_lshr_b32 s10, s10, 29
	s_add_i32 s10, s18, s10
	s_ashr_i32 s11, s10, 3
	s_and_b32 s10, s10, -8
	s_sub_i32 s10, s18, s10
	s_lshr_b32 s12, s10, 31
	s_or_b32 s12, s12, 32
	s_mul_i32 s10, s12, s10
	s_add_i32 s10, s10, s11
	s_ashr_i32 s11, s10, 31
	s_lshr_b32 s11, s11, 29
	s_add_i32 s11, s10, s11
	s_and_b32 s12, s11, -8
	s_sub_i32 s12, s10, s12
	s_ashr_i32 s10, s12, 31
	s_lshr_b32 s10, s10, 29
	s_add_i32 s10, s12, s10
	s_and_b32 s13, s10, -8
	s_sub_i32 s10, 8, s13
	s_min_i32 s14, s10, 8
	s_abs_i32 s15, s14
	v_cvt_f32_u32_e32 v2, s15
	s_sub_i32 s19, 0, s15
	s_ashr_i32 s10, s11, 3
	s_sub_i32 s11, s12, s13
	v_rcp_iflag_f32_e32 v2, v2
	s_abs_i32 s12, s11
	s_xor_b32 s18, s11, s14
	s_ashr_i32 s18, s18, 31
	v_mul_f32_e32 v2, 0x4f7ffffe, v2
	v_cvt_u32_f32_e32 v2, v2
	s_nop 0
	v_readfirstlane_b32 s24, v2
	s_mul_i32 s19, s19, s24
	s_mul_hi_u32 s19, s24, s19
	s_add_i32 s24, s24, s19
	s_mul_hi_u32 s19, s12, s24
	s_mul_i32 s24, s19, s15
	s_sub_i32 s12, s12, s24
	s_add_i32 s25, s19, 1
	s_sub_i32 s24, s12, s15
	s_cmp_ge_u32 s12, s15
	s_cselect_b32 s19, s25, s19
	s_cselect_b32 s12, s24, s12
	s_add_i32 s24, s19, 1
	s_cmp_ge_u32 s12, s15
	s_cselect_b32 s12, s24, s19
	s_xor_b32 s12, s12, s18
	s_sub_i32 s12, s12, s18
	s_mul_i32 s14, s12, s14
	s_sub_i32 s11, s11, s14
	s_add_i32 s14, s11, s13
.LBB0_764:
	s_ashr_i32 s15, s14, 31
	s_lshl_b64 s[18:19], s[14:15], 21
	s_add_u32 s18, s57, s18
	s_addc_u32 s19, s58, s19
	s_and_b64 s[24:25], s[2:3], exec
	s_cselect_b32 s15, s19, s45
	s_cselect_b32 s78, s18, s44
	s_ashr_i32 s11, s10, 31
	s_lshl_b64 s[24:25], s[10:11], 21
	s_add_u32 s11, s59, s24
	s_addc_u32 s33, s60, s25
	s_ashr_i32 s13, s12, 31
	s_lshl_b64 s[24:25], s[12:13], 21
	s_add_u32 s24, s11, s24
	s_addc_u32 s25, s33, s25
	s_and_b64 s[52:53], s[2:3], exec
	s_cselect_b32 s11, s25, s47
	s_cselect_b32 s13, s24, s46
	s_add_u32 s44, s44, 0x100080
	s_addc_u32 s45, s45, 0
	s_add_u32 s81, s46, 0x100
	s_addc_u32 s82, s47, 0
	s_mov_b32 s83, -2
	s_add_u32 s33, s44, 0xfff00080
	s_addc_u32 s46, s45, -1
	s_cmp_eq_u32 s83, 60
	s_cselect_b32 s53, s15, s46
	s_cselect_b32 s52, s78, s33
	s_cselect_b32 s47, s11, s82
	s_cselect_b32 s46, s13, s81
	v_lshl_add_u64 v[216:217], s[44:45], 0, v[138:139]
	s_add_i32 m0, s17, 0xc000
	global_load_lds_dwordx4 v[216:217], off
	v_lshl_add_u64 v[216:217], s[44:45], 0, v[140:141]
	s_add_i32 m0, s17, 0xe000
	s_nop 0
	global_load_lds_dwordx4 v[216:217], off
	s_waitcnt vmcnt(8)
	s_waitcnt lgkmcnt(0)
	s_barrier
	s_setprio 0
	v_mfma_f32_16x16x32_bf16 v[126:129], v[146:149], v[184:187], 0
	v_mfma_f32_16x16x32_bf16 v[122:125], v[160:163], v[184:187], 0
	v_mfma_f32_16x16x32_bf16 v[118:121], v[146:149], v[192:195], 0
	v_mfma_f32_16x16x32_bf16 v[110:113], v[160:163], v[192:195], 0
	v_mfma_f32_16x16x32_bf16 v[102:105], v[146:149], v[200:203], 0
	v_mfma_f32_16x16x32_bf16 v[94:97], v[160:163], v[200:203], 0
	v_mfma_f32_16x16x32_bf16 v[86:89], v[146:149], v[208:211], 0
	v_mfma_f32_16x16x32_bf16 v[78:81], v[160:163], v[208:211], 0
	v_mfma_f32_16x16x32_bf16 v[126:129], v[156:159], v[188:191], v[126:129]
	v_mfma_f32_16x16x32_bf16 v[122:125], v[164:167], v[188:191], v[122:125]
	v_mfma_f32_16x16x32_bf16 v[118:121], v[156:159], v[196:199], v[118:121]
	v_mfma_f32_16x16x32_bf16 v[110:113], v[164:167], v[196:199], v[110:113]
	v_mfma_f32_16x16x32_bf16 v[102:105], v[156:159], v[204:207], v[102:105]
	v_mfma_f32_16x16x32_bf16 v[94:97], v[164:167], v[204:207], v[94:97]
	v_mfma_f32_16x16x32_bf16 v[86:89], v[156:159], v[212:215], v[86:89]
	v_mfma_f32_16x16x32_bf16 v[78:81], v[164:167], v[212:215], v[78:81]
	s_setprio 2
	s_setprio 0
	v_mfma_f32_16x16x32_bf16 v[114:117], v[168:171], v[184:187], 0
	v_mfma_f32_16x16x32_bf16 v[106:109], v[176:179], v[184:187], 0
	v_mfma_f32_16x16x32_bf16 v[98:101], v[168:171], v[192:195], 0
	v_mfma_f32_16x16x32_bf16 v[90:93], v[176:179], v[192:195], 0
	v_mfma_f32_16x16x32_bf16 v[82:85], v[168:171], v[200:203], 0
	v_mfma_f32_16x16x32_bf16 v[74:77], v[176:179], v[200:203], 0
	v_mfma_f32_16x16x32_bf16 v[70:73], v[168:171], v[208:211], 0
	v_mfma_f32_16x16x32_bf16 v[66:69], v[176:179], v[208:211], 0
	v_mfma_f32_16x16x32_bf16 v[114:117], v[172:175], v[188:191], v[114:117]
	v_mfma_f32_16x16x32_bf16 v[106:109], v[180:183], v[188:191], v[106:109]
	v_mfma_f32_16x16x32_bf16 v[98:101], v[172:175], v[196:199], v[98:101]
	v_mfma_f32_16x16x32_bf16 v[90:93], v[180:183], v[196:199], v[90:93]
	v_mfma_f32_16x16x32_bf16 v[82:85], v[172:175], v[204:207], v[82:85]
	v_mfma_f32_16x16x32_bf16 v[74:77], v[180:183], v[204:207], v[74:77]
	v_mfma_f32_16x16x32_bf16 v[70:73], v[172:175], v[212:215], v[70:73]
	v_mfma_f32_16x16x32_bf16 v[66:69], v[180:183], v[212:215], v[66:69]
	s_setprio 2
	s_barrier
; #define PG8_STAGE(bufoff, gbase, voff) do { _Pragma("unroll") for (int _i = 0; _i < 2; ++_i) \
;         __builtin_amdgcn_global_load_lds((const unsigned*)((const char*)(gbase) + (voff)[_i]), (LAS unsigned*)(lds + (bufoff) + ldsw + _i * 8192), 16, 0, 0); } while (0)
; #define PG8_LDA(dst, b, h) do { _Pragma("unroll") for (int m = 0; m < 4; ++m) _Pragma("unroll") for (int k = 0; k < 2; ++k) dst[m][k] = *(const LAS bf16x8*)(lds + PG8_SA(b, h) + aoff + m * 2048 + k * 1024); } while (0)
; #define PG8_LDB(dst, b, h) do { _Pragma("unroll") for (int n = 0; n < 2; ++n) _Pragma("unroll") for (int k = 0; k < 2; ++k) dst[n][k] = *(const LAS bf16x8*)(lds + PG8_SB(b, h) + boff + n * 2048 + k * 1024); } while (0)
; #define PG8_MMA(ai, bj, At, Bt) do { __builtin_amdgcn_s_setprio(1); _Pragma("unroll") for (int m = 0; m < 4; ++m) _Pragma("unroll") for (int n = 0; n < 2; ++n) _Pragma("unroll") for (int k = 0; k < 2; ++k) \
;         acc[ai][bj][m][n] = __builtin_amdgcn_mfma_f32_16x16x32_bf16(Bt[n][k], At[m][k], acc[ai][bj][m][n], 0, 0, 0); __builtin_amdgcn_s_setprio(0); } while (0)
; #define PG8_WAIT_V(n) asm volatile("s_waitcnt vmcnt(" #n ")" ::: "memory")
; #define PG8_WAIT_L(n) asm volatile("s_waitcnt lgkmcnt(" #n ")" ::: "memory")
; #define PG8_BAR __builtin_amdgcn_s_barrier()
; #define PG8_SCHED __builtin_amdgcn_sched_barrier(0)
; template <class Epi>
; __device__ __forceinline__ void gemm_phase(LAS unsigned char* lds, const Gemm g, int G, int c, const Epi& E) {
;     ...
;             PG8_LDA(At, 0, 1); PG8_STAGE(PG8_SB(0, 0), b2, voffB); PG8_STAGE(PG8_SB(0, 1), b2 + hstepB, voffB); PG8_STAGE(PG8_SA(0, 0), a2, voffA);
;             PG8_WAIT_V(8); PG8_WAIT_L(0); PG8_BAR; PG8_MMA(1, 0, At, B0); PG8_MMA(1, 1, At, B1); PG8_BAR; PG8_SCHED;
;             PG8_LDB(B0, 1, 0); PG8_LDB(B1, 1, 1); PG8_SCHED; PG8_LDA(At, 1, 0); PG8_STAGE(PG8_SA(0, 1), a2 + hstepA, voffA);
;             PG8_WAIT_V(8); PG8_WAIT_L(0); PG8_BAR; PG8_MMA(0, 0, At, B0); PG8_MMA(0, 1, At, B1); PG8_BAR; PG8_SCHED;
	s_add_i32 s33, s72, s61
	v_lshl_add_u64 v[216:217], s[46:47], 0, v[134:135]
	s_mov_b32 m0, s33
	ds_read_b128 v[184:187], v154 offset:16384
	ds_read_b128 v[188:191], v154 offset:17408
	ds_read_b128 v[192:195], v154 offset:18432
	ds_read_b128 v[196:199], v154 offset:19456
	ds_read_b128 v[200:203], v154 offset:20480
	ds_read_b128 v[204:207], v154 offset:21504
	ds_read_b128 v[208:211], v154 offset:22528
	ds_read_b128 v[212:215], v154 offset:23552
	global_load_lds_dwordx4 v[216:217], off
	s_add_i32 m0, s33, 0x2000
	s_add_u32 s62, s46, 0x100000
	v_lshl_add_u64 v[218:219], s[46:47], 0, v[130:131]
	s_addc_u32 s63, s47, 0
	s_add_i32 s33, s73, s61
	global_load_lds_dwordx4 v[218:219], off
	v_lshl_add_u64 v[220:221], s[62:63], 0, v[134:135]
	s_mov_b32 m0, s33
	v_lshl_add_u64 v[224:225], s[52:53], 0, v[132:133]
	global_load_lds_dwordx4 v[220:221], off
	v_lshl_add_u64 v[220:221], s[62:63], 0, v[130:131]
	s_add_i32 m0, s33, 0x2000
	s_nop 0
	global_load_lds_dwordx4 v[220:221], off
	v_lshl_add_u64 v[220:221], s[52:53], 0, v[136:137]
	s_mov_b32 m0, s17
	s_nop 0
	global_load_lds_dwordx4 v[220:221], off
	s_mov_b32 m0, s39
	s_nop 0
	global_load_lds_dwordx4 v[224:225], off
	s_waitcnt vmcnt(8)
	s_waitcnt lgkmcnt(0)
	s_barrier
	s_setprio 0
	v_mfma_f32_16x16x32_bf16 v[62:65], v[146:149], v[184:187], 0
	v_mfma_f32_16x16x32_bf16 v[58:61], v[160:163], v[184:187], 0
	v_mfma_f32_16x16x32_bf16 v[54:57], v[146:149], v[192:195], 0
	v_mfma_f32_16x16x32_bf16 v[46:49], v[160:163], v[192:195], 0
	v_mfma_f32_16x16x32_bf16 v[38:41], v[146:149], v[200:203], 0
	v_mfma_f32_16x16x32_bf16 v[30:33], v[160:163], v[200:203], 0
	v_mfma_f32_16x16x32_bf16 v[22:25], v[146:149], v[208:211], 0
	v_mfma_f32_16x16x32_bf16 v[14:17], v[160:163], v[208:211], 0
	v_mfma_f32_16x16x32_bf16 v[62:65], v[156:159], v[188:191], v[62:65]
	v_mfma_f32_16x16x32_bf16 v[58:61], v[164:167], v[188:191], v[58:61]
	v_mfma_f32_16x16x32_bf16 v[54:57], v[156:159], v[196:199], v[54:57]
	v_mfma_f32_16x16x32_bf16 v[46:49], v[164:167], v[196:199], v[46:49]
	v_mfma_f32_16x16x32_bf16 v[38:41], v[156:159], v[204:207], v[38:41]
	v_mfma_f32_16x16x32_bf16 v[30:33], v[164:167], v[204:207], v[30:33]
	v_mfma_f32_16x16x32_bf16 v[22:25], v[156:159], v[212:215], v[22:25]
	v_mfma_f32_16x16x32_bf16 v[14:17], v[164:167], v[212:215], v[14:17]
	s_setprio 2
	s_setprio 0
	v_mfma_f32_16x16x32_bf16 v[50:53], v[168:171], v[184:187], 0
	v_mfma_f32_16x16x32_bf16 v[42:45], v[176:179], v[184:187], 0
	v_mfma_f32_16x16x32_bf16 v[34:37], v[168:171], v[192:195], 0
	v_mfma_f32_16x16x32_bf16 v[26:29], v[176:179], v[192:195], 0
	v_mfma_f32_16x16x32_bf16 v[18:21], v[168:171], v[200:203], 0
	v_mfma_f32_16x16x32_bf16 v[10:13], v[176:179], v[200:203], 0
	v_mfma_f32_16x16x32_bf16 v[6:9], v[168:171], v[208:211], 0
	v_mfma_f32_16x16x32_bf16 v[2:5], v[176:179], v[208:211], 0
	v_mfma_f32_16x16x32_bf16 v[50:53], v[172:175], v[188:191], v[50:53]
	v_mfma_f32_16x16x32_bf16 v[42:45], v[180:183], v[188:191], v[42:45]
	v_mfma_f32_16x16x32_bf16 v[34:37], v[172:175], v[196:199], v[34:37]
	v_mfma_f32_16x16x32_bf16 v[26:29], v[180:183], v[196:199], v[26:29]
	v_mfma_f32_16x16x32_bf16 v[18:21], v[172:175], v[204:207], v[18:21]
	v_mfma_f32_16x16x32_bf16 v[10:13], v[180:183], v[204:207], v[10:13]
	v_mfma_f32_16x16x32_bf16 v[6:9], v[172:175], v[212:215], v[6:9]
	v_mfma_f32_16x16x32_bf16 v[2:5], v[180:183], v[212:215], v[2:5]
	s_setprio 2
	s_barrier
	s_add_i32 s33, 0, 0x18000
	v_add_u32_e32 v155, s33, v151
	s_add_i32 s62, 0, 0x1c000
	ds_read_b128 v[146:149], v155
	ds_read_b128 v[156:159], v155 offset:1024
	ds_read_b128 v[160:163], v155 offset:2048
	ds_read_b128 v[164:167], v155 offset:3072
	v_add_u32_e32 v155, s62, v151
	ds_read_b128 v[168:171], v155
	ds_read_b128 v[172:175], v155 offset:1024
	ds_read_b128 v[176:179], v155 offset:2048
	ds_read_b128 v[180:183], v155 offset:3072
	s_add_u32 s52, s52, 0x100000
	s_addc_u32 s53, s53, 0
	s_mov_b32 m0, s43
	v_lshl_add_u64 v[226:227], s[52:53], 0, v[136:137]
	ds_read_b128 v[184:187], v154 offset:32768
	ds_read_b128 v[188:191], v154 offset:33792
	ds_read_b128 v[192:195], v154 offset:34816
	ds_read_b128 v[196:199], v154 offset:35840
	ds_read_b128 v[200:203], v154 offset:36864
	ds_read_b128 v[204:207], v154 offset:37888
	ds_read_b128 v[208:211], v154 offset:38912
	ds_read_b128 v[212:215], v154 offset:39936
	global_load_lds_dwordx4 v[226:227], off
	v_lshl_add_u64 v[226:227], s[52:53], 0, v[132:133]
	s_mov_b32 m0, s66
	s_nop 0
	global_load_lds_dwordx4 v[226:227], off
	s_waitcnt vmcnt(8)
	s_waitcnt lgkmcnt(0)
	s_barrier
; #define PG8_STAGE(bufoff, gbase, voff) do { _Pragma("unroll") for (int _i = 0; _i < 2; ++_i) \
;         __builtin_amdgcn_global_load_lds((const unsigned*)((const char*)(gbase) + (voff)[_i]), (LAS unsigned*)(lds + (bufoff) + ldsw + _i * 8192), 16, 0, 0); } while (0)
; #define PG8_LDA(dst, b, h) do { _Pragma("unroll") for (int m = 0; m < 4; ++m) _Pragma("unroll") for (int k = 0; k < 2; ++k) dst[m][k] = *(const LAS bf16x8*)(lds + PG8_SA(b, h) + aoff + m * 2048 + k * 1024); } while (0)
; #define PG8_MMA(ai, bj, At, Bt) do { __builtin_amdgcn_s_setprio(1); _Pragma("unroll") for (int m = 0; m < 4; ++m) _Pragma("unroll") for (int n = 0; n < 2; ++n) _Pragma("unroll") for (int k = 0; k < 2; ++k) \
;         acc[ai][bj][m][n] = __builtin_amdgcn_mfma_f32_16x16x32_bf16(Bt[n][k], At[m][k], acc[ai][bj][m][n], 0, 0, 0); __builtin_amdgcn_s_setprio(0); } while (0)
; #define PG8_WAIT_V(n) asm volatile("s_waitcnt vmcnt(" #n ")" ::: "memory")
; #define PG8_WAIT_L(n) asm volatile("s_waitcnt lgkmcnt(" #n ")" ::: "memory")
; #define PG8_BAR __builtin_amdgcn_s_barrier()
; #define PG8_SCHED __builtin_amdgcn_sched_barrier(0)
; template <class Epi>
; __device__ __forceinline__ void gemm_phase(LAS unsigned char* lds, const Gemm g, int G, int c, const Epi& E) {
;     ...
;             PG8_WAIT_V(8); PG8_WAIT_L(0); PG8_BAR; PG8_MMA(0, 0, At, B0); PG8_MMA(0, 1, At, B1); PG8_BAR; PG8_SCHED;
;             PG8_LDA(At, 1, 1); PG8_STAGE(PG8_SB(1, 0), b3, voffB); PG8_STAGE(PG8_SB(1, 1), b3 + hstepB, voffB); PG8_STAGE(PG8_SA(1, 0), a3, voffA);
;             PG8_WAIT_V(8); PG8_WAIT_L(0); PG8_BAR; PG8_MMA(1, 0, At, B0); PG8_MMA(1, 1, At, B1); PG8_BAR; PG8_SCHED;
;         }
	s_setprio 0
	v_mfma_f32_16x16x32_bf16 v[126:129], v[146:149], v[184:187], v[126:129]
	v_mfma_f32_16x16x32_bf16 v[122:125], v[160:163], v[184:187], v[122:125]
	v_mfma_f32_16x16x32_bf16 v[118:121], v[146:149], v[192:195], v[118:121]
	v_mfma_f32_16x16x32_bf16 v[110:113], v[160:163], v[192:195], v[110:113]
	v_mfma_f32_16x16x32_bf16 v[102:105], v[146:149], v[200:203], v[102:105]
	v_mfma_f32_16x16x32_bf16 v[94:97], v[160:163], v[200:203], v[94:97]
	v_mfma_f32_16x16x32_bf16 v[86:89], v[146:149], v[208:211], v[86:89]
	v_mfma_f32_16x16x32_bf16 v[78:81], v[160:163], v[208:211], v[78:81]
	v_mfma_f32_16x16x32_bf16 v[126:129], v[156:159], v[188:191], v[126:129]
	v_mfma_f32_16x16x32_bf16 v[122:125], v[164:167], v[188:191], v[122:125]
	v_mfma_f32_16x16x32_bf16 v[118:121], v[156:159], v[196:199], v[118:121]
	v_mfma_f32_16x16x32_bf16 v[110:113], v[164:167], v[196:199], v[110:113]
	v_mfma_f32_16x16x32_bf16 v[102:105], v[156:159], v[204:207], v[102:105]
	v_mfma_f32_16x16x32_bf16 v[94:97], v[164:167], v[204:207], v[94:97]
	v_mfma_f32_16x16x32_bf16 v[86:89], v[156:159], v[212:215], v[86:89]
	v_mfma_f32_16x16x32_bf16 v[78:81], v[164:167], v[212:215], v[78:81]
	s_setprio 2
	s_setprio 0
	v_mfma_f32_16x16x32_bf16 v[114:117], v[168:171], v[184:187], v[114:117]
	v_mfma_f32_16x16x32_bf16 v[106:109], v[176:179], v[184:187], v[106:109]
	v_mfma_f32_16x16x32_bf16 v[98:101], v[168:171], v[192:195], v[98:101]
	v_mfma_f32_16x16x32_bf16 v[90:93], v[176:179], v[192:195], v[90:93]
	v_mfma_f32_16x16x32_bf16 v[82:85], v[168:171], v[200:203], v[82:85]
	v_mfma_f32_16x16x32_bf16 v[74:77], v[176:179], v[200:203], v[74:77]
	v_mfma_f32_16x16x32_bf16 v[70:73], v[168:171], v[208:211], v[70:73]
	v_mfma_f32_16x16x32_bf16 v[66:69], v[176:179], v[208:211], v[66:69]
	v_mfma_f32_16x16x32_bf16 v[114:117], v[172:175], v[188:191], v[114:117]
	v_mfma_f32_16x16x32_bf16 v[106:109], v[180:183], v[188:191], v[106:109]
	v_mfma_f32_16x16x32_bf16 v[98:101], v[172:175], v[196:199], v[98:101]
	v_mfma_f32_16x16x32_bf16 v[90:93], v[180:183], v[196:199], v[90:93]
	v_mfma_f32_16x16x32_bf16 v[82:85], v[172:175], v[204:207], v[82:85]
	v_mfma_f32_16x16x32_bf16 v[74:77], v[180:183], v[204:207], v[74:77]
	v_mfma_f32_16x16x32_bf16 v[70:73], v[172:175], v[212:215], v[70:73]
	v_mfma_f32_16x16x32_bf16 v[66:69], v[180:183], v[212:215], v[66:69]
	s_setprio 2
	s_barrier
	s_add_i32 s33, s33, s61
	v_lshl_add_u64 v[216:217], v[216:217], 0, s[6:7]
	s_mov_b32 m0, s33
	ds_read_b128 v[184:187], v154 offset:49152
	ds_read_b128 v[188:191], v154 offset:50176
	ds_read_b128 v[192:195], v154 offset:51200
	ds_read_b128 v[196:199], v154 offset:52224
	ds_read_b128 v[200:203], v154 offset:53248
	ds_read_b128 v[204:207], v154 offset:54272
	ds_read_b128 v[208:211], v154 offset:55296
	ds_read_b128 v[212:215], v154 offset:56320
	global_load_lds_dwordx4 v[216:217], off
	s_add_i32 m0, s33, 0x2000
	s_add_u32 s46, s46, 0x100080
	v_lshl_add_u64 v[216:217], v[218:219], 0, s[6:7]
	s_addc_u32 s47, s47, 0
	s_add_i32 s33, s62, s61
	global_load_lds_dwordx4 v[216:217], off
	v_lshl_add_u64 v[216:217], s[46:47], 0, v[134:135]
	s_mov_b32 m0, s33
	s_nop 0
	global_load_lds_dwordx4 v[216:217], off
	v_lshl_add_u64 v[216:217], s[46:47], 0, v[130:131]
	s_add_i32 m0, s33, 0x2000
	s_nop 0
	global_load_lds_dwordx4 v[216:217], off
	v_lshl_add_u64 v[216:217], v[220:221], 0, s[6:7]
	s_mov_b32 m0, s70
	s_nop 0
	global_load_lds_dwordx4 v[216:217], off
	v_lshl_add_u64 v[216:217], v[224:225], 0, s[6:7]
	s_mov_b32 m0, s71
	s_nop 0
	global_load_lds_dwordx4 v[216:217], off
	s_waitcnt vmcnt(8)
	s_waitcnt lgkmcnt(0)
	s_barrier
	s_setprio 0
	v_mfma_f32_16x16x32_bf16 v[62:65], v[146:149], v[184:187], v[62:65]
	v_mfma_f32_16x16x32_bf16 v[58:61], v[160:163], v[184:187], v[58:61]
	v_mfma_f32_16x16x32_bf16 v[54:57], v[146:149], v[192:195], v[54:57]
	v_mfma_f32_16x16x32_bf16 v[46:49], v[160:163], v[192:195], v[46:49]
	v_mfma_f32_16x16x32_bf16 v[38:41], v[146:149], v[200:203], v[38:41]
	v_mfma_f32_16x16x32_bf16 v[30:33], v[160:163], v[200:203], v[30:33]
	v_mfma_f32_16x16x32_bf16 v[22:25], v[146:149], v[208:211], v[22:25]
	v_mfma_f32_16x16x32_bf16 v[14:17], v[160:163], v[208:211], v[14:17]
	v_mfma_f32_16x16x32_bf16 v[62:65], v[156:159], v[188:191], v[62:65]
	v_mfma_f32_16x16x32_bf16 v[58:61], v[164:167], v[188:191], v[58:61]
	v_mfma_f32_16x16x32_bf16 v[54:57], v[156:159], v[196:199], v[54:57]
	v_mfma_f32_16x16x32_bf16 v[46:49], v[164:167], v[196:199], v[46:49]
	v_mfma_f32_16x16x32_bf16 v[38:41], v[156:159], v[204:207], v[38:41]
	v_mfma_f32_16x16x32_bf16 v[30:33], v[164:167], v[204:207], v[30:33]
	v_mfma_f32_16x16x32_bf16 v[22:25], v[156:159], v[212:215], v[22:25]
	v_mfma_f32_16x16x32_bf16 v[14:17], v[164:167], v[212:215], v[14:17]
	s_setprio 2
	s_setprio 0
	v_mfma_f32_16x16x32_bf16 v[50:53], v[168:171], v[184:187], v[50:53]
	v_mfma_f32_16x16x32_bf16 v[42:45], v[176:179], v[184:187], v[42:45]
	v_mfma_f32_16x16x32_bf16 v[34:37], v[168:171], v[192:195], v[34:37]
	v_mfma_f32_16x16x32_bf16 v[26:29], v[176:179], v[192:195], v[26:29]
	v_mfma_f32_16x16x32_bf16 v[18:21], v[168:171], v[200:203], v[18:21]
	v_mfma_f32_16x16x32_bf16 v[10:13], v[176:179], v[200:203], v[10:13]
	v_mfma_f32_16x16x32_bf16 v[6:9], v[168:171], v[208:211], v[6:9]
	v_mfma_f32_16x16x32_bf16 v[2:5], v[176:179], v[208:211], v[2:5]
	v_mfma_f32_16x16x32_bf16 v[50:53], v[172:175], v[188:191], v[50:53]
	v_mfma_f32_16x16x32_bf16 v[42:45], v[180:183], v[188:191], v[42:45]
	v_mfma_f32_16x16x32_bf16 v[34:37], v[172:175], v[196:199], v[34:37]
	v_mfma_f32_16x16x32_bf16 v[26:29], v[180:183], v[196:199], v[26:29]
	v_mfma_f32_16x16x32_bf16 v[18:21], v[172:175], v[204:207], v[18:21]
	v_mfma_f32_16x16x32_bf16 v[10:13], v[180:183], v[204:207], v[10:13]
	v_mfma_f32_16x16x32_bf16 v[6:9], v[172:175], v[212:215], v[6:9]
	v_mfma_f32_16x16x32_bf16 v[2:5], v[180:183], v[212:215], v[2:5]
	s_setprio 2
	s_barrier
	s_add_i32 s83, s83, 2
	s_add_u32 s44, s44, 0x100
	s_addc_u32 s45, s45, 0
	s_add_u32 s81, s81, 0x100
	s_addc_u32 s82, s82, 0
	s_cmp_gt_u32 s83, 61
	s_cbranch_scc0 .LBB0_765

; #define PG8_STAGE(bufoff, gbase, voff) do { _Pragma("unroll") for (int _i = 0; _i < 2; ++_i) \
;         __builtin_amdgcn_global_load_lds((const unsigned*)((const char*)(gbase) + (voff)[_i]), (LAS unsigned*)(lds + (bufoff) + ldsw + _i * 8192), 16, 0, 0); } while (0)
; #define PG8_LDA(dst, b, h) do { _Pragma("unroll") for (int m = 0; m < 4; ++m) _Pragma("unroll") for (int k = 0; k < 2; ++k) dst[m][k] = *(const LAS bf16x8*)(lds + PG8_SA(b, h) + aoff + m * 2048 + k * 1024); } while (0)
; #define PG8_LDB(dst, b, h) do { _Pragma("unroll") for (int n = 0; n < 2; ++n) _Pragma("unroll") for (int k = 0; k < 2; ++k) dst[n][k] = *(const LAS bf16x8*)(lds + PG8_SB(b, h) + boff + n * 2048 + k * 1024); } while (0)
; #define PG8_WAIT_V(n) asm volatile("s_waitcnt vmcnt(" #n ")" ::: "memory")
;     __device__ __forceinline__ bool next(int i, Unit& u) const {
;         const long L = (long)i * G + c; if (L >= nwg) return false;
;         int w = (int)L; { const int q = nwg / NXCD, r = nwg % NXCD, xcd = w % NXCD, off = w / NXCD; w = (xcd < r ? xcd * (q + 1) : r * (q + 1) + (xcd - r) * q) + off; }
;         u.pb = w / per; w -= u.pb * per;
;         const int nig = WGM * nN, gid = w / nig, fm = gid * WGM, gsz = (nM - fm) < WGM ? (nM - fm) : WGM;
;         u.pm = fm + ((w % nig) % gsz); u.pn = (w % nig) / gsz; return true;
; template <class Epi>
; __device__ __forceinline__ void gemm_phase(LAS unsigned char* lds, const Gemm g, int G, int c, const Epi& E) {
;     ...
;         const bool has_next = S.next(ui + 1, nxt);
;         const char* nA = has_next ? (const char*)(g.A + (size_t)nxt.pb * g.sA) + (size_t)nxt.pm * 2 * hstepA : cA;
;         const char* nB = has_next ? (const char*)(g.Bt + (size_t)nxt.pb * g.sB) + (size_t)nxt.pn * 2 * hstepB : cB;
; #pragma nounroll
;         for (int t = 0; t < nt; t += 2) {
;             const bool last = (t == nt - 2);
;             const char* a1 = cA + (size_t)(t + 1) * kstep;
;             const char* a2 = last ? nA : cA + (size_t)(t + 2) * kstep; const char* b2 = last ? nB : cB + (size_t)(t + 2) * kstep;
;             const char* a3 = a2 + kstep; const char* b3 = b2 + kstep;
;             PG8_LDB(B0, 0, 0); PG8_LDB(B1, 0, 1); PG8_SCHED; PG8_LDA(At, 0, 0); PG8_STAGE(PG8_SA(1, 1), a1 + hstepA, voffA);
;             PG8_WAIT_V(8); PG8_WAIT_L(0); PG8_BAR; PG8_MMA(0, 0, At, B0); PG8_MMA(0, 1, At, B1); PG8_BAR; PG8_SCHED;
.LBB0_778:
	ds_read_b128 v[150:153], v146
	ds_read_b128 v[154:157], v146 offset:1024
	ds_read_b128 v[158:161], v146 offset:2048
	ds_read_b128 v[162:165], v146 offset:3072
	ds_read_b128 v[166:169], v147
	ds_read_b128 v[170:173], v147 offset:1024
	ds_read_b128 v[174:177], v147 offset:2048
	ds_read_b128 v[178:181], v147 offset:3072
	ds_read_b128 v[182:185], v148
	ds_read_b128 v[186:189], v148 offset:1024
	ds_read_b128 v[190:193], v148 offset:2048
	ds_read_b128 v[194:197], v148 offset:3072
	ds_read_b128 v[198:201], v148 offset:4096
	ds_read_b128 v[202:205], v148 offset:5120
	ds_read_b128 v[206:209], v148 offset:6144
	ds_read_b128 v[210:213], v148 offset:7168
	s_add_i32 s68, s68, 1
	s_mul_i32 s25, s68, s35
	s_mul_hi_u32 s33, s68, s27
	s_add_i32 s33, s33, s25
	s_mul_i32 s25, s68, s27
	s_add_u32 s42, s25, s26
	s_addc_u32 s43, s33, s34
	v_cmp_gt_i64_e64 s[52:53], s[42:43], 31
	v_cmp_lt_i64_e64 s[38:39], s[42:43], 32
	s_and_b64 vcc, exec, s[52:53]
	s_cbranch_vccnz .LBB0_780
	s_ashr_i32 s24, s42, 31
	s_lshr_b32 s24, s24, 29
	s_add_i32 s24, s42, s24
	s_ashr_i32 s25, s24, 3
	s_and_b32 s24, s24, -8
	s_sub_i32 s24, s42, s24
	s_lshr_b32 s33, s24, 31
	s_or_b32 s33, s33, 4
	s_mul_i32 s24, s33, s24
	s_add_i32 s24, s24, s25
.LBB0_780:
	s_ashr_i32 s25, s24, 31
	s_lshl_b64 s[42:43], s[24:25], 18
	s_add_u32 s42, s59, s42
	s_addc_u32 s43, s60, s43
	s_and_b64 s[52:53], s[38:39], exec
	s_cselect_b32 s25, s43, s47
	s_cselect_b32 s89, s42, s46
	s_add_u32 s90, s46, 0x100
	s_addc_u32 s91, s47, 0
	s_mov_b32 s92, -2
	s_mov_b64 s[46:47], 0
	s_add_u32 s52, s46, 0x100
	s_addc_u32 s53, s47, 0
	s_add_u32 s33, s90, s46
	s_addc_u32 s55, s91, s47
	s_cmp_eq_u32 s92, 4
	s_cselect_b32 s56, 0, s52
	s_cselect_b32 s57, 0, s53
	s_cselect_b32 s54, s89, s33
	s_cselect_b32 s55, s25, s55
	s_add_u32 s56, s2, s56
	s_addc_u32 s57, s3, s57
	s_mov_b32 m0, s83
	v_lshl_add_u64 v[142:143], v[138:139], 0, s[46:47]
	global_load_lds_dwordx4 v[142:143], off
	v_lshl_add_u64 v[142:143], v[140:141], 0, s[46:47]
	s_mov_b32 m0, s84
	s_nop 0
	global_load_lds_dwordx4 v[142:143], off
	s_waitcnt vmcnt(8)
	s_waitcnt lgkmcnt(0)
	s_barrier
	s_setprio 0
	v_mfma_f32_16x16x32_bf16 v[126:129], v[150:153], v[182:185], 0
	v_mfma_f32_16x16x32_bf16 v[122:125], v[158:161], v[182:185], 0
	v_mfma_f32_16x16x32_bf16 v[118:121], v[150:153], v[190:193], 0
	v_mfma_f32_16x16x32_bf16 v[110:113], v[158:161], v[190:193], 0
	v_mfma_f32_16x16x32_bf16 v[102:105], v[150:153], v[198:201], 0
	v_mfma_f32_16x16x32_bf16 v[94:97], v[158:161], v[198:201], 0
	v_mfma_f32_16x16x32_bf16 v[86:89], v[150:153], v[206:209], 0
	v_mfma_f32_16x16x32_bf16 v[78:81], v[158:161], v[206:209], 0
	v_mfma_f32_16x16x32_bf16 v[126:129], v[154:157], v[186:189], v[126:129]
	v_mfma_f32_16x16x32_bf16 v[122:125], v[162:165], v[186:189], v[122:125]
	v_mfma_f32_16x16x32_bf16 v[118:121], v[154:157], v[194:197], v[118:121]
	v_mfma_f32_16x16x32_bf16 v[110:113], v[162:165], v[194:197], v[110:113]
	v_mfma_f32_16x16x32_bf16 v[102:105], v[154:157], v[202:205], v[102:105]
	v_mfma_f32_16x16x32_bf16 v[94:97], v[162:165], v[202:205], v[94:97]
	v_mfma_f32_16x16x32_bf16 v[86:89], v[154:157], v[210:213], v[86:89]
	v_mfma_f32_16x16x32_bf16 v[78:81], v[162:165], v[210:213], v[78:81]
	s_setprio 2
	s_setprio 0
	v_mfma_f32_16x16x32_bf16 v[114:117], v[166:169], v[182:185], 0
	v_mfma_f32_16x16x32_bf16 v[106:109], v[174:177], v[182:185], 0
	v_mfma_f32_16x16x32_bf16 v[98:101], v[166:169], v[190:193], 0
	v_mfma_f32_16x16x32_bf16 v[90:93], v[174:177], v[190:193], 0
	v_mfma_f32_16x16x32_bf16 v[82:85], v[166:169], v[198:201], 0
	v_mfma_f32_16x16x32_bf16 v[74:77], v[174:177], v[198:201], 0
	v_mfma_f32_16x16x32_bf16 v[70:73], v[166:169], v[206:209], 0
	v_mfma_f32_16x16x32_bf16 v[66:69], v[174:177], v[206:209], 0
	v_mfma_f32_16x16x32_bf16 v[114:117], v[170:173], v[186:189], v[114:117]
	v_mfma_f32_16x16x32_bf16 v[106:109], v[178:181], v[186:189], v[106:109]
	v_mfma_f32_16x16x32_bf16 v[98:101], v[170:173], v[194:197], v[98:101]
	v_mfma_f32_16x16x32_bf16 v[90:93], v[178:181], v[194:197], v[90:93]
	v_mfma_f32_16x16x32_bf16 v[82:85], v[170:173], v[202:205], v[82:85]
	v_mfma_f32_16x16x32_bf16 v[74:77], v[178:181], v[202:205], v[74:77]
	v_mfma_f32_16x16x32_bf16 v[70:73], v[170:173], v[210:213], v[70:73]
	v_mfma_f32_16x16x32_bf16 v[66:69], v[178:181], v[210:213], v[66:69]
	s_setprio 2
	s_barrier
	s_mov_b32 m0, s85
	v_lshl_add_u64 v[142:143], s[54:55], 0, v[134:135]
	s_add_u32 s46, s54, 0x20000
	ds_read_b128 v[182:185], v148 offset:16384
	ds_read_b128 v[186:189], v148 offset:17408
	ds_read_b128 v[190:193], v148 offset:18432
	ds_read_b128 v[194:197], v148 offset:19456
	ds_read_b128 v[198:201], v148 offset:20480
	ds_read_b128 v[202:205], v148 offset:21504
	ds_read_b128 v[206:209], v148 offset:22528
	ds_read_b128 v[210:213], v148 offset:23552
	global_load_lds_dwordx4 v[142:143], off
	v_lshl_add_u64 v[214:215], s[54:55], 0, v[130:131]
	s_mov_b32 m0, s86
	s_addc_u32 s47, s55, 0
	global_load_lds_dwordx4 v[214:215], off
	v_lshl_add_u64 v[216:217], s[46:47], 0, v[134:135]
	s_mov_b32 m0, s87
	v_lshl_add_u64 v[218:219], s[56:57], 0, v[132:133]
	global_load_lds_dwordx4 v[216:217], off
	v_lshl_add_u64 v[216:217], s[46:47], 0, v[130:131]
	s_mov_b32 m0, s88
	s_nop 0
	global_load_lds_dwordx4 v[216:217], off
	v_lshl_add_u64 v[216:217], s[56:57], 0, v[136:137]
	s_mov_b32 m0, s45
	s_nop 0
	global_load_lds_dwordx4 v[216:217], off
	s_mov_b32 m0, s61
	s_nop 0
	global_load_lds_dwordx4 v[218:219], off
	s_waitcnt vmcnt(8)
	s_waitcnt lgkmcnt(0)
	s_barrier
; #define PG8_STAGE(bufoff, gbase, voff) do { _Pragma("unroll") for (int _i = 0; _i < 2; ++_i) \
;         __builtin_amdgcn_global_load_lds((const unsigned*)((const char*)(gbase) + (voff)[_i]), (LAS unsigned*)(lds + (bufoff) + ldsw + _i * 8192), 16, 0, 0); } while (0)
; #define PG8_LDA(dst, b, h) do { _Pragma("unroll") for (int m = 0; m < 4; ++m) _Pragma("unroll") for (int k = 0; k < 2; ++k) dst[m][k] = *(const LAS bf16x8*)(lds + PG8_SA(b, h) + aoff + m * 2048 + k * 1024); } while (0)
; #define PG8_LDB(dst, b, h) do { _Pragma("unroll") for (int n = 0; n < 2; ++n) _Pragma("unroll") for (int k = 0; k < 2; ++k) dst[n][k] = *(const LAS bf16x8*)(lds + PG8_SB(b, h) + boff + n * 2048 + k * 1024); } while (0)
; #define PG8_MMA(ai, bj, At, Bt) do { __builtin_amdgcn_s_setprio(1); _Pragma("unroll") for (int m = 0; m < 4; ++m) _Pragma("unroll") for (int n = 0; n < 2; ++n) _Pragma("unroll") for (int k = 0; k < 2; ++k) \
;         acc[ai][bj][m][n] = __builtin_amdgcn_mfma_f32_16x16x32_bf16(Bt[n][k], At[m][k], acc[ai][bj][m][n], 0, 0, 0); __builtin_amdgcn_s_setprio(0); } while (0)
; #define PG8_WAIT_V(n) asm volatile("s_waitcnt vmcnt(" #n ")" ::: "memory")
; #define PG8_WAIT_L(n) asm volatile("s_waitcnt lgkmcnt(" #n ")" ::: "memory")
; #define PG8_BAR __builtin_amdgcn_s_barrier()
; #define PG8_SCHED __builtin_amdgcn_sched_barrier(0)
; template <class Epi>
; __device__ __forceinline__ void gemm_phase(LAS unsigned char* lds, const Gemm g, int G, int c, const Epi& E) {
;     ...
;             PG8_WAIT_V(8); PG8_WAIT_L(0); PG8_BAR; PG8_MMA(1, 0, At, B0); PG8_MMA(1, 1, At, B1); PG8_BAR; PG8_SCHED;
;             PG8_LDB(B0, 1, 0); PG8_LDB(B1, 1, 1); PG8_SCHED; PG8_LDA(At, 1, 0); PG8_STAGE(PG8_SA(0, 1), a2 + hstepA, voffA);
;             PG8_WAIT_V(8); PG8_WAIT_L(0); PG8_BAR; PG8_MMA(0, 0, At, B0); PG8_MMA(0, 1, At, B1); PG8_BAR; PG8_SCHED;
	s_setprio 0
	v_mfma_f32_16x16x32_bf16 v[62:65], v[150:153], v[182:185], 0
	v_mfma_f32_16x16x32_bf16 v[58:61], v[158:161], v[182:185], 0
	v_mfma_f32_16x16x32_bf16 v[54:57], v[150:153], v[190:193], 0
	v_mfma_f32_16x16x32_bf16 v[46:49], v[158:161], v[190:193], 0
	v_mfma_f32_16x16x32_bf16 v[38:41], v[150:153], v[198:201], 0
	v_mfma_f32_16x16x32_bf16 v[30:33], v[158:161], v[198:201], 0
	v_mfma_f32_16x16x32_bf16 v[22:25], v[150:153], v[206:209], 0
	v_mfma_f32_16x16x32_bf16 v[14:17], v[158:161], v[206:209], 0
	v_mfma_f32_16x16x32_bf16 v[62:65], v[154:157], v[186:189], v[62:65]
	v_mfma_f32_16x16x32_bf16 v[58:61], v[162:165], v[186:189], v[58:61]
	v_mfma_f32_16x16x32_bf16 v[54:57], v[154:157], v[194:197], v[54:57]
	v_mfma_f32_16x16x32_bf16 v[46:49], v[162:165], v[194:197], v[46:49]
	v_mfma_f32_16x16x32_bf16 v[38:41], v[154:157], v[202:205], v[38:41]
	v_mfma_f32_16x16x32_bf16 v[30:33], v[162:165], v[202:205], v[30:33]
	v_mfma_f32_16x16x32_bf16 v[22:25], v[154:157], v[210:213], v[22:25]
	v_mfma_f32_16x16x32_bf16 v[14:17], v[162:165], v[210:213], v[14:17]
	s_setprio 2
	s_setprio 0
	v_mfma_f32_16x16x32_bf16 v[50:53], v[166:169], v[182:185], 0
	v_mfma_f32_16x16x32_bf16 v[42:45], v[174:177], v[182:185], 0
	v_mfma_f32_16x16x32_bf16 v[34:37], v[166:169], v[190:193], 0
	v_mfma_f32_16x16x32_bf16 v[26:29], v[174:177], v[190:193], 0
	v_mfma_f32_16x16x32_bf16 v[18:21], v[166:169], v[198:201], 0
	v_mfma_f32_16x16x32_bf16 v[10:13], v[174:177], v[198:201], 0
	v_mfma_f32_16x16x32_bf16 v[6:9], v[166:169], v[206:209], 0
	v_mfma_f32_16x16x32_bf16 v[2:5], v[174:177], v[206:209], 0
	v_mfma_f32_16x16x32_bf16 v[50:53], v[170:173], v[186:189], v[50:53]
	v_mfma_f32_16x16x32_bf16 v[42:45], v[178:181], v[186:189], v[42:45]
	v_mfma_f32_16x16x32_bf16 v[34:37], v[170:173], v[194:197], v[34:37]
	v_mfma_f32_16x16x32_bf16 v[26:29], v[178:181], v[194:197], v[26:29]
	v_mfma_f32_16x16x32_bf16 v[18:21], v[170:173], v[202:205], v[18:21]
	v_mfma_f32_16x16x32_bf16 v[10:13], v[178:181], v[202:205], v[10:13]
	v_mfma_f32_16x16x32_bf16 v[6:9], v[170:173], v[210:213], v[6:9]
	v_mfma_f32_16x16x32_bf16 v[2:5], v[178:181], v[210:213], v[2:5]
	s_setprio 2
	s_barrier
	s_add_i32 s33, 0, 0x18000
	v_add_u32_e32 v149, s33, v145
	s_add_i32 s62, 0, 0x1c000
	ds_read_b128 v[150:153], v149
	ds_read_b128 v[154:157], v149 offset:1024
	ds_read_b128 v[158:161], v149 offset:2048
	ds_read_b128 v[162:165], v149 offset:3072
	v_add_u32_e32 v149, s62, v145
	ds_read_b128 v[166:169], v149
	ds_read_b128 v[170:173], v149 offset:1024
	ds_read_b128 v[174:177], v149 offset:2048
	ds_read_b128 v[178:181], v149 offset:3072
	s_add_u32 s46, s56, 0x20000
	s_addc_u32 s47, s57, 0
	s_mov_b32 m0, s66
	v_lshl_add_u64 v[220:221], s[46:47], 0, v[136:137]
	ds_read_b128 v[182:185], v148 offset:32768
	ds_read_b128 v[186:189], v148 offset:33792
	ds_read_b128 v[190:193], v148 offset:34816
	ds_read_b128 v[194:197], v148 offset:35840
	ds_read_b128 v[198:201], v148 offset:36864
	ds_read_b128 v[202:205], v148 offset:37888
	ds_read_b128 v[206:209], v148 offset:38912
	ds_read_b128 v[210:213], v148 offset:39936
	global_load_lds_dwordx4 v[220:221], off
	v_lshl_add_u64 v[220:221], s[46:47], 0, v[132:133]
	s_mov_b32 m0, s67
	s_nop 0
	global_load_lds_dwordx4 v[220:221], off
	s_waitcnt vmcnt(8)
	s_waitcnt lgkmcnt(0)
	s_barrier
	s_setprio 0
	v_mfma_f32_16x16x32_bf16 v[126:129], v[150:153], v[182:185], v[126:129]
	v_mfma_f32_16x16x32_bf16 v[122:125], v[158:161], v[182:185], v[122:125]
	v_mfma_f32_16x16x32_bf16 v[118:121], v[150:153], v[190:193], v[118:121]
	v_mfma_f32_16x16x32_bf16 v[110:113], v[158:161], v[190:193], v[110:113]
	v_mfma_f32_16x16x32_bf16 v[102:105], v[150:153], v[198:201], v[102:105]
	v_mfma_f32_16x16x32_bf16 v[94:97], v[158:161], v[198:201], v[94:97]
	v_mfma_f32_16x16x32_bf16 v[86:89], v[150:153], v[206:209], v[86:89]
	v_mfma_f32_16x16x32_bf16 v[78:81], v[158:161], v[206:209], v[78:81]
	v_mfma_f32_16x16x32_bf16 v[126:129], v[154:157], v[186:189], v[126:129]
	v_mfma_f32_16x16x32_bf16 v[122:125], v[162:165], v[186:189], v[122:125]
	v_mfma_f32_16x16x32_bf16 v[118:121], v[154:157], v[194:197], v[118:121]
	v_mfma_f32_16x16x32_bf16 v[110:113], v[162:165], v[194:197], v[110:113]
	v_mfma_f32_16x16x32_bf16 v[102:105], v[154:157], v[202:205], v[102:105]
	v_mfma_f32_16x16x32_bf16 v[94:97], v[162:165], v[202:205], v[94:97]
	v_mfma_f32_16x16x32_bf16 v[86:89], v[154:157], v[210:213], v[86:89]
	v_mfma_f32_16x16x32_bf16 v[78:81], v[162:165], v[210:213], v[78:81]
	s_setprio 2
	s_setprio 0
	v_mfma_f32_16x16x32_bf16 v[114:117], v[166:169], v[182:185], v[114:117]
	v_mfma_f32_16x16x32_bf16 v[106:109], v[174:177], v[182:185], v[106:109]
	v_mfma_f32_16x16x32_bf16 v[98:101], v[166:169], v[190:193], v[98:101]
	v_mfma_f32_16x16x32_bf16 v[90:93], v[174:177], v[190:193], v[90:93]
	v_mfma_f32_16x16x32_bf16 v[82:85], v[166:169], v[198:201], v[82:85]
	v_mfma_f32_16x16x32_bf16 v[74:77], v[174:177], v[198:201], v[74:77]
	v_mfma_f32_16x16x32_bf16 v[70:73], v[166:169], v[206:209], v[70:73]
	v_mfma_f32_16x16x32_bf16 v[66:69], v[174:177], v[206:209], v[66:69]
	v_mfma_f32_16x16x32_bf16 v[114:117], v[170:173], v[186:189], v[114:117]
	v_mfma_f32_16x16x32_bf16 v[106:109], v[178:181], v[186:189], v[106:109]
	v_mfma_f32_16x16x32_bf16 v[98:101], v[170:173], v[194:197], v[98:101]
	v_mfma_f32_16x16x32_bf16 v[90:93], v[178:181], v[194:197], v[90:93]
	v_mfma_f32_16x16x32_bf16 v[82:85], v[170:173], v[202:205], v[82:85]
	v_mfma_f32_16x16x32_bf16 v[74:77], v[178:181], v[202:205], v[74:77]
	v_mfma_f32_16x16x32_bf16 v[70:73], v[170:173], v[210:213], v[70:73]
	v_mfma_f32_16x16x32_bf16 v[66:69], v[178:181], v[210:213], v[66:69]
	s_setprio 2
	s_barrier
; #define PG8_STAGE(bufoff, gbase, voff) do { _Pragma("unroll") for (int _i = 0; _i < 2; ++_i) \
;         __builtin_amdgcn_global_load_lds((const unsigned*)((const char*)(gbase) + (voff)[_i]), (LAS unsigned*)(lds + (bufoff) + ldsw + _i * 8192), 16, 0, 0); } while (0)
; #define PG8_LDA(dst, b, h) do { _Pragma("unroll") for (int m = 0; m < 4; ++m) _Pragma("unroll") for (int k = 0; k < 2; ++k) dst[m][k] = *(const LAS bf16x8*)(lds + PG8_SA(b, h) + aoff + m * 2048 + k * 1024); } while (0)
; #define PG8_MMA(ai, bj, At, Bt) do { __builtin_amdgcn_s_setprio(1); _Pragma("unroll") for (int m = 0; m < 4; ++m) _Pragma("unroll") for (int n = 0; n < 2; ++n) _Pragma("unroll") for (int k = 0; k < 2; ++k) \
;         acc[ai][bj][m][n] = __builtin_amdgcn_mfma_f32_16x16x32_bf16(Bt[n][k], At[m][k], acc[ai][bj][m][n], 0, 0, 0); __builtin_amdgcn_s_setprio(0); } while (0)
; #define PG8_WAIT_V(n) asm volatile("s_waitcnt vmcnt(" #n ")" ::: "memory")
; #define PG8_WAIT_L(n) asm volatile("s_waitcnt lgkmcnt(" #n ")" ::: "memory")
; #define PG8_BAR __builtin_amdgcn_s_barrier()
; #define PG8_SCHED __builtin_amdgcn_sched_barrier(0)
; template <class Epi>
; __device__ __forceinline__ void gemm_phase(LAS unsigned char* lds, const Gemm g, int G, int c, const Epi& E) {
;     ...
;             PG8_LDA(At, 1, 1); PG8_STAGE(PG8_SB(1, 0), b3, voffB); PG8_STAGE(PG8_SB(1, 1), b3 + hstepB, voffB); PG8_STAGE(PG8_SA(1, 0), a3, voffA);
;             PG8_WAIT_V(8); PG8_WAIT_L(0); PG8_BAR; PG8_MMA(1, 0, At, B0); PG8_MMA(1, 1, At, B1); PG8_BAR; PG8_SCHED;
;         }
	s_add_i32 s33, s33, s58
	v_lshl_add_u64 v[142:143], v[142:143], 0, s[6:7]
	s_mov_b32 m0, s33
	ds_read_b128 v[182:185], v148 offset:49152
	ds_read_b128 v[186:189], v148 offset:50176
	ds_read_b128 v[190:193], v148 offset:51200
	ds_read_b128 v[194:197], v148 offset:52224
	ds_read_b128 v[198:201], v148 offset:53248
	ds_read_b128 v[202:205], v148 offset:54272
	ds_read_b128 v[206:209], v148 offset:55296
	ds_read_b128 v[210:213], v148 offset:56320
	global_load_lds_dwordx4 v[142:143], off
	s_add_i32 m0, s33, 0x2000
	s_add_u32 s46, s54, 0x20080
	v_lshl_add_u64 v[142:143], v[214:215], 0, s[6:7]
	s_addc_u32 s47, s55, 0
	s_add_i32 s33, s62, s58
	global_load_lds_dwordx4 v[142:143], off
	v_lshl_add_u64 v[142:143], s[46:47], 0, v[134:135]
	s_mov_b32 m0, s33
	s_nop 0
	global_load_lds_dwordx4 v[142:143], off
	v_lshl_add_u64 v[142:143], s[46:47], 0, v[130:131]
	s_add_i32 m0, s33, 0x2000
	s_nop 0
	global_load_lds_dwordx4 v[142:143], off
	v_lshl_add_u64 v[142:143], v[216:217], 0, s[6:7]
	s_mov_b32 m0, s71
	s_nop 0
	global_load_lds_dwordx4 v[142:143], off
	v_lshl_add_u64 v[142:143], v[218:219], 0, s[6:7]
	s_mov_b32 m0, s72
	s_nop 0
	global_load_lds_dwordx4 v[142:143], off
	s_waitcnt vmcnt(8)
	s_waitcnt lgkmcnt(0)
	s_barrier
	s_setprio 0
	v_mfma_f32_16x16x32_bf16 v[62:65], v[150:153], v[182:185], v[62:65]
	v_mfma_f32_16x16x32_bf16 v[58:61], v[158:161], v[182:185], v[58:61]
	v_mfma_f32_16x16x32_bf16 v[54:57], v[150:153], v[190:193], v[54:57]
	v_mfma_f32_16x16x32_bf16 v[46:49], v[158:161], v[190:193], v[46:49]
	v_mfma_f32_16x16x32_bf16 v[38:41], v[150:153], v[198:201], v[38:41]
	v_mfma_f32_16x16x32_bf16 v[30:33], v[158:161], v[198:201], v[30:33]
	v_mfma_f32_16x16x32_bf16 v[22:25], v[150:153], v[206:209], v[22:25]
	v_mfma_f32_16x16x32_bf16 v[14:17], v[158:161], v[206:209], v[14:17]
	v_mfma_f32_16x16x32_bf16 v[62:65], v[154:157], v[186:189], v[62:65]
	v_mfma_f32_16x16x32_bf16 v[58:61], v[162:165], v[186:189], v[58:61]
	v_mfma_f32_16x16x32_bf16 v[54:57], v[154:157], v[194:197], v[54:57]
	v_mfma_f32_16x16x32_bf16 v[46:49], v[162:165], v[194:197], v[46:49]
	v_mfma_f32_16x16x32_bf16 v[38:41], v[154:157], v[202:205], v[38:41]
	v_mfma_f32_16x16x32_bf16 v[30:33], v[162:165], v[202:205], v[30:33]
	v_mfma_f32_16x16x32_bf16 v[22:25], v[154:157], v[210:213], v[22:25]
	v_mfma_f32_16x16x32_bf16 v[14:17], v[162:165], v[210:213], v[14:17]
	s_setprio 2
	s_setprio 0
	v_mfma_f32_16x16x32_bf16 v[50:53], v[166:169], v[182:185], v[50:53]
	v_mfma_f32_16x16x32_bf16 v[42:45], v[174:177], v[182:185], v[42:45]
	v_mfma_f32_16x16x32_bf16 v[34:37], v[166:169], v[190:193], v[34:37]
	v_mfma_f32_16x16x32_bf16 v[26:29], v[174:177], v[190:193], v[26:29]
	v_mfma_f32_16x16x32_bf16 v[18:21], v[166:169], v[198:201], v[18:21]
	v_mfma_f32_16x16x32_bf16 v[10:13], v[174:177], v[198:201], v[10:13]
	v_mfma_f32_16x16x32_bf16 v[6:9], v[166:169], v[206:209], v[6:9]
	v_mfma_f32_16x16x32_bf16 v[2:5], v[174:177], v[206:209], v[2:5]
	v_mfma_f32_16x16x32_bf16 v[50:53], v[170:173], v[186:189], v[50:53]
	v_mfma_f32_16x16x32_bf16 v[42:45], v[178:181], v[186:189], v[42:45]
	v_mfma_f32_16x16x32_bf16 v[34:37], v[170:173], v[194:197], v[34:37]
	v_mfma_f32_16x16x32_bf16 v[26:29], v[178:181], v[194:197], v[26:29]
	v_mfma_f32_16x16x32_bf16 v[18:21], v[170:173], v[202:205], v[18:21]
	v_mfma_f32_16x16x32_bf16 v[10:13], v[178:181], v[202:205], v[10:13]
	v_mfma_f32_16x16x32_bf16 v[6:9], v[170:173], v[210:213], v[6:9]
	v_mfma_f32_16x16x32_bf16 v[2:5], v[178:181], v[210:213], v[2:5]
	s_setprio 2
	s_barrier
	s_add_i32 s92, s92, 2
	s_cmp_gt_u32 s92, 5
	s_mov_b64 s[46:47], s[52:53]
	s_cbranch_scc0 .LBB0_781

; #define PG8_STAGE(bufoff, gbase, voff) do { _Pragma("unroll") for (int _i = 0; _i < 2; ++_i) \
;         __builtin_amdgcn_global_load_lds((const unsigned*)((const char*)(gbase) + (voff)[_i]), (LAS unsigned*)(lds + (bufoff) + ldsw + _i * 8192), 16, 0, 0); } while (0)
; #define PG8_LDA(dst, b, h) do { _Pragma("unroll") for (int m = 0; m < 4; ++m) _Pragma("unroll") for (int k = 0; k < 2; ++k) dst[m][k] = *(const LAS bf16x8*)(lds + PG8_SA(b, h) + aoff + m * 2048 + k * 1024); } while (0)
; #define PG8_LDB(dst, b, h) do { _Pragma("unroll") for (int n = 0; n < 2; ++n) _Pragma("unroll") for (int k = 0; k < 2; ++k) dst[n][k] = *(const LAS bf16x8*)(lds + PG8_SB(b, h) + boff + n * 2048 + k * 1024); } while (0)
; #define PG8_SCHED __builtin_amdgcn_sched_barrier(0)
;     __device__ __forceinline__ bool next(int i, Unit& u) const {
;         const long L = (long)i * G + c; if (L >= nwg) return false;
;         int w = (int)L; { const int q = nwg / NXCD, r = nwg % NXCD, xcd = w % NXCD, off = w / NXCD; w = (xcd < r ? xcd * (q + 1) : r * (q + 1) + (xcd - r) * q) + off; }
;         u.pb = w / per; w -= u.pb * per;
;         const int nig = WGM * nN, gid = w / nig, fm = gid * WGM, gsz = (nM - fm) < WGM ? (nM - fm) : WGM;
;         u.pm = fm + ((w % nig) % gsz); u.pn = (w % nig) / gsz; return true;
; template <class Epi>
; __device__ __forceinline__ void gemm_phase(LAS unsigned char* lds, const Gemm g, int G, int c, const Epi& E) {
;     ...
;             PG8_LDB(B0, 0, 0); PG8_LDB(B1, 0, 1); PG8_SCHED; PG8_LDA(At, 0, 0); PG8_STAGE(PG8_SA(1, 1), a1 + hstepA, voffA);
.LBB0_1053:
	ds_read_b128 v[152:155], v148
	ds_read_b128 v[156:159], v148 offset:1024
	ds_read_b128 v[160:163], v148 offset:2048
	ds_read_b128 v[164:167], v148 offset:3072
	ds_read_b128 v[168:171], v149
	ds_read_b128 v[172:175], v149 offset:1024
	ds_read_b128 v[176:179], v149 offset:2048
	ds_read_b128 v[180:183], v149 offset:3072
	ds_read_b128 v[184:187], v150
	ds_read_b128 v[188:191], v150 offset:1024
	ds_read_b128 v[192:195], v150 offset:2048
	ds_read_b128 v[196:199], v150 offset:3072
	ds_read_b128 v[200:203], v150 offset:4096
	ds_read_b128 v[204:207], v150 offset:5120
	ds_read_b128 v[208:211], v150 offset:6144
	ds_read_b128 v[212:215], v150 offset:7168
	s_add_i32 s53, s53, 1
	s_mul_i32 s2, s53, s34
	s_mul_hi_u32 s3, s53, s27
	s_add_i32 s3, s3, s2
	s_mul_i32 s2, s53, s27
	s_add_u32 s2, s2, s26
	s_addc_u32 s3, s3, s45
	v_cmp_gt_i64_e32 vcc, s[2:3], v[144:145]
	v_cmp_lt_i64_e64 s[4:5], s[2:3], v[142:143]
	s_cbranch_vccnz .LBB0_1055
	s_ashr_i32 s3, s2, 31
	s_lshr_b32 s3, s3, 29
	s_add_i32 s3, s2, s3
	s_ashr_i32 s16, s3, 3
	s_and_b32 s3, s3, -8
	s_sub_i32 s2, s2, s3
	s_lshr_b32 s3, s2, 31
	s_or_b32 s3, s3, 0x318
	s_mul_i32 s2, s3, s2
	s_add_i32 s2, s2, s16
	s_mul_hi_i32 s3, s2, 0xa57eb503
	s_add_i32 s3, s3, s2
	s_lshr_b32 s16, s3, 31
	s_ashr_i32 s3, s3, 7
	s_add_i32 s72, s3, s16
	s_mul_i32 s3, s72, 0xffffff3a
	s_add_i32 s3, s3, s2
	s_mul_hi_i32 s2, s3, 0x2e8ba2e9
	s_lshr_b32 s16, s2, 31
	s_ashr_i32 s2, s2, 5
	s_add_i32 s2, s2, s16
	s_lshl_b32 s17, s2, 3
	s_sub_i32 s16, 9, s17
	s_min_i32 s18, s16, 8
	s_abs_i32 s16, s18
	v_cvt_f32_u32_e32 v2, s16
	s_sub_i32 s20, 0, s16
	s_mulk_i32 s2, 0xb0
	s_sub_i32 s2, s3, s2
	v_rcp_iflag_f32_e32 v2, v2
	s_abs_i32 s3, s2
	s_xor_b32 s19, s2, s18
	s_ashr_i32 s19, s19, 31
	v_mul_f32_e32 v2, 0x4f7ffffe, v2
	v_cvt_u32_f32_e32 v2, v2
	s_nop 0
	v_readfirstlane_b32 s21, v2
	s_mul_i32 s20, s20, s21
	s_mul_hi_u32 s20, s21, s20
	s_add_i32 s21, s21, s20
	s_mul_hi_u32 s20, s3, s21
	s_mul_i32 s21, s20, s16
	s_sub_i32 s3, s3, s21
	s_add_i32 s21, s20, 1
	s_sub_i32 s22, s3, s16
	s_cmp_ge_u32 s3, s16
	s_cselect_b32 s20, s21, s20
	s_cselect_b32 s3, s22, s3
	s_add_i32 s21, s20, 1
	s_cmp_ge_u32 s3, s16
	s_cselect_b32 s3, s21, s20
	s_xor_b32 s3, s3, s19
	s_sub_i32 s16, s3, s19
	s_mul_i32 s3, s16, s18
	s_sub_i32 s2, s2, s3
	s_add_i32 s18, s2, s17

; #define PG8_STAGE(bufoff, gbase, voff) do { _Pragma("unroll") for (int _i = 0; _i < 2; ++_i) \
;         __builtin_amdgcn_global_load_lds((const unsigned*)((const char*)(gbase) + (voff)[_i]), (LAS unsigned*)(lds + (bufoff) + ldsw + _i * 8192), 16, 0, 0); } while (0)
; #define PG8_LDA(dst, b, h) do { _Pragma("unroll") for (int m = 0; m < 4; ++m) _Pragma("unroll") for (int k = 0; k < 2; ++k) dst[m][k] = *(const LAS bf16x8*)(lds + PG8_SA(b, h) + aoff + m * 2048 + k * 1024); } while (0)
; #define PG8_LDB(dst, b, h) do { _Pragma("unroll") for (int n = 0; n < 2; ++n) _Pragma("unroll") for (int k = 0; k < 2; ++k) dst[n][k] = *(const LAS bf16x8*)(lds + PG8_SB(b, h) + boff + n * 2048 + k * 1024); } while (0)
; #define PG8_MMA(ai, bj, At, Bt) do { __builtin_amdgcn_s_setprio(1); _Pragma("unroll") for (int m = 0; m < 4; ++m) _Pragma("unroll") for (int n = 0; n < 2; ++n) _Pragma("unroll") for (int k = 0; k < 2; ++k) \
;         acc[ai][bj][m][n] = __builtin_amdgcn_mfma_f32_16x16x32_bf16(Bt[n][k], At[m][k], acc[ai][bj][m][n], 0, 0, 0); __builtin_amdgcn_s_setprio(0); } while (0)
; #define PG8_BAR __builtin_amdgcn_s_barrier()
; template <class Epi>
; __device__ __forceinline__ void gemm_phase(LAS unsigned char* lds, const Gemm g, int G, int c, const Epi& E) {
;     ...
;         const char* nA = has_next ? (const char*)(g.A + (size_t)nxt.pb * g.sA) + (size_t)nxt.pm * 2 * hstepA : cA;
;         const char* nB = has_next ? (const char*)(g.Bt + (size_t)nxt.pb * g.sB) + (size_t)nxt.pn * 2 * hstepB : cB;
; #pragma nounroll
;         for (int t = 0; t < nt; t += 2) {
;             const bool last = (t == nt - 2);
;             const char* a1 = cA + (size_t)(t + 1) * kstep;
;             const char* a2 = last ? nA : cA + (size_t)(t + 2) * kstep; const char* b2 = last ? nB : cB + (size_t)(t + 2) * kstep;
;             const char* a3 = a2 + kstep; const char* b3 = b2 + kstep;
;             PG8_LDB(B0, 0, 0); PG8_LDB(B1, 0, 1); PG8_SCHED; PG8_LDA(At, 0, 0); PG8_STAGE(PG8_SA(1, 1), a1 + hstepA, voffA);
;             PG8_WAIT_V(8); PG8_WAIT_L(0); PG8_BAR; PG8_MMA(0, 0, At, B0); PG8_MMA(0, 1, At, B1); PG8_BAR; PG8_SCHED;
;             PG8_LDA(At, 0, 1); PG8_STAGE(PG8_SB(0, 0), b2, voffB); PG8_STAGE(PG8_SB(0, 1), b2 + hstepB, voffB); PG8_STAGE(PG8_SA(0, 0), a2, voffA);
;             PG8_WAIT_V(8); PG8_WAIT_L(0); PG8_BAR; PG8_MMA(1, 0, At, B0); PG8_MMA(1, 1, At, B1); PG8_BAR; PG8_SCHED;
.LBB0_1057:
	s_ashr_i32 s17, s16, 31
	s_lshl_b64 s[22:23], s[16:17], 19
	s_add_u32 s22, s35, s22
	s_addc_u32 s23, s42, s23
	s_and_b64 s[4:5], s[4:5], exec
	s_cselect_b32 s17, s23, s39
	s_cselect_b32 s19, s22, s38
	s_add_u32 s4, s40, 0x40080
	s_addc_u32 s5, s41, 0
	s_add_u32 s78, s38, 0x100
	s_addc_u32 s79, s39, 0
	s_mov_b32 s80, -2
	s_add_u32 s33, s4, 0xfffc0080
	s_addc_u32 s38, s5, -1
	s_cmp_eq_u32 s80, 12
	s_cselect_b32 s41, s21, s38
	s_cselect_b32 s40, s20, s33
	s_cselect_b32 s39, s17, s79
	s_cselect_b32 s38, s19, s78
	v_lshl_add_u64 v[216:217], s[4:5], 0, v[138:139]
	s_add_i32 m0, s25, 0xc000
	global_load_lds_dwordx4 v[216:217], off
	v_lshl_add_u64 v[216:217], s[4:5], 0, v[140:141]
	s_add_i32 m0, s25, 0xe000
	s_nop 0
	global_load_lds_dwordx4 v[216:217], off
	s_waitcnt vmcnt(8)
	s_waitcnt lgkmcnt(0)
	s_barrier
	s_setprio 0
	v_mfma_f32_16x16x32_bf16 v[126:129], v[152:155], v[184:187], 0
	v_mfma_f32_16x16x32_bf16 v[122:125], v[160:163], v[184:187], 0
	v_mfma_f32_16x16x32_bf16 v[110:113], v[152:155], v[192:195], 0
	v_mfma_f32_16x16x32_bf16 v[106:109], v[160:163], v[192:195], 0
	v_mfma_f32_16x16x32_bf16 v[94:97], v[152:155], v[200:203], 0
	v_mfma_f32_16x16x32_bf16 v[90:93], v[160:163], v[200:203], 0
	v_mfma_f32_16x16x32_bf16 v[78:81], v[152:155], v[208:211], 0
	v_mfma_f32_16x16x32_bf16 v[74:77], v[160:163], v[208:211], 0
	v_mfma_f32_16x16x32_bf16 v[126:129], v[156:159], v[188:191], v[126:129]
	v_mfma_f32_16x16x32_bf16 v[122:125], v[164:167], v[188:191], v[122:125]
	v_mfma_f32_16x16x32_bf16 v[110:113], v[156:159], v[196:199], v[110:113]
	v_mfma_f32_16x16x32_bf16 v[106:109], v[164:167], v[196:199], v[106:109]
	v_mfma_f32_16x16x32_bf16 v[94:97], v[156:159], v[204:207], v[94:97]
	v_mfma_f32_16x16x32_bf16 v[90:93], v[164:167], v[204:207], v[90:93]
	v_mfma_f32_16x16x32_bf16 v[78:81], v[156:159], v[212:215], v[78:81]
	v_mfma_f32_16x16x32_bf16 v[74:77], v[164:167], v[212:215], v[74:77]
	s_setprio 2
	s_setprio 0
	v_mfma_f32_16x16x32_bf16 v[118:121], v[168:171], v[184:187], 0
	v_mfma_f32_16x16x32_bf16 v[114:117], v[176:179], v[184:187], 0
	v_mfma_f32_16x16x32_bf16 v[102:105], v[168:171], v[192:195], 0
	v_mfma_f32_16x16x32_bf16 v[98:101], v[176:179], v[192:195], 0
	v_mfma_f32_16x16x32_bf16 v[86:89], v[168:171], v[200:203], 0
	v_mfma_f32_16x16x32_bf16 v[82:85], v[176:179], v[200:203], 0
	v_mfma_f32_16x16x32_bf16 v[70:73], v[168:171], v[208:211], 0
	v_mfma_f32_16x16x32_bf16 v[66:69], v[176:179], v[208:211], 0
	v_mfma_f32_16x16x32_bf16 v[118:121], v[172:175], v[188:191], v[118:121]
	v_mfma_f32_16x16x32_bf16 v[114:117], v[180:183], v[188:191], v[114:117]
	v_mfma_f32_16x16x32_bf16 v[102:105], v[172:175], v[196:199], v[102:105]
	v_mfma_f32_16x16x32_bf16 v[98:101], v[180:183], v[196:199], v[98:101]
	v_mfma_f32_16x16x32_bf16 v[86:89], v[172:175], v[204:207], v[86:89]
	v_mfma_f32_16x16x32_bf16 v[82:85], v[180:183], v[204:207], v[82:85]
	v_mfma_f32_16x16x32_bf16 v[70:73], v[172:175], v[212:215], v[70:73]
	v_mfma_f32_16x16x32_bf16 v[66:69], v[180:183], v[212:215], v[66:69]
	s_setprio 2
	s_barrier
	s_add_i32 s33, s60, s46
	v_lshl_add_u64 v[216:217], s[38:39], 0, v[134:135]
	s_mov_b32 m0, s33
	ds_read_b128 v[184:187], v150 offset:16384
	ds_read_b128 v[188:191], v150 offset:17408
	ds_read_b128 v[192:195], v150 offset:18432
	ds_read_b128 v[196:199], v150 offset:19456
	ds_read_b128 v[200:203], v150 offset:20480
	ds_read_b128 v[204:207], v150 offset:21504
	ds_read_b128 v[208:211], v150 offset:22528
	ds_read_b128 v[212:215], v150 offset:23552
	global_load_lds_dwordx4 v[216:217], off
	s_add_i32 m0, s33, 0x2000
	s_add_u32 s62, s38, 0x40000
	v_lshl_add_u64 v[218:219], s[38:39], 0, v[130:131]
	s_addc_u32 s63, s39, 0
	s_add_i32 s33, s61, s46
	global_load_lds_dwordx4 v[218:219], off
	v_lshl_add_u64 v[220:221], s[62:63], 0, v[134:135]
	s_mov_b32 m0, s33
	v_lshl_add_u64 v[222:223], s[40:41], 0, v[132:133]
	global_load_lds_dwordx4 v[220:221], off
	v_lshl_add_u64 v[220:221], s[62:63], 0, v[130:131]
	s_add_i32 m0, s33, 0x2000
	s_nop 0
	global_load_lds_dwordx4 v[220:221], off
	v_lshl_add_u64 v[220:221], s[40:41], 0, v[136:137]
	s_mov_b32 m0, s25
	s_nop 0
	global_load_lds_dwordx4 v[220:221], off
	s_mov_b32 m0, s37
	s_nop 0
	global_load_lds_dwordx4 v[222:223], off
	s_waitcnt vmcnt(8)
	s_waitcnt lgkmcnt(0)
	s_barrier
	s_setprio 0
	v_mfma_f32_16x16x32_bf16 v[62:65], v[152:155], v[184:187], 0
	v_mfma_f32_16x16x32_bf16 v[58:61], v[160:163], v[184:187], 0
	v_mfma_f32_16x16x32_bf16 v[46:49], v[152:155], v[192:195], 0
	v_mfma_f32_16x16x32_bf16 v[42:45], v[160:163], v[192:195], 0
	v_mfma_f32_16x16x32_bf16 v[30:33], v[152:155], v[200:203], 0
	v_mfma_f32_16x16x32_bf16 v[26:29], v[160:163], v[200:203], 0
	v_mfma_f32_16x16x32_bf16 v[14:17], v[152:155], v[208:211], 0
	v_mfma_f32_16x16x32_bf16 v[10:13], v[160:163], v[208:211], 0
	v_mfma_f32_16x16x32_bf16 v[62:65], v[156:159], v[188:191], v[62:65]
	v_mfma_f32_16x16x32_bf16 v[58:61], v[164:167], v[188:191], v[58:61]
	v_mfma_f32_16x16x32_bf16 v[46:49], v[156:159], v[196:199], v[46:49]
	v_mfma_f32_16x16x32_bf16 v[42:45], v[164:167], v[196:199], v[42:45]
	v_mfma_f32_16x16x32_bf16 v[30:33], v[156:159], v[204:207], v[30:33]
	v_mfma_f32_16x16x32_bf16 v[26:29], v[164:167], v[204:207], v[26:29]
	v_mfma_f32_16x16x32_bf16 v[14:17], v[156:159], v[212:215], v[14:17]
	v_mfma_f32_16x16x32_bf16 v[10:13], v[164:167], v[212:215], v[10:13]
	s_setprio 2
	s_setprio 0
	v_mfma_f32_16x16x32_bf16 v[54:57], v[168:171], v[184:187], 0
	v_mfma_f32_16x16x32_bf16 v[50:53], v[176:179], v[184:187], 0
	v_mfma_f32_16x16x32_bf16 v[38:41], v[168:171], v[192:195], 0
	v_mfma_f32_16x16x32_bf16 v[34:37], v[176:179], v[192:195], 0
	v_mfma_f32_16x16x32_bf16 v[22:25], v[168:171], v[200:203], 0
	v_mfma_f32_16x16x32_bf16 v[18:21], v[176:179], v[200:203], 0
	v_mfma_f32_16x16x32_bf16 v[6:9], v[168:171], v[208:211], 0
	v_mfma_f32_16x16x32_bf16 v[2:5], v[176:179], v[208:211], 0
	v_mfma_f32_16x16x32_bf16 v[54:57], v[172:175], v[188:191], v[54:57]
	v_mfma_f32_16x16x32_bf16 v[50:53], v[180:183], v[188:191], v[50:53]
	v_mfma_f32_16x16x32_bf16 v[38:41], v[172:175], v[196:199], v[38:41]
	v_mfma_f32_16x16x32_bf16 v[34:37], v[180:183], v[196:199], v[34:37]
	v_mfma_f32_16x16x32_bf16 v[22:25], v[172:175], v[204:207], v[22:25]
	v_mfma_f32_16x16x32_bf16 v[18:21], v[180:183], v[204:207], v[18:21]
	v_mfma_f32_16x16x32_bf16 v[6:9], v[172:175], v[212:215], v[6:9]
	v_mfma_f32_16x16x32_bf16 v[2:5], v[180:183], v[212:215], v[2:5]
	s_setprio 2
	s_barrier
; #define PG8_STAGE(bufoff, gbase, voff) do { _Pragma("unroll") for (int _i = 0; _i < 2; ++_i) \
;         __builtin_amdgcn_global_load_lds((const unsigned*)((const char*)(gbase) + (voff)[_i]), (LAS unsigned*)(lds + (bufoff) + ldsw + _i * 8192), 16, 0, 0); } while (0)
; #define PG8_LDA(dst, b, h) do { _Pragma("unroll") for (int m = 0; m < 4; ++m) _Pragma("unroll") for (int k = 0; k < 2; ++k) dst[m][k] = *(const LAS bf16x8*)(lds + PG8_SA(b, h) + aoff + m * 2048 + k * 1024); } while (0)
; #define PG8_LDB(dst, b, h) do { _Pragma("unroll") for (int n = 0; n < 2; ++n) _Pragma("unroll") for (int k = 0; k < 2; ++k) dst[n][k] = *(const LAS bf16x8*)(lds + PG8_SB(b, h) + boff + n * 2048 + k * 1024); } while (0)
; #define PG8_MMA(ai, bj, At, Bt) do { __builtin_amdgcn_s_setprio(1); _Pragma("unroll") for (int m = 0; m < 4; ++m) _Pragma("unroll") for (int n = 0; n < 2; ++n) _Pragma("unroll") for (int k = 0; k < 2; ++k) \
;         acc[ai][bj][m][n] = __builtin_amdgcn_mfma_f32_16x16x32_bf16(Bt[n][k], At[m][k], acc[ai][bj][m][n], 0, 0, 0); __builtin_amdgcn_s_setprio(0); } while (0)
; #define PG8_WAIT_V(n) asm volatile("s_waitcnt vmcnt(" #n ")" ::: "memory")
; #define PG8_WAIT_L(n) asm volatile("s_waitcnt lgkmcnt(" #n ")" ::: "memory")
; #define PG8_BAR __builtin_amdgcn_s_barrier()
; #define PG8_SCHED __builtin_amdgcn_sched_barrier(0)
; template <class Epi>
; __device__ __forceinline__ void gemm_phase(LAS unsigned char* lds, const Gemm g, int G, int c, const Epi& E) {
;     ...
;             PG8_LDB(B0, 1, 0); PG8_LDB(B1, 1, 1); PG8_SCHED; PG8_LDA(At, 1, 0); PG8_STAGE(PG8_SA(0, 1), a2 + hstepA, voffA);
;             PG8_WAIT_V(8); PG8_WAIT_L(0); PG8_BAR; PG8_MMA(0, 0, At, B0); PG8_MMA(0, 1, At, B1); PG8_BAR; PG8_SCHED;
	s_add_i32 s33, 0, 0x18000
	s_add_i32 s62, 0, 0x1c000
	v_add_u32_e32 v164, s33, v147
	v_add_u32_e32 v180, s62, v147
	ds_read_b128 v[152:155], v164
	ds_read_b128 v[156:159], v164 offset:1024
	ds_read_b128 v[160:163], v164 offset:2048
	ds_read_b128 v[164:167], v164 offset:3072
	ds_read_b128 v[168:171], v180
	ds_read_b128 v[172:175], v180 offset:1024
	ds_read_b128 v[176:179], v180 offset:2048
	ds_read_b128 v[180:183], v180 offset:3072
	s_add_u32 s40, s40, 0x40000
	s_addc_u32 s41, s41, 0
	s_mov_b32 m0, s47
	v_lshl_add_u64 v[224:225], s[40:41], 0, v[136:137]
	ds_read_b128 v[184:187], v150 offset:32768
	ds_read_b128 v[188:191], v150 offset:33792
	ds_read_b128 v[192:195], v150 offset:34816
	ds_read_b128 v[196:199], v150 offset:35840
	ds_read_b128 v[200:203], v150 offset:36864
	ds_read_b128 v[204:207], v150 offset:37888
	ds_read_b128 v[208:211], v150 offset:38912
	ds_read_b128 v[212:215], v150 offset:39936
	global_load_lds_dwordx4 v[224:225], off
	v_lshl_add_u64 v[224:225], s[40:41], 0, v[132:133]
	s_mov_b32 m0, s52
	s_nop 0
	global_load_lds_dwordx4 v[224:225], off
	s_waitcnt vmcnt(8)
	s_waitcnt lgkmcnt(0)
	s_barrier
	s_setprio 0
	v_mfma_f32_16x16x32_bf16 v[126:129], v[152:155], v[184:187], v[126:129]
	v_mfma_f32_16x16x32_bf16 v[122:125], v[160:163], v[184:187], v[122:125]
	v_mfma_f32_16x16x32_bf16 v[110:113], v[152:155], v[192:195], v[110:113]
	v_mfma_f32_16x16x32_bf16 v[106:109], v[160:163], v[192:195], v[106:109]
	v_mfma_f32_16x16x32_bf16 v[94:97], v[152:155], v[200:203], v[94:97]
	v_mfma_f32_16x16x32_bf16 v[90:93], v[160:163], v[200:203], v[90:93]
	v_mfma_f32_16x16x32_bf16 v[78:81], v[152:155], v[208:211], v[78:81]
	v_mfma_f32_16x16x32_bf16 v[74:77], v[160:163], v[208:211], v[74:77]
	v_mfma_f32_16x16x32_bf16 v[126:129], v[156:159], v[188:191], v[126:129]
	v_mfma_f32_16x16x32_bf16 v[122:125], v[164:167], v[188:191], v[122:125]
	v_mfma_f32_16x16x32_bf16 v[110:113], v[156:159], v[196:199], v[110:113]
	v_mfma_f32_16x16x32_bf16 v[106:109], v[164:167], v[196:199], v[106:109]
	v_mfma_f32_16x16x32_bf16 v[94:97], v[156:159], v[204:207], v[94:97]
	v_mfma_f32_16x16x32_bf16 v[90:93], v[164:167], v[204:207], v[90:93]
	v_mfma_f32_16x16x32_bf16 v[78:81], v[156:159], v[212:215], v[78:81]
	v_mfma_f32_16x16x32_bf16 v[74:77], v[164:167], v[212:215], v[74:77]
	s_setprio 2
	s_setprio 0
	v_mfma_f32_16x16x32_bf16 v[118:121], v[168:171], v[184:187], v[118:121]
	v_mfma_f32_16x16x32_bf16 v[114:117], v[176:179], v[184:187], v[114:117]
	v_mfma_f32_16x16x32_bf16 v[102:105], v[168:171], v[192:195], v[102:105]
	v_mfma_f32_16x16x32_bf16 v[98:101], v[176:179], v[192:195], v[98:101]
	v_mfma_f32_16x16x32_bf16 v[86:89], v[168:171], v[200:203], v[86:89]
	v_mfma_f32_16x16x32_bf16 v[82:85], v[176:179], v[200:203], v[82:85]
	v_mfma_f32_16x16x32_bf16 v[70:73], v[168:171], v[208:211], v[70:73]
	v_mfma_f32_16x16x32_bf16 v[66:69], v[176:179], v[208:211], v[66:69]
	v_mfma_f32_16x16x32_bf16 v[118:121], v[172:175], v[188:191], v[118:121]
	v_mfma_f32_16x16x32_bf16 v[114:117], v[180:183], v[188:191], v[114:117]
	v_mfma_f32_16x16x32_bf16 v[102:105], v[172:175], v[196:199], v[102:105]
	v_mfma_f32_16x16x32_bf16 v[98:101], v[180:183], v[196:199], v[98:101]
	v_mfma_f32_16x16x32_bf16 v[86:89], v[172:175], v[204:207], v[86:89]
	v_mfma_f32_16x16x32_bf16 v[82:85], v[180:183], v[204:207], v[82:85]
	v_mfma_f32_16x16x32_bf16 v[70:73], v[172:175], v[212:215], v[70:73]
	v_mfma_f32_16x16x32_bf16 v[66:69], v[180:183], v[212:215], v[66:69]
	s_setprio 2
	s_barrier
; #define PG8_STAGE(bufoff, gbase, voff) do { _Pragma("unroll") for (int _i = 0; _i < 2; ++_i) \
;         __builtin_amdgcn_global_load_lds((const unsigned*)((const char*)(gbase) + (voff)[_i]), (LAS unsigned*)(lds + (bufoff) + ldsw + _i * 8192), 16, 0, 0); } while (0)
; #define PG8_LDA(dst, b, h) do { _Pragma("unroll") for (int m = 0; m < 4; ++m) _Pragma("unroll") for (int k = 0; k < 2; ++k) dst[m][k] = *(const LAS bf16x8*)(lds + PG8_SA(b, h) + aoff + m * 2048 + k * 1024); } while (0)
; #define PG8_MMA(ai, bj, At, Bt) do { __builtin_amdgcn_s_setprio(1); _Pragma("unroll") for (int m = 0; m < 4; ++m) _Pragma("unroll") for (int n = 0; n < 2; ++n) _Pragma("unroll") for (int k = 0; k < 2; ++k) \
;         acc[ai][bj][m][n] = __builtin_amdgcn_mfma_f32_16x16x32_bf16(Bt[n][k], At[m][k], acc[ai][bj][m][n], 0, 0, 0); __builtin_amdgcn_s_setprio(0); } while (0)
; #define PG8_WAIT_V(n) asm volatile("s_waitcnt vmcnt(" #n ")" ::: "memory")
; #define PG8_WAIT_L(n) asm volatile("s_waitcnt lgkmcnt(" #n ")" ::: "memory")
; #define PG8_BAR __builtin_amdgcn_s_barrier()
; #define PG8_SCHED __builtin_amdgcn_sched_barrier(0)
; template <class Epi>
; __device__ __forceinline__ void gemm_phase(LAS unsigned char* lds, const Gemm g, int G, int c, const Epi& E) {
;     ...
;             PG8_LDA(At, 1, 1); PG8_STAGE(PG8_SB(1, 0), b3, voffB); PG8_STAGE(PG8_SB(1, 1), b3 + hstepB, voffB); PG8_STAGE(PG8_SA(1, 0), a3, voffA);
;             PG8_WAIT_V(8); PG8_WAIT_L(0); PG8_BAR; PG8_MMA(1, 0, At, B0); PG8_MMA(1, 1, At, B1); PG8_BAR; PG8_SCHED;
;         }
	s_add_i32 s33, s33, s46
	v_lshl_add_u64 v[216:217], v[216:217], 0, s[12:13]
	s_mov_b32 m0, s33
	ds_read_b128 v[184:187], v150 offset:49152
	ds_read_b128 v[188:191], v150 offset:50176
	ds_read_b128 v[192:195], v150 offset:51200
	ds_read_b128 v[196:199], v150 offset:52224
	ds_read_b128 v[200:203], v150 offset:53248
	ds_read_b128 v[204:207], v150 offset:54272
	ds_read_b128 v[208:211], v150 offset:55296
	ds_read_b128 v[212:215], v150 offset:56320
	global_load_lds_dwordx4 v[216:217], off
	s_add_i32 m0, s33, 0x2000
	s_add_u32 s38, s38, 0x40080
	v_lshl_add_u64 v[216:217], v[218:219], 0, s[12:13]
	s_addc_u32 s39, s39, 0
	s_add_i32 s33, s62, s46
	global_load_lds_dwordx4 v[216:217], off
	v_lshl_add_u64 v[216:217], s[38:39], 0, v[134:135]
	s_mov_b32 m0, s33
	s_nop 0
	global_load_lds_dwordx4 v[216:217], off
	v_lshl_add_u64 v[216:217], s[38:39], 0, v[130:131]
	s_add_i32 m0, s33, 0x2000
	s_nop 0
	global_load_lds_dwordx4 v[216:217], off
	v_lshl_add_u64 v[216:217], v[220:221], 0, s[12:13]
	s_mov_b32 m0, s57
	s_nop 0
	global_load_lds_dwordx4 v[216:217], off
	v_lshl_add_u64 v[216:217], v[222:223], 0, s[12:13]
	s_mov_b32 m0, s58
	s_nop 0
	global_load_lds_dwordx4 v[216:217], off
	s_waitcnt vmcnt(8)
	s_waitcnt lgkmcnt(0)
	s_barrier
	s_setprio 0
	v_mfma_f32_16x16x32_bf16 v[62:65], v[152:155], v[184:187], v[62:65]
	v_mfma_f32_16x16x32_bf16 v[58:61], v[160:163], v[184:187], v[58:61]
	v_mfma_f32_16x16x32_bf16 v[46:49], v[152:155], v[192:195], v[46:49]
	v_mfma_f32_16x16x32_bf16 v[42:45], v[160:163], v[192:195], v[42:45]
	v_mfma_f32_16x16x32_bf16 v[30:33], v[152:155], v[200:203], v[30:33]
	v_mfma_f32_16x16x32_bf16 v[26:29], v[160:163], v[200:203], v[26:29]
	v_mfma_f32_16x16x32_bf16 v[14:17], v[152:155], v[208:211], v[14:17]
	v_mfma_f32_16x16x32_bf16 v[10:13], v[160:163], v[208:211], v[10:13]
	v_mfma_f32_16x16x32_bf16 v[62:65], v[156:159], v[188:191], v[62:65]
	v_mfma_f32_16x16x32_bf16 v[58:61], v[164:167], v[188:191], v[58:61]
	v_mfma_f32_16x16x32_bf16 v[46:49], v[156:159], v[196:199], v[46:49]
	v_mfma_f32_16x16x32_bf16 v[42:45], v[164:167], v[196:199], v[42:45]
	v_mfma_f32_16x16x32_bf16 v[30:33], v[156:159], v[204:207], v[30:33]
	v_mfma_f32_16x16x32_bf16 v[26:29], v[164:167], v[204:207], v[26:29]
	v_mfma_f32_16x16x32_bf16 v[14:17], v[156:159], v[212:215], v[14:17]
	v_mfma_f32_16x16x32_bf16 v[10:13], v[164:167], v[212:215], v[10:13]
	s_setprio 2
	s_setprio 0
	v_mfma_f32_16x16x32_bf16 v[54:57], v[168:171], v[184:187], v[54:57]
	v_mfma_f32_16x16x32_bf16 v[50:53], v[176:179], v[184:187], v[50:53]
	v_mfma_f32_16x16x32_bf16 v[38:41], v[168:171], v[192:195], v[38:41]
	v_mfma_f32_16x16x32_bf16 v[34:37], v[176:179], v[192:195], v[34:37]
	v_mfma_f32_16x16x32_bf16 v[22:25], v[168:171], v[200:203], v[22:25]
	v_mfma_f32_16x16x32_bf16 v[18:21], v[176:179], v[200:203], v[18:21]
	v_mfma_f32_16x16x32_bf16 v[6:9], v[168:171], v[208:211], v[6:9]
	v_mfma_f32_16x16x32_bf16 v[2:5], v[176:179], v[208:211], v[2:5]
	v_mfma_f32_16x16x32_bf16 v[54:57], v[172:175], v[188:191], v[54:57]
	v_mfma_f32_16x16x32_bf16 v[50:53], v[180:183], v[188:191], v[50:53]
	v_mfma_f32_16x16x32_bf16 v[38:41], v[172:175], v[196:199], v[38:41]
	v_mfma_f32_16x16x32_bf16 v[34:37], v[180:183], v[196:199], v[34:37]
	v_mfma_f32_16x16x32_bf16 v[22:25], v[172:175], v[204:207], v[22:25]
	v_mfma_f32_16x16x32_bf16 v[18:21], v[180:183], v[204:207], v[18:21]
	v_mfma_f32_16x16x32_bf16 v[6:9], v[172:175], v[212:215], v[6:9]
	v_mfma_f32_16x16x32_bf16 v[2:5], v[180:183], v[212:215], v[2:5]
	s_setprio 2
	s_barrier
	s_add_i32 s80, s80, 2
	s_add_u32 s4, s4, 0x100
	s_addc_u32 s5, s5, 0
	s_add_u32 s78, s78, 0x100
	s_addc_u32 s79, s79, 0
	s_cmp_gt_u32 s80, 13
	s_cbranch_scc0 .LBB0_1058

; #define PG8_STAGE(bufoff, gbase, voff) do { _Pragma("unroll") for (int _i = 0; _i < 2; ++_i) \
;         __builtin_amdgcn_global_load_lds((const unsigned*)((const char*)(gbase) + (voff)[_i]), (LAS unsigned*)(lds + (bufoff) + ldsw + _i * 8192), 16, 0, 0); } while (0)
; #define PG8_LDA(dst, b, h) do { _Pragma("unroll") for (int m = 0; m < 4; ++m) _Pragma("unroll") for (int k = 0; k < 2; ++k) dst[m][k] = *(const LAS bf16x8*)(lds + PG8_SA(b, h) + aoff + m * 2048 + k * 1024); } while (0)
; #define PG8_LDB(dst, b, h) do { _Pragma("unroll") for (int n = 0; n < 2; ++n) _Pragma("unroll") for (int k = 0; k < 2; ++k) dst[n][k] = *(const LAS bf16x8*)(lds + PG8_SB(b, h) + boff + n * 2048 + k * 1024); } while (0)
; #define PG8_SCHED __builtin_amdgcn_sched_barrier(0)
;     __device__ __forceinline__ bool next(int i, Unit& u) const {
;         const long L = (long)i * G + c; if (L >= nwg) return false;
;         int w = (int)L; { const int q = nwg / NXCD, r = nwg % NXCD, xcd = w % NXCD, off = w / NXCD; w = (xcd < r ? xcd * (q + 1) : r * (q + 1) + (xcd - r) * q) + off; }
;         u.pb = w / per; w -= u.pb * per;
;         const int nig = WGM * nN, gid = w / nig, fm = gid * WGM, gsz = (nM - fm) < WGM ? (nM - fm) : WGM;
;         u.pm = fm + ((w % nig) % gsz); u.pn = (w % nig) / gsz; return true;
; template <class Epi>
; __device__ __forceinline__ void gemm_phase(LAS unsigned char* lds, const Gemm g, int G, int c, const Epi& E) {
;     ...
;             PG8_LDB(B0, 0, 0); PG8_LDB(B1, 0, 1); PG8_SCHED; PG8_LDA(At, 0, 0); PG8_STAGE(PG8_SA(1, 1), a1 + hstepA, voffA);
.LBB0_1422:
	ds_read_b128 v[142:145], v148
	ds_read_b128 v[152:155], v148 offset:1024
	ds_read_b128 v[156:159], v148 offset:2048
	ds_read_b128 v[160:163], v148 offset:3072
	ds_read_b128 v[164:167], v149
	ds_read_b128 v[168:171], v149 offset:1024
	ds_read_b128 v[172:175], v149 offset:2048
	ds_read_b128 v[176:179], v149 offset:3072
	ds_read_b128 v[180:183], v150
	ds_read_b128 v[184:187], v150 offset:1024
	ds_read_b128 v[188:191], v150 offset:2048
	ds_read_b128 v[192:195], v150 offset:3072
	ds_read_b128 v[196:199], v150 offset:4096
	ds_read_b128 v[200:203], v150 offset:5120
	ds_read_b128 v[204:207], v150 offset:6144
	ds_read_b128 v[208:211], v150 offset:7168
	s_add_i32 s55, s55, 1
	s_mul_i32 s2, s55, s60
	s_mul_hi_u32 s3, s55, s27
	s_add_i32 s3, s3, s2
	s_mul_i32 s2, s55, s27
	s_add_u32 s2, s2, s26
	s_addc_u32 s3, s3, s61
	v_cmp_gt_i64_e32 vcc, s[2:3], v[140:141]
	v_cmp_lt_i64_e64 s[4:5], s[2:3], v[138:139]
	s_cbranch_vccnz .LBB0_1424
	s_ashr_i32 s3, s2, 31
	s_lshr_b32 s3, s3, 29
	s_add_i32 s3, s2, s3
	s_ashr_i32 s13, s3, 3
	s_and_b32 s3, s3, -8
	s_sub_i32 s2, s2, s3
	s_lshr_b32 s3, s2, 31
	s_or_b32 s3, s3, 64
	s_mul_i32 s2, s3, s2
	s_add_i32 s2, s2, s13
	s_ashr_i32 s3, s2, 31
	s_lshr_b32 s3, s3, 28
	s_add_i32 s3, s2, s3
	s_and_b32 s13, s3, -16
	s_sub_i32 s2, s2, s13
	s_ashr_i32 s13, s2, 31
	s_lshr_b32 s13, s13, 26
	s_add_i32 s13, s2, s13
	s_ashr_i32 s14, s13, 6
	s_lshl_b32 s14, s14, 3
	s_sub_i32 s15, 2, s14
	s_min_i32 s15, s15, 8
	s_abs_i32 s20, s15
	v_cvt_f32_u32_e32 v2, s20
	s_sub_i32 s21, 0, s20
	s_andn2_b32 s13, s13, 63
	s_sub_i32 s2, s2, s13
	v_rcp_iflag_f32_e32 v2, v2
	s_ashr_i32 s78, s3, 4
	s_abs_i32 s3, s2
	s_xor_b32 s13, s2, s15
	v_mul_f32_e32 v2, 0x4f7ffffe, v2
	v_cvt_u32_f32_e32 v2, v2
	s_ashr_i32 s13, s13, 31
	v_readfirstlane_b32 s22, v2
	s_mul_i32 s21, s21, s22
	s_mul_hi_u32 s21, s22, s21
	s_add_i32 s22, s22, s21
	s_mul_hi_u32 s21, s3, s22
	s_mul_i32 s22, s21, s20
	s_sub_i32 s3, s3, s22
	s_add_i32 s23, s21, 1
	s_sub_i32 s22, s3, s20
	s_cmp_ge_u32 s3, s20
	s_cselect_b32 s21, s23, s21
	s_cselect_b32 s3, s22, s3
	s_add_i32 s22, s21, 1
	s_cmp_ge_u32 s3, s20
	s_cselect_b32 s3, s22, s21
	s_xor_b32 s3, s3, s13
	s_sub_i32 s79, s3, s13
	s_mul_i32 s3, s79, s15
	s_sub_i32 s2, s2, s3
	s_add_i32 s80, s2, s14

; #define PG8_STAGE(bufoff, gbase, voff) do { _Pragma("unroll") for (int _i = 0; _i < 2; ++_i) \
;         __builtin_amdgcn_global_load_lds((const unsigned*)((const char*)(gbase) + (voff)[_i]), (LAS unsigned*)(lds + (bufoff) + ldsw + _i * 8192), 16, 0, 0); } while (0)
; #define PG8_LDA(dst, b, h) do { _Pragma("unroll") for (int m = 0; m < 4; ++m) _Pragma("unroll") for (int k = 0; k < 2; ++k) dst[m][k] = *(const LAS bf16x8*)(lds + PG8_SA(b, h) + aoff + m * 2048 + k * 1024); } while (0)
; #define PG8_LDB(dst, b, h) do { _Pragma("unroll") for (int n = 0; n < 2; ++n) _Pragma("unroll") for (int k = 0; k < 2; ++k) dst[n][k] = *(const LAS bf16x8*)(lds + PG8_SB(b, h) + boff + n * 2048 + k * 1024); } while (0)
; #define PG8_MMA(ai, bj, At, Bt) do { __builtin_amdgcn_s_setprio(1); _Pragma("unroll") for (int m = 0; m < 4; ++m) _Pragma("unroll") for (int n = 0; n < 2; ++n) _Pragma("unroll") for (int k = 0; k < 2; ++k) \
;         acc[ai][bj][m][n] = __builtin_amdgcn_mfma_f32_16x16x32_bf16(Bt[n][k], At[m][k], acc[ai][bj][m][n], 0, 0, 0); __builtin_amdgcn_s_setprio(0); } while (0)
; #define PG8_WAIT_V(n) asm volatile("s_waitcnt vmcnt(" #n ")" ::: "memory")
; #define PG8_WAIT_L(n) asm volatile("s_waitcnt lgkmcnt(" #n ")" ::: "memory")
; #define PG8_BAR __builtin_amdgcn_s_barrier()
; #define PG8_SCHED __builtin_amdgcn_sched_barrier(0)
; template <class Epi>
; __device__ __forceinline__ void gemm_phase(LAS unsigned char* lds, const Gemm g, int G, int c, const Epi& E) {
;     ...
;             const bool last = (t == nt - 2);
;             const char* a1 = cA + (size_t)(t + 1) * kstep;
;             const char* a2 = last ? nA : cA + (size_t)(t + 2) * kstep; const char* b2 = last ? nB : cB + (size_t)(t + 2) * kstep;
;             const char* a3 = a2 + kstep; const char* b3 = b2 + kstep;
;             PG8_LDB(B0, 0, 0); PG8_LDB(B1, 0, 1); PG8_SCHED; PG8_LDA(At, 0, 0); PG8_STAGE(PG8_SA(1, 1), a1 + hstepA, voffA);
;             PG8_WAIT_V(8); PG8_WAIT_L(0); PG8_BAR; PG8_MMA(0, 0, At, B0); PG8_MMA(0, 1, At, B1); PG8_BAR; PG8_SCHED;
;             PG8_LDA(At, 0, 1); PG8_STAGE(PG8_SB(0, 0), b2, voffB); PG8_STAGE(PG8_SB(0, 1), b2 + hstepB, voffB); PG8_STAGE(PG8_SA(0, 0), a2, voffA);
;             PG8_WAIT_V(8); PG8_WAIT_L(0); PG8_BAR; PG8_MMA(1, 0, At, B0); PG8_MMA(1, 1, At, B1); PG8_BAR; PG8_SCHED;
.LBB0_1428:
	s_mov_b32 s13, 0
	s_mov_b64 s[20:21], -1
	s_mov_b64 s[22:23], 0
	s_add_u32 s33, s18, s13
	s_addc_u32 s42, s19, 0
	s_add_u32 s38, s33, 0x100
	s_addc_u32 s39, s42, 0
	s_and_b64 s[24:25], s[22:23], exec
	s_cselect_b32 s39, s5, s39
	s_cselect_b32 s38, s4, s38
	s_add_u32 s13, s16, s13
	s_addc_u32 s24, s17, 0
	s_add_u32 s13, s13, 0x100
	s_addc_u32 s24, s24, 0
	s_and_b64 s[22:23], s[22:23], exec
	s_cselect_b32 s41, s15, s24
	s_cselect_b32 s40, s14, s13
	s_add_u32 s44, s33, 0xb0080
	s_addc_u32 s45, s42, 0
	s_add_i32 s65, s72, s48
	s_add_i32 m0, s49, 0xc000
	s_add_i32 s85, s49, 0xe000
	s_add_i32 s62, s65, 0x2000
	s_add_u32 s42, s40, 0xb0000
	s_addc_u32 s43, s41, 0
	s_add_i32 s64, s73, s48
	s_add_i32 s63, s64, 0x2000
	s_add_i32 s84, 0, 0x18000
	s_add_i32 s33, 0, 0x1c000
	s_add_u32 s24, s38, 0xb0000
	s_addc_u32 s25, s39, 0
	s_add_i32 s83, s84, s48
	s_add_i32 s13, s83, 0x2000
	s_add_u32 s22, s40, 0xb0080
	s_addc_u32 s23, s41, 0
	s_add_i32 s75, s33, s48
	s_add_i32 s74, s75, 0x2000
	v_lshl_add_u64 v[212:213], s[44:45], 0, v[136:137]
	global_load_lds_dwordx4 v[212:213], off
	v_lshl_add_u64 v[212:213], s[44:45], 0, v[132:133]
	s_mov_b32 m0, s85
	s_nop 0
	global_load_lds_dwordx4 v[212:213], off
	s_waitcnt vmcnt(8)
	s_waitcnt lgkmcnt(0)
	s_barrier
	s_setprio 0
	v_mfma_f32_16x16x32_bf16 v[126:129], v[142:145], v[180:183], 0
	v_mfma_f32_16x16x32_bf16 v[122:125], v[156:159], v[180:183], 0
	v_mfma_f32_16x16x32_bf16 v[118:121], v[142:145], v[188:191], 0
	v_mfma_f32_16x16x32_bf16 v[110:113], v[156:159], v[188:191], 0
	v_mfma_f32_16x16x32_bf16 v[102:105], v[142:145], v[196:199], 0
	v_mfma_f32_16x16x32_bf16 v[94:97], v[156:159], v[196:199], 0
	v_mfma_f32_16x16x32_bf16 v[86:89], v[142:145], v[204:207], 0
	v_mfma_f32_16x16x32_bf16 v[78:81], v[156:159], v[204:207], 0
	v_mfma_f32_16x16x32_bf16 v[126:129], v[152:155], v[184:187], v[126:129]
	v_mfma_f32_16x16x32_bf16 v[122:125], v[160:163], v[184:187], v[122:125]
	v_mfma_f32_16x16x32_bf16 v[118:121], v[152:155], v[192:195], v[118:121]
	v_mfma_f32_16x16x32_bf16 v[110:113], v[160:163], v[192:195], v[110:113]
	v_mfma_f32_16x16x32_bf16 v[102:105], v[152:155], v[200:203], v[102:105]
	v_mfma_f32_16x16x32_bf16 v[94:97], v[160:163], v[200:203], v[94:97]
	v_mfma_f32_16x16x32_bf16 v[86:89], v[152:155], v[208:211], v[86:89]
	v_mfma_f32_16x16x32_bf16 v[78:81], v[160:163], v[208:211], v[78:81]
	s_setprio 2
	s_setprio 0
	v_mfma_f32_16x16x32_bf16 v[114:117], v[164:167], v[180:183], 0
	v_mfma_f32_16x16x32_bf16 v[106:109], v[172:175], v[180:183], 0
	v_mfma_f32_16x16x32_bf16 v[98:101], v[164:167], v[188:191], 0
	v_mfma_f32_16x16x32_bf16 v[90:93], v[172:175], v[188:191], 0
	v_mfma_f32_16x16x32_bf16 v[82:85], v[164:167], v[196:199], 0
	v_mfma_f32_16x16x32_bf16 v[74:77], v[172:175], v[196:199], 0
	v_mfma_f32_16x16x32_bf16 v[70:73], v[164:167], v[204:207], 0
	v_mfma_f32_16x16x32_bf16 v[66:69], v[172:175], v[204:207], 0
	v_mfma_f32_16x16x32_bf16 v[114:117], v[168:171], v[184:187], v[114:117]
	v_mfma_f32_16x16x32_bf16 v[106:109], v[176:179], v[184:187], v[106:109]
	v_mfma_f32_16x16x32_bf16 v[98:101], v[168:171], v[192:195], v[98:101]
	v_mfma_f32_16x16x32_bf16 v[90:93], v[176:179], v[192:195], v[90:93]
	v_mfma_f32_16x16x32_bf16 v[82:85], v[168:171], v[200:203], v[82:85]
	v_mfma_f32_16x16x32_bf16 v[74:77], v[176:179], v[200:203], v[74:77]
	v_mfma_f32_16x16x32_bf16 v[70:73], v[168:171], v[208:211], v[70:73]
	v_mfma_f32_16x16x32_bf16 v[66:69], v[176:179], v[208:211], v[66:69]
	s_setprio 2
	s_barrier
	s_mov_b32 m0, s65
	v_lshl_add_u64 v[212:213], s[40:41], 0, v[134:135]
	ds_read_b128 v[180:183], v150 offset:16384
	ds_read_b128 v[184:187], v150 offset:17408
	ds_read_b128 v[188:191], v150 offset:18432
	ds_read_b128 v[192:195], v150 offset:19456
	ds_read_b128 v[196:199], v150 offset:20480
	ds_read_b128 v[200:203], v150 offset:21504
	ds_read_b128 v[204:207], v150 offset:22528
	ds_read_b128 v[208:211], v150 offset:23552
	global_load_lds_dwordx4 v[212:213], off
	v_lshl_add_u64 v[214:215], s[40:41], 0, v[130:131]
	s_mov_b32 m0, s62
	v_lshl_add_u64 v[216:217], s[42:43], 0, v[134:135]
	global_load_lds_dwordx4 v[214:215], off
	s_mov_b32 m0, s64
	v_lshl_add_u64 v[218:219], s[38:39], 0, v[132:133]
	global_load_lds_dwordx4 v[216:217], off
	v_lshl_add_u64 v[216:217], s[42:43], 0, v[130:131]
	s_mov_b32 m0, s63
	s_nop 0
	global_load_lds_dwordx4 v[216:217], off
	v_lshl_add_u64 v[216:217], s[38:39], 0, v[136:137]
	s_mov_b32 m0, s49
	s_nop 0
	global_load_lds_dwordx4 v[216:217], off
	s_mov_b32 m0, s52
	s_nop 0
	global_load_lds_dwordx4 v[218:219], off
	s_waitcnt vmcnt(8)
	s_waitcnt lgkmcnt(0)
	s_barrier
; #define PG8_STAGE(bufoff, gbase, voff) do { _Pragma("unroll") for (int _i = 0; _i < 2; ++_i) \
;         __builtin_amdgcn_global_load_lds((const unsigned*)((const char*)(gbase) + (voff)[_i]), (LAS unsigned*)(lds + (bufoff) + ldsw + _i * 8192), 16, 0, 0); } while (0)
; #define PG8_LDA(dst, b, h) do { _Pragma("unroll") for (int m = 0; m < 4; ++m) _Pragma("unroll") for (int k = 0; k < 2; ++k) dst[m][k] = *(const LAS bf16x8*)(lds + PG8_SA(b, h) + aoff + m * 2048 + k * 1024); } while (0)
; #define PG8_LDB(dst, b, h) do { _Pragma("unroll") for (int n = 0; n < 2; ++n) _Pragma("unroll") for (int k = 0; k < 2; ++k) dst[n][k] = *(const LAS bf16x8*)(lds + PG8_SB(b, h) + boff + n * 2048 + k * 1024); } while (0)
; #define PG8_MMA(ai, bj, At, Bt) do { __builtin_amdgcn_s_setprio(1); _Pragma("unroll") for (int m = 0; m < 4; ++m) _Pragma("unroll") for (int n = 0; n < 2; ++n) _Pragma("unroll") for (int k = 0; k < 2; ++k) \
;         acc[ai][bj][m][n] = __builtin_amdgcn_mfma_f32_16x16x32_bf16(Bt[n][k], At[m][k], acc[ai][bj][m][n], 0, 0, 0); __builtin_amdgcn_s_setprio(0); } while (0)
; #define PG8_WAIT_V(n) asm volatile("s_waitcnt vmcnt(" #n ")" ::: "memory")
; #define PG8_WAIT_L(n) asm volatile("s_waitcnt lgkmcnt(" #n ")" ::: "memory")
; #define PG8_BAR __builtin_amdgcn_s_barrier()
; #define PG8_SCHED __builtin_amdgcn_sched_barrier(0)
; template <class Epi>
; __device__ __forceinline__ void gemm_phase(LAS unsigned char* lds, const Gemm g, int G, int c, const Epi& E) {
;     ...
;             PG8_WAIT_V(8); PG8_WAIT_L(0); PG8_BAR; PG8_MMA(1, 0, At, B0); PG8_MMA(1, 1, At, B1); PG8_BAR; PG8_SCHED;
;             PG8_LDB(B0, 1, 0); PG8_LDB(B1, 1, 1); PG8_SCHED; PG8_LDA(At, 1, 0); PG8_STAGE(PG8_SA(0, 1), a2 + hstepA, voffA);
;             PG8_WAIT_V(8); PG8_WAIT_L(0); PG8_BAR; PG8_MMA(0, 0, At, B0); PG8_MMA(0, 1, At, B1); PG8_BAR; PG8_SCHED;
	s_setprio 0
	v_mfma_f32_16x16x32_bf16 v[62:65], v[142:145], v[180:183], 0
	v_mfma_f32_16x16x32_bf16 v[58:61], v[156:159], v[180:183], 0
	v_mfma_f32_16x16x32_bf16 v[54:57], v[142:145], v[188:191], 0
	v_mfma_f32_16x16x32_bf16 v[46:49], v[156:159], v[188:191], 0
	v_mfma_f32_16x16x32_bf16 v[38:41], v[142:145], v[196:199], 0
	v_mfma_f32_16x16x32_bf16 v[30:33], v[156:159], v[196:199], 0
	v_mfma_f32_16x16x32_bf16 v[22:25], v[142:145], v[204:207], 0
	v_mfma_f32_16x16x32_bf16 v[14:17], v[156:159], v[204:207], 0
	v_mfma_f32_16x16x32_bf16 v[62:65], v[152:155], v[184:187], v[62:65]
	v_mfma_f32_16x16x32_bf16 v[58:61], v[160:163], v[184:187], v[58:61]
	v_mfma_f32_16x16x32_bf16 v[54:57], v[152:155], v[192:195], v[54:57]
	v_mfma_f32_16x16x32_bf16 v[46:49], v[160:163], v[192:195], v[46:49]
	v_mfma_f32_16x16x32_bf16 v[38:41], v[152:155], v[200:203], v[38:41]
	v_mfma_f32_16x16x32_bf16 v[30:33], v[160:163], v[200:203], v[30:33]
	v_mfma_f32_16x16x32_bf16 v[22:25], v[152:155], v[208:211], v[22:25]
	v_mfma_f32_16x16x32_bf16 v[14:17], v[160:163], v[208:211], v[14:17]
	s_setprio 2
	s_setprio 0
	v_mfma_f32_16x16x32_bf16 v[50:53], v[164:167], v[180:183], 0
	v_mfma_f32_16x16x32_bf16 v[42:45], v[172:175], v[180:183], 0
	v_mfma_f32_16x16x32_bf16 v[34:37], v[164:167], v[188:191], 0
	v_mfma_f32_16x16x32_bf16 v[26:29], v[172:175], v[188:191], 0
	v_mfma_f32_16x16x32_bf16 v[18:21], v[164:167], v[196:199], 0
	v_mfma_f32_16x16x32_bf16 v[10:13], v[172:175], v[196:199], 0
	v_mfma_f32_16x16x32_bf16 v[6:9], v[164:167], v[204:207], 0
	v_mfma_f32_16x16x32_bf16 v[2:5], v[172:175], v[204:207], 0
	v_mfma_f32_16x16x32_bf16 v[50:53], v[168:171], v[184:187], v[50:53]
	v_mfma_f32_16x16x32_bf16 v[42:45], v[176:179], v[184:187], v[42:45]
	v_mfma_f32_16x16x32_bf16 v[34:37], v[168:171], v[192:195], v[34:37]
	v_mfma_f32_16x16x32_bf16 v[26:29], v[176:179], v[192:195], v[26:29]
	v_mfma_f32_16x16x32_bf16 v[18:21], v[168:171], v[200:203], v[18:21]
	v_mfma_f32_16x16x32_bf16 v[10:13], v[176:179], v[200:203], v[10:13]
	v_mfma_f32_16x16x32_bf16 v[6:9], v[168:171], v[208:211], v[6:9]
	v_mfma_f32_16x16x32_bf16 v[2:5], v[176:179], v[208:211], v[2:5]
	s_setprio 2
	s_barrier
	v_add_u32_e32 v151, s84, v147
	ds_read_b128 v[142:145], v151
	ds_read_b128 v[152:155], v151 offset:1024
	ds_read_b128 v[156:159], v151 offset:2048
	ds_read_b128 v[160:163], v151 offset:3072
	v_add_u32_e32 v151, s33, v147
	ds_read_b128 v[164:167], v151
	ds_read_b128 v[168:171], v151 offset:1024
	ds_read_b128 v[172:175], v151 offset:2048
	ds_read_b128 v[176:179], v151 offset:3072
	s_mov_b32 m0, s53
	v_lshl_add_u64 v[220:221], s[24:25], 0, v[136:137]
	ds_read_b128 v[180:183], v150 offset:32768
	ds_read_b128 v[184:187], v150 offset:33792
	ds_read_b128 v[188:191], v150 offset:34816
	ds_read_b128 v[192:195], v150 offset:35840
	ds_read_b128 v[196:199], v150 offset:36864
	ds_read_b128 v[200:203], v150 offset:37888
	ds_read_b128 v[204:207], v150 offset:38912
	ds_read_b128 v[208:211], v150 offset:39936
	global_load_lds_dwordx4 v[220:221], off
	v_lshl_add_u64 v[220:221], s[24:25], 0, v[132:133]
	s_mov_b32 m0, s54
	s_nop 0
	global_load_lds_dwordx4 v[220:221], off
	s_waitcnt vmcnt(8)
	s_waitcnt lgkmcnt(0)
	s_barrier
	s_setprio 0
	v_mfma_f32_16x16x32_bf16 v[126:129], v[142:145], v[180:183], v[126:129]
	v_mfma_f32_16x16x32_bf16 v[122:125], v[156:159], v[180:183], v[122:125]
	v_mfma_f32_16x16x32_bf16 v[118:121], v[142:145], v[188:191], v[118:121]
	v_mfma_f32_16x16x32_bf16 v[110:113], v[156:159], v[188:191], v[110:113]
	v_mfma_f32_16x16x32_bf16 v[102:105], v[142:145], v[196:199], v[102:105]
	v_mfma_f32_16x16x32_bf16 v[94:97], v[156:159], v[196:199], v[94:97]
	v_mfma_f32_16x16x32_bf16 v[86:89], v[142:145], v[204:207], v[86:89]
	v_mfma_f32_16x16x32_bf16 v[78:81], v[156:159], v[204:207], v[78:81]
	v_mfma_f32_16x16x32_bf16 v[126:129], v[152:155], v[184:187], v[126:129]
	v_mfma_f32_16x16x32_bf16 v[122:125], v[160:163], v[184:187], v[122:125]
	v_mfma_f32_16x16x32_bf16 v[118:121], v[152:155], v[192:195], v[118:121]
	v_mfma_f32_16x16x32_bf16 v[110:113], v[160:163], v[192:195], v[110:113]
	v_mfma_f32_16x16x32_bf16 v[102:105], v[152:155], v[200:203], v[102:105]
	v_mfma_f32_16x16x32_bf16 v[94:97], v[160:163], v[200:203], v[94:97]
	v_mfma_f32_16x16x32_bf16 v[86:89], v[152:155], v[208:211], v[86:89]
	v_mfma_f32_16x16x32_bf16 v[78:81], v[160:163], v[208:211], v[78:81]
	s_setprio 2
	s_setprio 0
	v_mfma_f32_16x16x32_bf16 v[114:117], v[164:167], v[180:183], v[114:117]
	v_mfma_f32_16x16x32_bf16 v[106:109], v[172:175], v[180:183], v[106:109]
	v_mfma_f32_16x16x32_bf16 v[98:101], v[164:167], v[188:191], v[98:101]
	v_mfma_f32_16x16x32_bf16 v[90:93], v[172:175], v[188:191], v[90:93]
	v_mfma_f32_16x16x32_bf16 v[82:85], v[164:167], v[196:199], v[82:85]
	v_mfma_f32_16x16x32_bf16 v[74:77], v[172:175], v[196:199], v[74:77]
	v_mfma_f32_16x16x32_bf16 v[70:73], v[164:167], v[204:207], v[70:73]
	v_mfma_f32_16x16x32_bf16 v[66:69], v[172:175], v[204:207], v[66:69]
	v_mfma_f32_16x16x32_bf16 v[114:117], v[168:171], v[184:187], v[114:117]
	v_mfma_f32_16x16x32_bf16 v[106:109], v[176:179], v[184:187], v[106:109]
	v_mfma_f32_16x16x32_bf16 v[98:101], v[168:171], v[192:195], v[98:101]
	v_mfma_f32_16x16x32_bf16 v[90:93], v[176:179], v[192:195], v[90:93]
	v_mfma_f32_16x16x32_bf16 v[82:85], v[168:171], v[200:203], v[82:85]
	v_mfma_f32_16x16x32_bf16 v[74:77], v[176:179], v[200:203], v[74:77]
	v_mfma_f32_16x16x32_bf16 v[70:73], v[168:171], v[208:211], v[70:73]
	v_mfma_f32_16x16x32_bf16 v[66:69], v[176:179], v[208:211], v[66:69]
	s_setprio 2
	s_barrier
; #define PG8_STAGE(bufoff, gbase, voff) do { _Pragma("unroll") for (int _i = 0; _i < 2; ++_i) \
;         __builtin_amdgcn_global_load_lds((const unsigned*)((const char*)(gbase) + (voff)[_i]), (LAS unsigned*)(lds + (bufoff) + ldsw + _i * 8192), 16, 0, 0); } while (0)
; #define PG8_LDA(dst, b, h) do { _Pragma("unroll") for (int m = 0; m < 4; ++m) _Pragma("unroll") for (int k = 0; k < 2; ++k) dst[m][k] = *(const LAS bf16x8*)(lds + PG8_SA(b, h) + aoff + m * 2048 + k * 1024); } while (0)
; #define PG8_MMA(ai, bj, At, Bt) do { __builtin_amdgcn_s_setprio(1); _Pragma("unroll") for (int m = 0; m < 4; ++m) _Pragma("unroll") for (int n = 0; n < 2; ++n) _Pragma("unroll") for (int k = 0; k < 2; ++k) \
;         acc[ai][bj][m][n] = __builtin_amdgcn_mfma_f32_16x16x32_bf16(Bt[n][k], At[m][k], acc[ai][bj][m][n], 0, 0, 0); __builtin_amdgcn_s_setprio(0); } while (0)
; #define PG8_WAIT_V(n) asm volatile("s_waitcnt vmcnt(" #n ")" ::: "memory")
; #define PG8_WAIT_L(n) asm volatile("s_waitcnt lgkmcnt(" #n ")" ::: "memory")
; #define PG8_BAR __builtin_amdgcn_s_barrier()
; #define PG8_SCHED __builtin_amdgcn_sched_barrier(0)
; template <class Epi>
; __device__ __forceinline__ void gemm_phase(LAS unsigned char* lds, const Gemm g, int G, int c, const Epi& E) {
;     ...
;             PG8_LDA(At, 1, 1); PG8_STAGE(PG8_SB(1, 0), b3, voffB); PG8_STAGE(PG8_SB(1, 1), b3 + hstepB, voffB); PG8_STAGE(PG8_SA(1, 0), a3, voffA);
;             PG8_WAIT_V(8); PG8_WAIT_L(0); PG8_BAR; PG8_MMA(1, 0, At, B0); PG8_MMA(1, 1, At, B1); PG8_BAR; PG8_SCHED;
;         }
	s_mov_b32 m0, s83
	v_lshl_add_u64 v[212:213], v[212:213], 0, s[8:9]
	ds_read_b128 v[180:183], v150 offset:49152
	ds_read_b128 v[184:187], v150 offset:50176
	ds_read_b128 v[188:191], v150 offset:51200
	ds_read_b128 v[192:195], v150 offset:52224
	ds_read_b128 v[196:199], v150 offset:53248
	ds_read_b128 v[200:203], v150 offset:54272
	ds_read_b128 v[204:207], v150 offset:55296
	ds_read_b128 v[208:211], v150 offset:56320
	global_load_lds_dwordx4 v[212:213], off
	v_lshl_add_u64 v[212:213], v[214:215], 0, s[8:9]
	s_mov_b32 m0, s13
	s_nop 0
	global_load_lds_dwordx4 v[212:213], off
	v_lshl_add_u64 v[212:213], s[22:23], 0, v[134:135]
	s_mov_b32 m0, s75
	s_nop 0
	global_load_lds_dwordx4 v[212:213], off
	v_lshl_add_u64 v[212:213], s[22:23], 0, v[130:131]
	s_mov_b32 m0, s74
	s_nop 0
	global_load_lds_dwordx4 v[212:213], off
	v_lshl_add_u64 v[212:213], v[216:217], 0, s[8:9]
	s_mov_b32 m0, s70
	s_nop 0
	global_load_lds_dwordx4 v[212:213], off
	v_lshl_add_u64 v[212:213], v[218:219], 0, s[8:9]
	s_mov_b32 m0, s71
	s_nop 0
	global_load_lds_dwordx4 v[212:213], off
	s_waitcnt vmcnt(8)
	s_waitcnt lgkmcnt(0)
	s_barrier
	s_setprio 0
	v_mfma_f32_16x16x32_bf16 v[62:65], v[142:145], v[180:183], v[62:65]
	v_mfma_f32_16x16x32_bf16 v[58:61], v[156:159], v[180:183], v[58:61]
	v_mfma_f32_16x16x32_bf16 v[54:57], v[142:145], v[188:191], v[54:57]
	v_mfma_f32_16x16x32_bf16 v[46:49], v[156:159], v[188:191], v[46:49]
	v_mfma_f32_16x16x32_bf16 v[38:41], v[142:145], v[196:199], v[38:41]
	v_mfma_f32_16x16x32_bf16 v[30:33], v[156:159], v[196:199], v[30:33]
	v_mfma_f32_16x16x32_bf16 v[22:25], v[142:145], v[204:207], v[22:25]
	v_mfma_f32_16x16x32_bf16 v[14:17], v[156:159], v[204:207], v[14:17]
	v_mfma_f32_16x16x32_bf16 v[62:65], v[152:155], v[184:187], v[62:65]
	v_mfma_f32_16x16x32_bf16 v[58:61], v[160:163], v[184:187], v[58:61]
	v_mfma_f32_16x16x32_bf16 v[54:57], v[152:155], v[192:195], v[54:57]
	v_mfma_f32_16x16x32_bf16 v[46:49], v[160:163], v[192:195], v[46:49]
	v_mfma_f32_16x16x32_bf16 v[38:41], v[152:155], v[200:203], v[38:41]
	v_mfma_f32_16x16x32_bf16 v[30:33], v[160:163], v[200:203], v[30:33]
	v_mfma_f32_16x16x32_bf16 v[22:25], v[152:155], v[208:211], v[22:25]
	v_mfma_f32_16x16x32_bf16 v[14:17], v[160:163], v[208:211], v[14:17]
	s_setprio 2
	s_setprio 0
	v_mfma_f32_16x16x32_bf16 v[50:53], v[164:167], v[180:183], v[50:53]
	v_mfma_f32_16x16x32_bf16 v[42:45], v[172:175], v[180:183], v[42:45]
	v_mfma_f32_16x16x32_bf16 v[34:37], v[164:167], v[188:191], v[34:37]
	v_mfma_f32_16x16x32_bf16 v[26:29], v[172:175], v[188:191], v[26:29]
	v_mfma_f32_16x16x32_bf16 v[18:21], v[164:167], v[196:199], v[18:21]
	v_mfma_f32_16x16x32_bf16 v[10:13], v[172:175], v[196:199], v[10:13]
	v_mfma_f32_16x16x32_bf16 v[6:9], v[164:167], v[204:207], v[6:9]
	v_mfma_f32_16x16x32_bf16 v[2:5], v[172:175], v[204:207], v[2:5]
	v_mfma_f32_16x16x32_bf16 v[50:53], v[168:171], v[184:187], v[50:53]
	v_mfma_f32_16x16x32_bf16 v[42:45], v[176:179], v[184:187], v[42:45]
	v_mfma_f32_16x16x32_bf16 v[34:37], v[168:171], v[192:195], v[34:37]
	v_mfma_f32_16x16x32_bf16 v[26:29], v[176:179], v[192:195], v[26:29]
	v_mfma_f32_16x16x32_bf16 v[18:21], v[168:171], v[200:203], v[18:21]
	v_mfma_f32_16x16x32_bf16 v[10:13], v[176:179], v[200:203], v[10:13]
	v_mfma_f32_16x16x32_bf16 v[6:9], v[168:171], v[208:211], v[6:9]
	v_mfma_f32_16x16x32_bf16 v[2:5], v[176:179], v[208:211], v[2:5]
	s_setprio 2
	s_barrier
	s_movk_i32 s13, 0x100
	s_andn2_b64 vcc, exec, s[20:21]
	s_mov_b64 s[22:23], -1
	s_mov_b64 s[20:21], 0
	s_cbranch_vccz .LBB0_1429

; #define PG8_STAGE(bufoff, gbase, voff) do { _Pragma("unroll") for (int _i = 0; _i < 2; ++_i) \
;         __builtin_amdgcn_global_load_lds((const unsigned*)((const char*)(gbase) + (voff)[_i]), (LAS unsigned*)(lds + (bufoff) + ldsw + _i * 8192), 16, 0, 0); } while (0)
; #define PG8_LDA(dst, b, h) do { _Pragma("unroll") for (int m = 0; m < 4; ++m) _Pragma("unroll") for (int k = 0; k < 2; ++k) dst[m][k] = *(const LAS bf16x8*)(lds + PG8_SA(b, h) + aoff + m * 2048 + k * 1024); } while (0)
; #define PG8_LDB(dst, b, h) do { _Pragma("unroll") for (int n = 0; n < 2; ++n) _Pragma("unroll") for (int k = 0; k < 2; ++k) dst[n][k] = *(const LAS bf16x8*)(lds + PG8_SB(b, h) + boff + n * 2048 + k * 1024); } while (0)
; #define PG8_WAIT_V(n) asm volatile("s_waitcnt vmcnt(" #n ")" ::: "memory")
;     __device__ __forceinline__ bool next(int i, Unit& u) const {
;         const long L = (long)i * G + c; if (L >= nwg) return false;
;         int w = (int)L; { const int q = nwg / NXCD, r = nwg % NXCD, xcd = w % NXCD, off = w / NXCD; w = (xcd < r ? xcd * (q + 1) : r * (q + 1) + (xcd - r) * q) + off; }
;         u.pb = w / per; w -= u.pb * per;
;         const int nig = WGM * nN, gid = w / nig, fm = gid * WGM, gsz = (nM - fm) < WGM ? (nM - fm) : WGM;
;         u.pm = fm + ((w % nig) % gsz); u.pn = (w % nig) / gsz; return true;
;     }
; template <class Epi>
; __device__ __forceinline__ void gemm_phase(LAS unsigned char* lds, const Gemm g, int G, int c, const Epi& E) {
;     ...
;         const bool has_next = S.next(ui + 1, nxt);
;         const char* nA = has_next ? (const char*)(g.A + (size_t)nxt.pb * g.sA) + (size_t)nxt.pm * 2 * hstepA : cA;
;         const char* nB = has_next ? (const char*)(g.Bt + (size_t)nxt.pb * g.sB) + (size_t)nxt.pn * 2 * hstepB : cB;
; #pragma nounroll
;         for (int t = 0; t < nt; t += 2) {
;             const bool last = (t == nt - 2);
;             const char* a1 = cA + (size_t)(t + 1) * kstep;
;             const char* a2 = last ? nA : cA + (size_t)(t + 2) * kstep; const char* b2 = last ? nB : cB + (size_t)(t + 2) * kstep;
;             const char* a3 = a2 + kstep; const char* b3 = b2 + kstep;
;             PG8_LDB(B0, 0, 0); PG8_LDB(B1, 0, 1); PG8_SCHED; PG8_LDA(At, 0, 0); PG8_STAGE(PG8_SA(1, 1), a1 + hstepA, voffA);
;             PG8_WAIT_V(8); PG8_WAIT_L(0); PG8_BAR; PG8_MMA(0, 0, At, B0); PG8_MMA(0, 1, At, B1); PG8_BAR; PG8_SCHED;
.LBB0_1822:
	ds_read_b128 v[146:149], v152
	ds_read_b128 v[156:159], v152 offset:1024
	ds_read_b128 v[160:163], v152 offset:2048
	ds_read_b128 v[164:167], v152 offset:3072
	ds_read_b128 v[168:171], v153
	ds_read_b128 v[172:175], v153 offset:1024
	ds_read_b128 v[176:179], v153 offset:2048
	ds_read_b128 v[180:183], v153 offset:3072
	ds_read_b128 v[184:187], v154
	ds_read_b128 v[188:191], v154 offset:1024
	ds_read_b128 v[192:195], v154 offset:2048
	ds_read_b128 v[196:199], v154 offset:3072
	ds_read_b128 v[200:203], v154 offset:4096
	ds_read_b128 v[204:207], v154 offset:5120
	ds_read_b128 v[208:211], v154 offset:6144
	ds_read_b128 v[212:215], v154 offset:7168
	s_add_i32 s54, s54, 1
	s_mul_i32 s2, s54, s56
	s_mul_hi_u32 s3, s54, s27
	s_add_i32 s3, s3, s2
	s_mul_i32 s2, s54, s27
	s_add_u32 s18, s2, s26
	s_addc_u32 s19, s3, s55
	v_cmp_gt_i64_e32 vcc, s[18:19], v[144:145]
	v_cmp_lt_i64_e64 s[2:3], s[18:19], v[142:143]
	s_cbranch_vccnz .LBB0_1824
	s_ashr_i32 s10, s18, 31
	s_lshr_b32 s10, s10, 29
	s_add_i32 s10, s18, s10
	s_ashr_i32 s11, s10, 3
	s_and_b32 s10, s10, -8
	s_sub_i32 s10, s18, s10
	s_lshr_b32 s12, s10, 31
	s_or_b32 s12, s12, 32
	s_mul_i32 s10, s12, s10
	s_add_i32 s10, s10, s11
	s_ashr_i32 s11, s10, 31
	s_lshr_b32 s11, s11, 29
	s_add_i32 s11, s10, s11
	s_and_b32 s12, s11, -8
	s_sub_i32 s12, s10, s12
	s_ashr_i32 s10, s12, 31
	s_lshr_b32 s10, s10, 29
	s_add_i32 s10, s12, s10
	s_and_b32 s13, s10, -8
	s_sub_i32 s10, 8, s13
	s_min_i32 s14, s10, 8
	s_abs_i32 s15, s14
	v_cvt_f32_u32_e32 v2, s15
	s_sub_i32 s19, 0, s15
	s_ashr_i32 s10, s11, 3
	s_sub_i32 s11, s12, s13
	v_rcp_iflag_f32_e32 v2, v2
	s_abs_i32 s12, s11
	s_xor_b32 s18, s11, s14
	s_ashr_i32 s18, s18, 31
	v_mul_f32_e32 v2, 0x4f7ffffe, v2
	v_cvt_u32_f32_e32 v2, v2
	s_nop 0
	v_readfirstlane_b32 s24, v2
	s_mul_i32 s19, s19, s24
	s_mul_hi_u32 s19, s24, s19
	s_add_i32 s24, s24, s19
	s_mul_hi_u32 s19, s12, s24
	s_mul_i32 s24, s19, s15
	s_sub_i32 s12, s12, s24
	s_add_i32 s25, s19, 1
	s_sub_i32 s24, s12, s15
	s_cmp_ge_u32 s12, s15
	s_cselect_b32 s19, s25, s19
	s_cselect_b32 s12, s24, s12
	s_add_i32 s24, s19, 1
	s_cmp_ge_u32 s12, s15
	s_cselect_b32 s12, s24, s19
	s_xor_b32 s12, s12, s18
	s_sub_i32 s12, s12, s18
	s_mul_i32 s14, s12, s14
	s_sub_i32 s11, s11, s14
	s_add_i32 s14, s11, s13
.LBB0_1824:
	s_ashr_i32 s15, s14, 31
	s_lshl_b64 s[18:19], s[14:15], 21
	s_add_u32 s18, s34, s18
	s_addc_u32 s19, s35, s19
	s_and_b64 s[24:25], s[2:3], exec
	s_cselect_b32 s15, s19, s41
	s_cselect_b32 s63, s18, s40
	s_ashr_i32 s11, s10, 31
	s_lshl_b64 s[24:25], s[10:11], 21
	s_add_u32 s11, s46, s24
	s_addc_u32 s33, s47, s25
	s_ashr_i32 s13, s12, 31
	s_lshl_b64 s[24:25], s[12:13], 21
	s_add_u32 s24, s11, s24
	s_addc_u32 s25, s33, s25
	s_and_b64 s[44:45], s[2:3], exec
	s_cselect_b32 s11, s25, s43
	s_cselect_b32 s13, s24, s42
	s_add_u32 s40, s40, 0x100080
	s_addc_u32 s41, s41, 0
	s_add_u32 s66, s42, 0x100
	s_addc_u32 s67, s43, 0
	s_mov_b32 s68, -2
	s_add_u32 s33, s40, 0xfff00080
	s_addc_u32 s42, s41, -1
	s_cmp_eq_u32 s68, 60
	s_cselect_b32 s45, s15, s42
	s_cselect_b32 s44, s63, s33
	s_cselect_b32 s43, s11, s67
	s_cselect_b32 s42, s13, s66
	v_lshl_add_u64 v[216:217], s[40:41], 0, v[138:139]
	s_add_i32 m0, s17, 0xc000
	global_load_lds_dwordx4 v[216:217], off
	v_lshl_add_u64 v[216:217], s[40:41], 0, v[140:141]
	s_add_i32 m0, s17, 0xe000
	s_nop 0
	global_load_lds_dwordx4 v[216:217], off
	s_waitcnt vmcnt(8)
	s_waitcnt lgkmcnt(0)
	s_barrier
	s_setprio 0
	v_mfma_f32_16x16x32_bf16 v[126:129], v[146:149], v[184:187], 0
	v_mfma_f32_16x16x32_bf16 v[122:125], v[160:163], v[184:187], 0
	v_mfma_f32_16x16x32_bf16 v[118:121], v[146:149], v[192:195], 0
	v_mfma_f32_16x16x32_bf16 v[110:113], v[160:163], v[192:195], 0
	v_mfma_f32_16x16x32_bf16 v[102:105], v[146:149], v[200:203], 0
	v_mfma_f32_16x16x32_bf16 v[94:97], v[160:163], v[200:203], 0
	v_mfma_f32_16x16x32_bf16 v[86:89], v[146:149], v[208:211], 0
	v_mfma_f32_16x16x32_bf16 v[78:81], v[160:163], v[208:211], 0
	v_mfma_f32_16x16x32_bf16 v[126:129], v[156:159], v[188:191], v[126:129]
	v_mfma_f32_16x16x32_bf16 v[122:125], v[164:167], v[188:191], v[122:125]
	v_mfma_f32_16x16x32_bf16 v[118:121], v[156:159], v[196:199], v[118:121]
	v_mfma_f32_16x16x32_bf16 v[110:113], v[164:167], v[196:199], v[110:113]
	v_mfma_f32_16x16x32_bf16 v[102:105], v[156:159], v[204:207], v[102:105]
	v_mfma_f32_16x16x32_bf16 v[94:97], v[164:167], v[204:207], v[94:97]
	v_mfma_f32_16x16x32_bf16 v[86:89], v[156:159], v[212:215], v[86:89]
	v_mfma_f32_16x16x32_bf16 v[78:81], v[164:167], v[212:215], v[78:81]
	s_setprio 2
	s_setprio 0
	v_mfma_f32_16x16x32_bf16 v[114:117], v[168:171], v[184:187], 0
	v_mfma_f32_16x16x32_bf16 v[106:109], v[176:179], v[184:187], 0
	v_mfma_f32_16x16x32_bf16 v[98:101], v[168:171], v[192:195], 0
	v_mfma_f32_16x16x32_bf16 v[90:93], v[176:179], v[192:195], 0
	v_mfma_f32_16x16x32_bf16 v[82:85], v[168:171], v[200:203], 0
	v_mfma_f32_16x16x32_bf16 v[74:77], v[176:179], v[200:203], 0
	v_mfma_f32_16x16x32_bf16 v[70:73], v[168:171], v[208:211], 0
	v_mfma_f32_16x16x32_bf16 v[66:69], v[176:179], v[208:211], 0
	v_mfma_f32_16x16x32_bf16 v[114:117], v[172:175], v[188:191], v[114:117]
	v_mfma_f32_16x16x32_bf16 v[106:109], v[180:183], v[188:191], v[106:109]
	v_mfma_f32_16x16x32_bf16 v[98:101], v[172:175], v[196:199], v[98:101]
	v_mfma_f32_16x16x32_bf16 v[90:93], v[180:183], v[196:199], v[90:93]
	v_mfma_f32_16x16x32_bf16 v[82:85], v[172:175], v[204:207], v[82:85]
	v_mfma_f32_16x16x32_bf16 v[74:77], v[180:183], v[204:207], v[74:77]
	v_mfma_f32_16x16x32_bf16 v[70:73], v[172:175], v[212:215], v[70:73]
	v_mfma_f32_16x16x32_bf16 v[66:69], v[180:183], v[212:215], v[66:69]
	s_setprio 2
	s_barrier
; #define PG8_STAGE(bufoff, gbase, voff) do { _Pragma("unroll") for (int _i = 0; _i < 2; ++_i) \
;         __builtin_amdgcn_global_load_lds((const unsigned*)((const char*)(gbase) + (voff)[_i]), (LAS unsigned*)(lds + (bufoff) + ldsw + _i * 8192), 16, 0, 0); } while (0)
; #define PG8_LDA(dst, b, h) do { _Pragma("unroll") for (int m = 0; m < 4; ++m) _Pragma("unroll") for (int k = 0; k < 2; ++k) dst[m][k] = *(const LAS bf16x8*)(lds + PG8_SA(b, h) + aoff + m * 2048 + k * 1024); } while (0)
; #define PG8_LDB(dst, b, h) do { _Pragma("unroll") for (int n = 0; n < 2; ++n) _Pragma("unroll") for (int k = 0; k < 2; ++k) dst[n][k] = *(const LAS bf16x8*)(lds + PG8_SB(b, h) + boff + n * 2048 + k * 1024); } while (0)
; #define PG8_MMA(ai, bj, At, Bt) do { __builtin_amdgcn_s_setprio(1); _Pragma("unroll") for (int m = 0; m < 4; ++m) _Pragma("unroll") for (int n = 0; n < 2; ++n) _Pragma("unroll") for (int k = 0; k < 2; ++k) \
;         acc[ai][bj][m][n] = __builtin_amdgcn_mfma_f32_16x16x32_bf16(Bt[n][k], At[m][k], acc[ai][bj][m][n], 0, 0, 0); __builtin_amdgcn_s_setprio(0); } while (0)
; #define PG8_WAIT_V(n) asm volatile("s_waitcnt vmcnt(" #n ")" ::: "memory")
; #define PG8_WAIT_L(n) asm volatile("s_waitcnt lgkmcnt(" #n ")" ::: "memory")
; #define PG8_BAR __builtin_amdgcn_s_barrier()
; #define PG8_SCHED __builtin_amdgcn_sched_barrier(0)
; template <class Epi>
; __device__ __forceinline__ void gemm_phase(LAS unsigned char* lds, const Gemm g, int G, int c, const Epi& E) {
;     ...
;             PG8_LDA(At, 0, 1); PG8_STAGE(PG8_SB(0, 0), b2, voffB); PG8_STAGE(PG8_SB(0, 1), b2 + hstepB, voffB); PG8_STAGE(PG8_SA(0, 0), a2, voffA);
;             PG8_WAIT_V(8); PG8_WAIT_L(0); PG8_BAR; PG8_MMA(1, 0, At, B0); PG8_MMA(1, 1, At, B1); PG8_BAR; PG8_SCHED;
;             PG8_LDB(B0, 1, 0); PG8_LDB(B1, 1, 1); PG8_SCHED; PG8_LDA(At, 1, 0); PG8_STAGE(PG8_SA(0, 1), a2 + hstepA, voffA);
;             PG8_WAIT_V(8); PG8_WAIT_L(0); PG8_BAR; PG8_MMA(0, 0, At, B0); PG8_MMA(0, 1, At, B1); PG8_BAR; PG8_SCHED;
	s_add_i32 s33, s61, s52
	v_lshl_add_u64 v[216:217], s[42:43], 0, v[134:135]
	s_mov_b32 m0, s33
	ds_read_b128 v[184:187], v154 offset:16384
	ds_read_b128 v[188:191], v154 offset:17408
	ds_read_b128 v[192:195], v154 offset:18432
	ds_read_b128 v[196:199], v154 offset:19456
	ds_read_b128 v[200:203], v154 offset:20480
	ds_read_b128 v[204:207], v154 offset:21504
	ds_read_b128 v[208:211], v154 offset:22528
	ds_read_b128 v[212:215], v154 offset:23552
	global_load_lds_dwordx4 v[216:217], off
	s_add_i32 m0, s33, 0x2000
	s_add_u32 s64, s42, 0x100000
	v_lshl_add_u64 v[218:219], s[42:43], 0, v[130:131]
	s_addc_u32 s65, s43, 0
	s_add_i32 s33, s62, s52
	global_load_lds_dwordx4 v[218:219], off
	v_lshl_add_u64 v[220:221], s[64:65], 0, v[134:135]
	s_mov_b32 m0, s33
	v_lshl_add_u64 v[222:223], s[44:45], 0, v[132:133]
	global_load_lds_dwordx4 v[220:221], off
	v_lshl_add_u64 v[220:221], s[64:65], 0, v[130:131]
	s_add_i32 m0, s33, 0x2000
	s_nop 0
	global_load_lds_dwordx4 v[220:221], off
	v_lshl_add_u64 v[220:221], s[44:45], 0, v[136:137]
	s_mov_b32 m0, s17
	s_nop 0
	global_load_lds_dwordx4 v[220:221], off
	s_mov_b32 m0, s37
	s_nop 0
	global_load_lds_dwordx4 v[222:223], off
	s_waitcnt vmcnt(8)
	s_waitcnt lgkmcnt(0)
	s_barrier
	s_setprio 0
	v_mfma_f32_16x16x32_bf16 v[62:65], v[146:149], v[184:187], 0
	v_mfma_f32_16x16x32_bf16 v[58:61], v[160:163], v[184:187], 0
	v_mfma_f32_16x16x32_bf16 v[54:57], v[146:149], v[192:195], 0
	v_mfma_f32_16x16x32_bf16 v[46:49], v[160:163], v[192:195], 0
	v_mfma_f32_16x16x32_bf16 v[38:41], v[146:149], v[200:203], 0
	v_mfma_f32_16x16x32_bf16 v[30:33], v[160:163], v[200:203], 0
	v_mfma_f32_16x16x32_bf16 v[22:25], v[146:149], v[208:211], 0
	v_mfma_f32_16x16x32_bf16 v[14:17], v[160:163], v[208:211], 0
	v_mfma_f32_16x16x32_bf16 v[62:65], v[156:159], v[188:191], v[62:65]
	v_mfma_f32_16x16x32_bf16 v[58:61], v[164:167], v[188:191], v[58:61]
	v_mfma_f32_16x16x32_bf16 v[54:57], v[156:159], v[196:199], v[54:57]
	v_mfma_f32_16x16x32_bf16 v[46:49], v[164:167], v[196:199], v[46:49]
	v_mfma_f32_16x16x32_bf16 v[38:41], v[156:159], v[204:207], v[38:41]
	v_mfma_f32_16x16x32_bf16 v[30:33], v[164:167], v[204:207], v[30:33]
	v_mfma_f32_16x16x32_bf16 v[22:25], v[156:159], v[212:215], v[22:25]
	v_mfma_f32_16x16x32_bf16 v[14:17], v[164:167], v[212:215], v[14:17]
	s_setprio 2
	s_setprio 0
	v_mfma_f32_16x16x32_bf16 v[50:53], v[168:171], v[184:187], 0
	v_mfma_f32_16x16x32_bf16 v[42:45], v[176:179], v[184:187], 0
	v_mfma_f32_16x16x32_bf16 v[34:37], v[168:171], v[192:195], 0
	v_mfma_f32_16x16x32_bf16 v[26:29], v[176:179], v[192:195], 0
	v_mfma_f32_16x16x32_bf16 v[18:21], v[168:171], v[200:203], 0
	v_mfma_f32_16x16x32_bf16 v[10:13], v[176:179], v[200:203], 0
	v_mfma_f32_16x16x32_bf16 v[6:9], v[168:171], v[208:211], 0
	v_mfma_f32_16x16x32_bf16 v[2:5], v[176:179], v[208:211], 0
	v_mfma_f32_16x16x32_bf16 v[50:53], v[172:175], v[188:191], v[50:53]
	v_mfma_f32_16x16x32_bf16 v[42:45], v[180:183], v[188:191], v[42:45]
	v_mfma_f32_16x16x32_bf16 v[34:37], v[172:175], v[196:199], v[34:37]
	v_mfma_f32_16x16x32_bf16 v[26:29], v[180:183], v[196:199], v[26:29]
	v_mfma_f32_16x16x32_bf16 v[18:21], v[172:175], v[204:207], v[18:21]
	v_mfma_f32_16x16x32_bf16 v[10:13], v[180:183], v[204:207], v[10:13]
	v_mfma_f32_16x16x32_bf16 v[6:9], v[172:175], v[212:215], v[6:9]
	v_mfma_f32_16x16x32_bf16 v[2:5], v[180:183], v[212:215], v[2:5]
	s_setprio 2
	s_barrier
	s_add_i32 s33, 0, 0x18000
	v_add_u32_e32 v155, s33, v151
	s_add_i32 s64, 0, 0x1c000
	ds_read_b128 v[146:149], v155
	ds_read_b128 v[156:159], v155 offset:1024
	ds_read_b128 v[160:163], v155 offset:2048
	ds_read_b128 v[164:167], v155 offset:3072
	v_add_u32_e32 v155, s64, v151
	ds_read_b128 v[168:171], v155
	ds_read_b128 v[172:175], v155 offset:1024
	ds_read_b128 v[176:179], v155 offset:2048
	ds_read_b128 v[180:183], v155 offset:3072
	s_add_u32 s44, s44, 0x100000
	s_addc_u32 s45, s45, 0
	s_mov_b32 m0, s39
	v_lshl_add_u64 v[226:227], s[44:45], 0, v[136:137]
	ds_read_b128 v[184:187], v154 offset:32768
	ds_read_b128 v[188:191], v154 offset:33792
	ds_read_b128 v[192:195], v154 offset:34816
	ds_read_b128 v[196:199], v154 offset:35840
	ds_read_b128 v[200:203], v154 offset:36864
	ds_read_b128 v[204:207], v154 offset:37888
	ds_read_b128 v[208:211], v154 offset:38912
	ds_read_b128 v[212:215], v154 offset:39936
	global_load_lds_dwordx4 v[226:227], off
	v_lshl_add_u64 v[226:227], s[44:45], 0, v[132:133]
	s_mov_b32 m0, s53
	s_nop 0
	global_load_lds_dwordx4 v[226:227], off
	s_waitcnt vmcnt(8)
	s_waitcnt lgkmcnt(0)
	s_barrier
; #define PG8_STAGE(bufoff, gbase, voff) do { _Pragma("unroll") for (int _i = 0; _i < 2; ++_i) \
;         __builtin_amdgcn_global_load_lds((const unsigned*)((const char*)(gbase) + (voff)[_i]), (LAS unsigned*)(lds + (bufoff) + ldsw + _i * 8192), 16, 0, 0); } while (0)
; #define PG8_LDA(dst, b, h) do { _Pragma("unroll") for (int m = 0; m < 4; ++m) _Pragma("unroll") for (int k = 0; k < 2; ++k) dst[m][k] = *(const LAS bf16x8*)(lds + PG8_SA(b, h) + aoff + m * 2048 + k * 1024); } while (0)
; #define PG8_MMA(ai, bj, At, Bt) do { __builtin_amdgcn_s_setprio(1); _Pragma("unroll") for (int m = 0; m < 4; ++m) _Pragma("unroll") for (int n = 0; n < 2; ++n) _Pragma("unroll") for (int k = 0; k < 2; ++k) \
;         acc[ai][bj][m][n] = __builtin_amdgcn_mfma_f32_16x16x32_bf16(Bt[n][k], At[m][k], acc[ai][bj][m][n], 0, 0, 0); __builtin_amdgcn_s_setprio(0); } while (0)
; #define PG8_WAIT_V(n) asm volatile("s_waitcnt vmcnt(" #n ")" ::: "memory")
; #define PG8_WAIT_L(n) asm volatile("s_waitcnt lgkmcnt(" #n ")" ::: "memory")
; #define PG8_BAR __builtin_amdgcn_s_barrier()
; #define PG8_SCHED __builtin_amdgcn_sched_barrier(0)
; template <class Epi>
; __device__ __forceinline__ void gemm_phase(LAS unsigned char* lds, const Gemm g, int G, int c, const Epi& E) {
;     ...
;             PG8_WAIT_V(8); PG8_WAIT_L(0); PG8_BAR; PG8_MMA(0, 0, At, B0); PG8_MMA(0, 1, At, B1); PG8_BAR; PG8_SCHED;
;             PG8_LDA(At, 1, 1); PG8_STAGE(PG8_SB(1, 0), b3, voffB); PG8_STAGE(PG8_SB(1, 1), b3 + hstepB, voffB); PG8_STAGE(PG8_SA(1, 0), a3, voffA);
;             PG8_WAIT_V(8); PG8_WAIT_L(0); PG8_BAR; PG8_MMA(1, 0, At, B0); PG8_MMA(1, 1, At, B1); PG8_BAR; PG8_SCHED;
;         }
	s_setprio 0
	v_mfma_f32_16x16x32_bf16 v[126:129], v[146:149], v[184:187], v[126:129]
	v_mfma_f32_16x16x32_bf16 v[122:125], v[160:163], v[184:187], v[122:125]
	v_mfma_f32_16x16x32_bf16 v[118:121], v[146:149], v[192:195], v[118:121]
	v_mfma_f32_16x16x32_bf16 v[110:113], v[160:163], v[192:195], v[110:113]
	v_mfma_f32_16x16x32_bf16 v[102:105], v[146:149], v[200:203], v[102:105]
	v_mfma_f32_16x16x32_bf16 v[94:97], v[160:163], v[200:203], v[94:97]
	v_mfma_f32_16x16x32_bf16 v[86:89], v[146:149], v[208:211], v[86:89]
	v_mfma_f32_16x16x32_bf16 v[78:81], v[160:163], v[208:211], v[78:81]
	v_mfma_f32_16x16x32_bf16 v[126:129], v[156:159], v[188:191], v[126:129]
	v_mfma_f32_16x16x32_bf16 v[122:125], v[164:167], v[188:191], v[122:125]
	v_mfma_f32_16x16x32_bf16 v[118:121], v[156:159], v[196:199], v[118:121]
	v_mfma_f32_16x16x32_bf16 v[110:113], v[164:167], v[196:199], v[110:113]
	v_mfma_f32_16x16x32_bf16 v[102:105], v[156:159], v[204:207], v[102:105]
	v_mfma_f32_16x16x32_bf16 v[94:97], v[164:167], v[204:207], v[94:97]
	v_mfma_f32_16x16x32_bf16 v[86:89], v[156:159], v[212:215], v[86:89]
	v_mfma_f32_16x16x32_bf16 v[78:81], v[164:167], v[212:215], v[78:81]
	s_setprio 2
	s_setprio 0
	v_mfma_f32_16x16x32_bf16 v[114:117], v[168:171], v[184:187], v[114:117]
	v_mfma_f32_16x16x32_bf16 v[106:109], v[176:179], v[184:187], v[106:109]
	v_mfma_f32_16x16x32_bf16 v[98:101], v[168:171], v[192:195], v[98:101]
	v_mfma_f32_16x16x32_bf16 v[90:93], v[176:179], v[192:195], v[90:93]
	v_mfma_f32_16x16x32_bf16 v[82:85], v[168:171], v[200:203], v[82:85]
	v_mfma_f32_16x16x32_bf16 v[74:77], v[176:179], v[200:203], v[74:77]
	v_mfma_f32_16x16x32_bf16 v[70:73], v[168:171], v[208:211], v[70:73]
	v_mfma_f32_16x16x32_bf16 v[66:69], v[176:179], v[208:211], v[66:69]
	v_mfma_f32_16x16x32_bf16 v[114:117], v[172:175], v[188:191], v[114:117]
	v_mfma_f32_16x16x32_bf16 v[106:109], v[180:183], v[188:191], v[106:109]
	v_mfma_f32_16x16x32_bf16 v[98:101], v[172:175], v[196:199], v[98:101]
	v_mfma_f32_16x16x32_bf16 v[90:93], v[180:183], v[196:199], v[90:93]
	v_mfma_f32_16x16x32_bf16 v[82:85], v[172:175], v[204:207], v[82:85]
	v_mfma_f32_16x16x32_bf16 v[74:77], v[180:183], v[204:207], v[74:77]
	v_mfma_f32_16x16x32_bf16 v[70:73], v[172:175], v[212:215], v[70:73]
	v_mfma_f32_16x16x32_bf16 v[66:69], v[180:183], v[212:215], v[66:69]
	s_setprio 2
	s_barrier
	s_add_i32 s33, s33, s52
	v_lshl_add_u64 v[216:217], v[216:217], 0, s[6:7]
	s_mov_b32 m0, s33
	ds_read_b128 v[184:187], v154 offset:49152
	ds_read_b128 v[188:191], v154 offset:50176
	ds_read_b128 v[192:195], v154 offset:51200
	ds_read_b128 v[196:199], v154 offset:52224
	ds_read_b128 v[200:203], v154 offset:53248
	ds_read_b128 v[204:207], v154 offset:54272
	ds_read_b128 v[208:211], v154 offset:55296
	ds_read_b128 v[212:215], v154 offset:56320
	global_load_lds_dwordx4 v[216:217], off
	s_add_i32 m0, s33, 0x2000
	s_add_u32 s42, s42, 0x100080
	v_lshl_add_u64 v[216:217], v[218:219], 0, s[6:7]
	s_addc_u32 s43, s43, 0
	s_add_i32 s33, s64, s52
	global_load_lds_dwordx4 v[216:217], off
	v_lshl_add_u64 v[216:217], s[42:43], 0, v[134:135]
	s_mov_b32 m0, s33
	s_nop 0
	global_load_lds_dwordx4 v[216:217], off
	v_lshl_add_u64 v[216:217], s[42:43], 0, v[130:131]
	s_add_i32 m0, s33, 0x2000
	s_nop 0
	global_load_lds_dwordx4 v[216:217], off
	v_lshl_add_u64 v[216:217], v[220:221], 0, s[6:7]
	s_mov_b32 m0, s59
	s_nop 0
	global_load_lds_dwordx4 v[216:217], off
	v_lshl_add_u64 v[216:217], v[222:223], 0, s[6:7]
	s_mov_b32 m0, s60
	s_nop 0
	global_load_lds_dwordx4 v[216:217], off
	s_waitcnt vmcnt(8)
	s_waitcnt lgkmcnt(0)
	s_barrier
	s_setprio 0
	v_mfma_f32_16x16x32_bf16 v[62:65], v[146:149], v[184:187], v[62:65]
	v_mfma_f32_16x16x32_bf16 v[58:61], v[160:163], v[184:187], v[58:61]
	v_mfma_f32_16x16x32_bf16 v[54:57], v[146:149], v[192:195], v[54:57]
	v_mfma_f32_16x16x32_bf16 v[46:49], v[160:163], v[192:195], v[46:49]
	v_mfma_f32_16x16x32_bf16 v[38:41], v[146:149], v[200:203], v[38:41]
	v_mfma_f32_16x16x32_bf16 v[30:33], v[160:163], v[200:203], v[30:33]
	v_mfma_f32_16x16x32_bf16 v[22:25], v[146:149], v[208:211], v[22:25]
	v_mfma_f32_16x16x32_bf16 v[14:17], v[160:163], v[208:211], v[14:17]
	v_mfma_f32_16x16x32_bf16 v[62:65], v[156:159], v[188:191], v[62:65]
	v_mfma_f32_16x16x32_bf16 v[58:61], v[164:167], v[188:191], v[58:61]
	v_mfma_f32_16x16x32_bf16 v[54:57], v[156:159], v[196:199], v[54:57]
	v_mfma_f32_16x16x32_bf16 v[46:49], v[164:167], v[196:199], v[46:49]
	v_mfma_f32_16x16x32_bf16 v[38:41], v[156:159], v[204:207], v[38:41]
	v_mfma_f32_16x16x32_bf16 v[30:33], v[164:167], v[204:207], v[30:33]
	v_mfma_f32_16x16x32_bf16 v[22:25], v[156:159], v[212:215], v[22:25]
	v_mfma_f32_16x16x32_bf16 v[14:17], v[164:167], v[212:215], v[14:17]
	s_setprio 2
	s_setprio 0
	v_mfma_f32_16x16x32_bf16 v[50:53], v[168:171], v[184:187], v[50:53]
	v_mfma_f32_16x16x32_bf16 v[42:45], v[176:179], v[184:187], v[42:45]
	v_mfma_f32_16x16x32_bf16 v[34:37], v[168:171], v[192:195], v[34:37]
	v_mfma_f32_16x16x32_bf16 v[26:29], v[176:179], v[192:195], v[26:29]
	v_mfma_f32_16x16x32_bf16 v[18:21], v[168:171], v[200:203], v[18:21]
	v_mfma_f32_16x16x32_bf16 v[10:13], v[176:179], v[200:203], v[10:13]
	v_mfma_f32_16x16x32_bf16 v[6:9], v[168:171], v[208:211], v[6:9]
	v_mfma_f32_16x16x32_bf16 v[2:5], v[176:179], v[208:211], v[2:5]
	v_mfma_f32_16x16x32_bf16 v[50:53], v[172:175], v[188:191], v[50:53]
	v_mfma_f32_16x16x32_bf16 v[42:45], v[180:183], v[188:191], v[42:45]
	v_mfma_f32_16x16x32_bf16 v[34:37], v[172:175], v[196:199], v[34:37]
	v_mfma_f32_16x16x32_bf16 v[26:29], v[180:183], v[196:199], v[26:29]
	v_mfma_f32_16x16x32_bf16 v[18:21], v[172:175], v[204:207], v[18:21]
	v_mfma_f32_16x16x32_bf16 v[10:13], v[180:183], v[204:207], v[10:13]
	v_mfma_f32_16x16x32_bf16 v[6:9], v[172:175], v[212:215], v[6:9]
	v_mfma_f32_16x16x32_bf16 v[2:5], v[180:183], v[212:215], v[2:5]
	s_setprio 2
	s_barrier
	s_add_i32 s68, s68, 2
	s_add_u32 s40, s40, 0x100
	s_addc_u32 s41, s41, 0
	s_add_u32 s66, s66, 0x100
	s_addc_u32 s67, s67, 0
	s_cmp_gt_u32 s68, 61
	s_cbranch_scc0 .LBB0_1825

; #define PG8_STAGE(bufoff, gbase, voff) do { _Pragma("unroll") for (int _i = 0; _i < 2; ++_i) \
;         __builtin_amdgcn_global_load_lds((const unsigned*)((const char*)(gbase) + (voff)[_i]), (LAS unsigned*)(lds + (bufoff) + ldsw + _i * 8192), 16, 0, 0); } while (0)
; #define PG8_LDA(dst, b, h) do { _Pragma("unroll") for (int m = 0; m < 4; ++m) _Pragma("unroll") for (int k = 0; k < 2; ++k) dst[m][k] = *(const LAS bf16x8*)(lds + PG8_SA(b, h) + aoff + m * 2048 + k * 1024); } while (0)
; #define PG8_LDB(dst, b, h) do { _Pragma("unroll") for (int n = 0; n < 2; ++n) _Pragma("unroll") for (int k = 0; k < 2; ++k) dst[n][k] = *(const LAS bf16x8*)(lds + PG8_SB(b, h) + boff + n * 2048 + k * 1024); } while (0)
; #define PG8_SCHED __builtin_amdgcn_sched_barrier(0)
;     __device__ __forceinline__ bool next(int i, Unit& u) const {
;         const long L = (long)i * G + c; if (L >= nwg) return false;
;         int w = (int)L; { const int q = nwg / NXCD, r = nwg % NXCD, xcd = w % NXCD, off = w / NXCD; w = (xcd < r ? xcd * (q + 1) : r * (q + 1) + (xcd - r) * q) + off; }
;         u.pb = w / per; w -= u.pb * per;
;         const int nig = WGM * nN, gid = w / nig, fm = gid * WGM, gsz = (nM - fm) < WGM ? (nM - fm) : WGM;
;         u.pm = fm + ((w % nig) % gsz); u.pn = (w % nig) / gsz; return true;
;     }
; template <class Epi>
; __device__ __forceinline__ void gemm_phase(LAS unsigned char* lds, const Gemm g, int G, int c, const Epi& E) {
;     ...
;             PG8_LDB(B0, 0, 0); PG8_LDB(B1, 0, 1); PG8_SCHED; PG8_LDA(At, 0, 0); PG8_STAGE(PG8_SA(1, 1), a1 + hstepA, voffA);
.LBB0_2079:
	ds_read_b128 v[152:155], v148
	ds_read_b128 v[156:159], v148 offset:1024
	ds_read_b128 v[160:163], v148 offset:2048
	ds_read_b128 v[164:167], v148 offset:3072
	ds_read_b128 v[168:171], v149
	ds_read_b128 v[172:175], v149 offset:1024
	ds_read_b128 v[176:179], v149 offset:2048
	ds_read_b128 v[180:183], v149 offset:3072
	ds_read_b128 v[184:187], v150
	ds_read_b128 v[188:191], v150 offset:1024
	ds_read_b128 v[192:195], v150 offset:2048
	ds_read_b128 v[196:199], v150 offset:3072
	ds_read_b128 v[200:203], v150 offset:4096
	ds_read_b128 v[204:207], v150 offset:5120
	ds_read_b128 v[208:211], v150 offset:6144
	ds_read_b128 v[212:215], v150 offset:7168
	s_add_i32 s49, s49, 1
	s_mul_i32 s2, s49, s34
	s_mul_hi_u32 s3, s49, s27
	s_add_i32 s3, s3, s2
	s_mul_i32 s2, s49, s27
	s_add_u32 s2, s2, s26
	s_addc_u32 s3, s3, s45
	v_cmp_gt_i64_e32 vcc, s[2:3], v[144:145]
	v_cmp_lt_i64_e64 s[4:5], s[2:3], v[142:143]
	s_cbranch_vccnz .LBB0_2081
	s_ashr_i32 s3, s2, 31
	s_lshr_b32 s3, s3, 29
	s_add_i32 s3, s2, s3
	s_ashr_i32 s16, s3, 3
	s_and_b32 s3, s3, -8
	s_sub_i32 s2, s2, s3
	s_lshr_b32 s3, s2, 31
	s_or_b32 s3, s3, 0x2c0
	s_mul_i32 s2, s3, s2
	s_add_i32 s2, s2, s16
	s_mul_hi_i32 s3, s2, 0x2e8ba2e9
	s_lshr_b32 s16, s3, 31
	s_ashr_i32 s3, s3, 5
	s_add_i32 s64, s3, s16
	s_mul_i32 s3, s64, 0xffffff50
	s_add_i32 s3, s3, s2
	s_mul_hi_i32 s2, s3, 0x2e8ba2e9
	s_lshr_b32 s16, s2, 31
	s_ashr_i32 s2, s2, 5
	s_add_i32 s2, s2, s16
	s_lshl_b32 s17, s2, 3
	s_sub_i32 s16, 8, s17
	s_min_i32 s18, s16, 8
	s_abs_i32 s16, s18
	v_cvt_f32_u32_e32 v2, s16
	s_sub_i32 s20, 0, s16
	s_mulk_i32 s2, 0xb0
	s_sub_i32 s2, s3, s2
	v_rcp_iflag_f32_e32 v2, v2
	s_abs_i32 s3, s2
	s_xor_b32 s19, s2, s18
	s_ashr_i32 s19, s19, 31
	v_mul_f32_e32 v2, 0x4f7ffffe, v2
	v_cvt_u32_f32_e32 v2, v2
	s_nop 0
	v_readfirstlane_b32 s21, v2
	s_mul_i32 s20, s20, s21
	s_mul_hi_u32 s20, s21, s20
	s_add_i32 s21, s21, s20
	s_mul_hi_u32 s20, s3, s21
	s_mul_i32 s21, s20, s16
	s_sub_i32 s3, s3, s21
	s_add_i32 s21, s20, 1
	s_sub_i32 s22, s3, s16
	s_cmp_ge_u32 s3, s16
	s_cselect_b32 s20, s21, s20
	s_cselect_b32 s3, s22, s3
	s_add_i32 s21, s20, 1
	s_cmp_ge_u32 s3, s16
	s_cselect_b32 s3, s21, s20
	s_xor_b32 s3, s3, s19
	s_sub_i32 s16, s3, s19
	s_mul_i32 s3, s16, s18
	s_sub_i32 s2, s2, s3
	s_add_i32 s18, s2, s17

; #define PG8_STAGE(bufoff, gbase, voff) do { _Pragma("unroll") for (int _i = 0; _i < 2; ++_i) \
;         __builtin_amdgcn_global_load_lds((const unsigned*)((const char*)(gbase) + (voff)[_i]), (LAS unsigned*)(lds + (bufoff) + ldsw + _i * 8192), 16, 0, 0); } while (0)
; #define PG8_LDA(dst, b, h) do { _Pragma("unroll") for (int m = 0; m < 4; ++m) _Pragma("unroll") for (int k = 0; k < 2; ++k) dst[m][k] = *(const LAS bf16x8*)(lds + PG8_SA(b, h) + aoff + m * 2048 + k * 1024); } while (0)
; #define PG8_LDB(dst, b, h) do { _Pragma("unroll") for (int n = 0; n < 2; ++n) _Pragma("unroll") for (int k = 0; k < 2; ++k) dst[n][k] = *(const LAS bf16x8*)(lds + PG8_SB(b, h) + boff + n * 2048 + k * 1024); } while (0)
; #define PG8_MMA(ai, bj, At, Bt) do { __builtin_amdgcn_s_setprio(1); _Pragma("unroll") for (int m = 0; m < 4; ++m) _Pragma("unroll") for (int n = 0; n < 2; ++n) _Pragma("unroll") for (int k = 0; k < 2; ++k) \
;         acc[ai][bj][m][n] = __builtin_amdgcn_mfma_f32_16x16x32_bf16(Bt[n][k], At[m][k], acc[ai][bj][m][n], 0, 0, 0); __builtin_amdgcn_s_setprio(0); } while (0)
; #define PG8_BAR __builtin_amdgcn_s_barrier()
; template <class Epi>
; __device__ __forceinline__ void gemm_phase(LAS unsigned char* lds, const Gemm g, int G, int c, const Epi& E) {
;     ...
;         const char* nA = has_next ? (const char*)(g.A + (size_t)nxt.pb * g.sA) + (size_t)nxt.pm * 2 * hstepA : cA;
;         const char* nB = has_next ? (const char*)(g.Bt + (size_t)nxt.pb * g.sB) + (size_t)nxt.pn * 2 * hstepB : cB;
; #pragma nounroll
;         for (int t = 0; t < nt; t += 2) {
;             const bool last = (t == nt - 2);
;             const char* a1 = cA + (size_t)(t + 1) * kstep;
;             const char* a2 = last ? nA : cA + (size_t)(t + 2) * kstep; const char* b2 = last ? nB : cB + (size_t)(t + 2) * kstep;
;             const char* a3 = a2 + kstep; const char* b3 = b2 + kstep;
;             PG8_LDB(B0, 0, 0); PG8_LDB(B1, 0, 1); PG8_SCHED; PG8_LDA(At, 0, 0); PG8_STAGE(PG8_SA(1, 1), a1 + hstepA, voffA);
;             PG8_WAIT_V(8); PG8_WAIT_L(0); PG8_BAR; PG8_MMA(0, 0, At, B0); PG8_MMA(0, 1, At, B1); PG8_BAR; PG8_SCHED;
;             PG8_LDA(At, 0, 1); PG8_STAGE(PG8_SB(0, 0), b2, voffB); PG8_STAGE(PG8_SB(0, 1), b2 + hstepB, voffB); PG8_STAGE(PG8_SA(0, 0), a2, voffA);
;             PG8_WAIT_V(8); PG8_WAIT_L(0); PG8_BAR; PG8_MMA(1, 0, At, B0); PG8_MMA(1, 1, At, B1); PG8_BAR; PG8_SCHED;
.LBB0_2083:
	s_ashr_i32 s17, s16, 31
	s_lshl_b64 s[22:23], s[16:17], 19
	s_add_u32 s22, s43, s22
	s_addc_u32 s23, s44, s23
	s_and_b64 s[4:5], s[4:5], exec
	s_cselect_b32 s17, s23, s39
	s_cselect_b32 s19, s22, s38
	s_add_u32 s4, s40, 0x40080
	s_addc_u32 s5, s41, 0
	s_add_u32 s66, s38, 0x100
	s_addc_u32 s67, s39, 0
	s_mov_b32 s68, -2
	s_add_u32 s33, s4, 0xfffc0080
	s_addc_u32 s38, s5, -1
	s_cmp_eq_u32 s68, 12
	s_cselect_b32 s41, s21, s38
	s_cselect_b32 s40, s20, s33
	s_cselect_b32 s39, s17, s67
	s_cselect_b32 s38, s19, s66
	v_lshl_add_u64 v[216:217], s[4:5], 0, v[138:139]
	s_add_i32 m0, s25, 0xc000
	global_load_lds_dwordx4 v[216:217], off
	v_lshl_add_u64 v[216:217], s[4:5], 0, v[140:141]
	s_add_i32 m0, s25, 0xe000
	s_nop 0
	global_load_lds_dwordx4 v[216:217], off
	s_waitcnt vmcnt(8)
	s_waitcnt lgkmcnt(0)
	s_barrier
	s_setprio 0
	v_mfma_f32_16x16x32_bf16 v[126:129], v[152:155], v[184:187], 0
	v_mfma_f32_16x16x32_bf16 v[122:125], v[160:163], v[184:187], 0
	v_mfma_f32_16x16x32_bf16 v[110:113], v[152:155], v[192:195], 0
	v_mfma_f32_16x16x32_bf16 v[106:109], v[160:163], v[192:195], 0
	v_mfma_f32_16x16x32_bf16 v[94:97], v[152:155], v[200:203], 0
	v_mfma_f32_16x16x32_bf16 v[90:93], v[160:163], v[200:203], 0
	v_mfma_f32_16x16x32_bf16 v[78:81], v[152:155], v[208:211], 0
	v_mfma_f32_16x16x32_bf16 v[74:77], v[160:163], v[208:211], 0
	v_mfma_f32_16x16x32_bf16 v[126:129], v[156:159], v[188:191], v[126:129]
	v_mfma_f32_16x16x32_bf16 v[122:125], v[164:167], v[188:191], v[122:125]
	v_mfma_f32_16x16x32_bf16 v[110:113], v[156:159], v[196:199], v[110:113]
	v_mfma_f32_16x16x32_bf16 v[106:109], v[164:167], v[196:199], v[106:109]
	v_mfma_f32_16x16x32_bf16 v[94:97], v[156:159], v[204:207], v[94:97]
	v_mfma_f32_16x16x32_bf16 v[90:93], v[164:167], v[204:207], v[90:93]
	v_mfma_f32_16x16x32_bf16 v[78:81], v[156:159], v[212:215], v[78:81]
	v_mfma_f32_16x16x32_bf16 v[74:77], v[164:167], v[212:215], v[74:77]
	s_setprio 2
	s_setprio 0
	v_mfma_f32_16x16x32_bf16 v[118:121], v[168:171], v[184:187], 0
	v_mfma_f32_16x16x32_bf16 v[114:117], v[176:179], v[184:187], 0
	v_mfma_f32_16x16x32_bf16 v[102:105], v[168:171], v[192:195], 0
	v_mfma_f32_16x16x32_bf16 v[98:101], v[176:179], v[192:195], 0
	v_mfma_f32_16x16x32_bf16 v[86:89], v[168:171], v[200:203], 0
	v_mfma_f32_16x16x32_bf16 v[82:85], v[176:179], v[200:203], 0
	v_mfma_f32_16x16x32_bf16 v[70:73], v[168:171], v[208:211], 0
	v_mfma_f32_16x16x32_bf16 v[66:69], v[176:179], v[208:211], 0
	v_mfma_f32_16x16x32_bf16 v[118:121], v[172:175], v[188:191], v[118:121]
	v_mfma_f32_16x16x32_bf16 v[114:117], v[180:183], v[188:191], v[114:117]
	v_mfma_f32_16x16x32_bf16 v[102:105], v[172:175], v[196:199], v[102:105]
	v_mfma_f32_16x16x32_bf16 v[98:101], v[180:183], v[196:199], v[98:101]
	v_mfma_f32_16x16x32_bf16 v[86:89], v[172:175], v[204:207], v[86:89]
	v_mfma_f32_16x16x32_bf16 v[82:85], v[180:183], v[204:207], v[82:85]
	v_mfma_f32_16x16x32_bf16 v[70:73], v[172:175], v[212:215], v[70:73]
	v_mfma_f32_16x16x32_bf16 v[66:69], v[180:183], v[212:215], v[66:69]
	s_setprio 2
	s_barrier
	s_add_i32 s33, s56, s46
	v_lshl_add_u64 v[216:217], s[38:39], 0, v[134:135]
	s_mov_b32 m0, s33
	ds_read_b128 v[184:187], v150 offset:16384
	ds_read_b128 v[188:191], v150 offset:17408
	ds_read_b128 v[192:195], v150 offset:18432
	ds_read_b128 v[196:199], v150 offset:19456
	ds_read_b128 v[200:203], v150 offset:20480
	ds_read_b128 v[204:207], v150 offset:21504
	ds_read_b128 v[208:211], v150 offset:22528
	ds_read_b128 v[212:215], v150 offset:23552
	global_load_lds_dwordx4 v[216:217], off
	s_add_i32 m0, s33, 0x2000
	s_add_u32 s70, s38, 0x40000
	v_lshl_add_u64 v[218:219], s[38:39], 0, v[130:131]
	s_addc_u32 s71, s39, 0
	s_add_i32 s33, s57, s46
	global_load_lds_dwordx4 v[218:219], off
	v_lshl_add_u64 v[220:221], s[70:71], 0, v[134:135]
	s_mov_b32 m0, s33
	v_lshl_add_u64 v[222:223], s[40:41], 0, v[132:133]
	global_load_lds_dwordx4 v[220:221], off
	v_lshl_add_u64 v[220:221], s[70:71], 0, v[130:131]
	s_add_i32 m0, s33, 0x2000
	s_nop 0
	global_load_lds_dwordx4 v[220:221], off
	v_lshl_add_u64 v[220:221], s[40:41], 0, v[136:137]
	s_mov_b32 m0, s25
	s_nop 0
	global_load_lds_dwordx4 v[220:221], off
	s_mov_b32 m0, s37
	s_nop 0
	global_load_lds_dwordx4 v[222:223], off
	s_waitcnt vmcnt(8)
	s_waitcnt lgkmcnt(0)
	s_barrier
	s_setprio 0
	v_mfma_f32_16x16x32_bf16 v[62:65], v[152:155], v[184:187], 0
	v_mfma_f32_16x16x32_bf16 v[58:61], v[160:163], v[184:187], 0
	v_mfma_f32_16x16x32_bf16 v[46:49], v[152:155], v[192:195], 0
	v_mfma_f32_16x16x32_bf16 v[42:45], v[160:163], v[192:195], 0
	v_mfma_f32_16x16x32_bf16 v[30:33], v[152:155], v[200:203], 0
	v_mfma_f32_16x16x32_bf16 v[26:29], v[160:163], v[200:203], 0
	v_mfma_f32_16x16x32_bf16 v[14:17], v[152:155], v[208:211], 0
	v_mfma_f32_16x16x32_bf16 v[10:13], v[160:163], v[208:211], 0
	v_mfma_f32_16x16x32_bf16 v[62:65], v[156:159], v[188:191], v[62:65]
	v_mfma_f32_16x16x32_bf16 v[58:61], v[164:167], v[188:191], v[58:61]
	v_mfma_f32_16x16x32_bf16 v[46:49], v[156:159], v[196:199], v[46:49]
	v_mfma_f32_16x16x32_bf16 v[42:45], v[164:167], v[196:199], v[42:45]
	v_mfma_f32_16x16x32_bf16 v[30:33], v[156:159], v[204:207], v[30:33]
	v_mfma_f32_16x16x32_bf16 v[26:29], v[164:167], v[204:207], v[26:29]
	v_mfma_f32_16x16x32_bf16 v[14:17], v[156:159], v[212:215], v[14:17]
	v_mfma_f32_16x16x32_bf16 v[10:13], v[164:167], v[212:215], v[10:13]
	s_setprio 2
	s_setprio 0
	v_mfma_f32_16x16x32_bf16 v[54:57], v[168:171], v[184:187], 0
	v_mfma_f32_16x16x32_bf16 v[50:53], v[176:179], v[184:187], 0
	v_mfma_f32_16x16x32_bf16 v[38:41], v[168:171], v[192:195], 0
	v_mfma_f32_16x16x32_bf16 v[34:37], v[176:179], v[192:195], 0
	v_mfma_f32_16x16x32_bf16 v[22:25], v[168:171], v[200:203], 0
	v_mfma_f32_16x16x32_bf16 v[18:21], v[176:179], v[200:203], 0
	v_mfma_f32_16x16x32_bf16 v[6:9], v[168:171], v[208:211], 0
	v_mfma_f32_16x16x32_bf16 v[2:5], v[176:179], v[208:211], 0
	v_mfma_f32_16x16x32_bf16 v[54:57], v[172:175], v[188:191], v[54:57]
	v_mfma_f32_16x16x32_bf16 v[50:53], v[180:183], v[188:191], v[50:53]
	v_mfma_f32_16x16x32_bf16 v[38:41], v[172:175], v[196:199], v[38:41]
	v_mfma_f32_16x16x32_bf16 v[34:37], v[180:183], v[196:199], v[34:37]
	v_mfma_f32_16x16x32_bf16 v[22:25], v[172:175], v[204:207], v[22:25]
	v_mfma_f32_16x16x32_bf16 v[18:21], v[180:183], v[204:207], v[18:21]
	v_mfma_f32_16x16x32_bf16 v[6:9], v[172:175], v[212:215], v[6:9]
	v_mfma_f32_16x16x32_bf16 v[2:5], v[180:183], v[212:215], v[2:5]
	s_setprio 2
	s_barrier
; #define PG8_STAGE(bufoff, gbase, voff) do { _Pragma("unroll") for (int _i = 0; _i < 2; ++_i) \
;         __builtin_amdgcn_global_load_lds((const unsigned*)((const char*)(gbase) + (voff)[_i]), (LAS unsigned*)(lds + (bufoff) + ldsw + _i * 8192), 16, 0, 0); } while (0)
; #define PG8_LDA(dst, b, h) do { _Pragma("unroll") for (int m = 0; m < 4; ++m) _Pragma("unroll") for (int k = 0; k < 2; ++k) dst[m][k] = *(const LAS bf16x8*)(lds + PG8_SA(b, h) + aoff + m * 2048 + k * 1024); } while (0)
; #define PG8_LDB(dst, b, h) do { _Pragma("unroll") for (int n = 0; n < 2; ++n) _Pragma("unroll") for (int k = 0; k < 2; ++k) dst[n][k] = *(const LAS bf16x8*)(lds + PG8_SB(b, h) + boff + n * 2048 + k * 1024); } while (0)
; #define PG8_MMA(ai, bj, At, Bt) do { __builtin_amdgcn_s_setprio(1); _Pragma("unroll") for (int m = 0; m < 4; ++m) _Pragma("unroll") for (int n = 0; n < 2; ++n) _Pragma("unroll") for (int k = 0; k < 2; ++k) \
;         acc[ai][bj][m][n] = __builtin_amdgcn_mfma_f32_16x16x32_bf16(Bt[n][k], At[m][k], acc[ai][bj][m][n], 0, 0, 0); __builtin_amdgcn_s_setprio(0); } while (0)
; #define PG8_WAIT_V(n) asm volatile("s_waitcnt vmcnt(" #n ")" ::: "memory")
; #define PG8_WAIT_L(n) asm volatile("s_waitcnt lgkmcnt(" #n ")" ::: "memory")
; #define PG8_BAR __builtin_amdgcn_s_barrier()
; #define PG8_SCHED __builtin_amdgcn_sched_barrier(0)
; template <class Epi>
; __device__ __forceinline__ void gemm_phase(LAS unsigned char* lds, const Gemm g, int G, int c, const Epi& E) {
;     ...
;             PG8_LDB(B0, 1, 0); PG8_LDB(B1, 1, 1); PG8_SCHED; PG8_LDA(At, 1, 0); PG8_STAGE(PG8_SA(0, 1), a2 + hstepA, voffA);
;             PG8_WAIT_V(8); PG8_WAIT_L(0); PG8_BAR; PG8_MMA(0, 0, At, B0); PG8_MMA(0, 1, At, B1); PG8_BAR; PG8_SCHED;
	s_add_i32 s33, 0, 0x18000
	s_add_i32 s69, 0, 0x1c000
	v_add_u32_e32 v164, s33, v147
	v_add_u32_e32 v180, s69, v147
	ds_read_b128 v[152:155], v164
	ds_read_b128 v[156:159], v164 offset:1024
	ds_read_b128 v[160:163], v164 offset:2048
	ds_read_b128 v[164:167], v164 offset:3072
	ds_read_b128 v[168:171], v180
	ds_read_b128 v[172:175], v180 offset:1024
	ds_read_b128 v[176:179], v180 offset:2048
	ds_read_b128 v[180:183], v180 offset:3072
	s_add_u32 s40, s40, 0x40000
	s_addc_u32 s41, s41, 0
	s_mov_b32 m0, s47
	v_lshl_add_u64 v[224:225], s[40:41], 0, v[136:137]
	ds_read_b128 v[184:187], v150 offset:32768
	ds_read_b128 v[188:191], v150 offset:33792
	ds_read_b128 v[192:195], v150 offset:34816
	ds_read_b128 v[196:199], v150 offset:35840
	ds_read_b128 v[200:203], v150 offset:36864
	ds_read_b128 v[204:207], v150 offset:37888
	ds_read_b128 v[208:211], v150 offset:38912
	ds_read_b128 v[212:215], v150 offset:39936
	global_load_lds_dwordx4 v[224:225], off
	v_lshl_add_u64 v[224:225], s[40:41], 0, v[132:133]
	s_mov_b32 m0, s48
	s_nop 0
	global_load_lds_dwordx4 v[224:225], off
	s_waitcnt vmcnt(8)
	s_waitcnt lgkmcnt(0)
	s_barrier
	s_setprio 0
	v_mfma_f32_16x16x32_bf16 v[126:129], v[152:155], v[184:187], v[126:129]
	v_mfma_f32_16x16x32_bf16 v[122:125], v[160:163], v[184:187], v[122:125]
	v_mfma_f32_16x16x32_bf16 v[110:113], v[152:155], v[192:195], v[110:113]
	v_mfma_f32_16x16x32_bf16 v[106:109], v[160:163], v[192:195], v[106:109]
	v_mfma_f32_16x16x32_bf16 v[94:97], v[152:155], v[200:203], v[94:97]
	v_mfma_f32_16x16x32_bf16 v[90:93], v[160:163], v[200:203], v[90:93]
	v_mfma_f32_16x16x32_bf16 v[78:81], v[152:155], v[208:211], v[78:81]
	v_mfma_f32_16x16x32_bf16 v[74:77], v[160:163], v[208:211], v[74:77]
	v_mfma_f32_16x16x32_bf16 v[126:129], v[156:159], v[188:191], v[126:129]
	v_mfma_f32_16x16x32_bf16 v[122:125], v[164:167], v[188:191], v[122:125]
	v_mfma_f32_16x16x32_bf16 v[110:113], v[156:159], v[196:199], v[110:113]
	v_mfma_f32_16x16x32_bf16 v[106:109], v[164:167], v[196:199], v[106:109]
	v_mfma_f32_16x16x32_bf16 v[94:97], v[156:159], v[204:207], v[94:97]
	v_mfma_f32_16x16x32_bf16 v[90:93], v[164:167], v[204:207], v[90:93]
	v_mfma_f32_16x16x32_bf16 v[78:81], v[156:159], v[212:215], v[78:81]
	v_mfma_f32_16x16x32_bf16 v[74:77], v[164:167], v[212:215], v[74:77]
	s_setprio 2
	s_setprio 0
	v_mfma_f32_16x16x32_bf16 v[118:121], v[168:171], v[184:187], v[118:121]
	v_mfma_f32_16x16x32_bf16 v[114:117], v[176:179], v[184:187], v[114:117]
	v_mfma_f32_16x16x32_bf16 v[102:105], v[168:171], v[192:195], v[102:105]
	v_mfma_f32_16x16x32_bf16 v[98:101], v[176:179], v[192:195], v[98:101]
	v_mfma_f32_16x16x32_bf16 v[86:89], v[168:171], v[200:203], v[86:89]
	v_mfma_f32_16x16x32_bf16 v[82:85], v[176:179], v[200:203], v[82:85]
	v_mfma_f32_16x16x32_bf16 v[70:73], v[168:171], v[208:211], v[70:73]
	v_mfma_f32_16x16x32_bf16 v[66:69], v[176:179], v[208:211], v[66:69]
	v_mfma_f32_16x16x32_bf16 v[118:121], v[172:175], v[188:191], v[118:121]
	v_mfma_f32_16x16x32_bf16 v[114:117], v[180:183], v[188:191], v[114:117]
	v_mfma_f32_16x16x32_bf16 v[102:105], v[172:175], v[196:199], v[102:105]
	v_mfma_f32_16x16x32_bf16 v[98:101], v[180:183], v[196:199], v[98:101]
	v_mfma_f32_16x16x32_bf16 v[86:89], v[172:175], v[204:207], v[86:89]
	v_mfma_f32_16x16x32_bf16 v[82:85], v[180:183], v[204:207], v[82:85]
	v_mfma_f32_16x16x32_bf16 v[70:73], v[172:175], v[212:215], v[70:73]
	v_mfma_f32_16x16x32_bf16 v[66:69], v[180:183], v[212:215], v[66:69]
	s_setprio 2
	s_barrier
; #define PG8_STAGE(bufoff, gbase, voff) do { _Pragma("unroll") for (int _i = 0; _i < 2; ++_i) \
;         __builtin_amdgcn_global_load_lds((const unsigned*)((const char*)(gbase) + (voff)[_i]), (LAS unsigned*)(lds + (bufoff) + ldsw + _i * 8192), 16, 0, 0); } while (0)
; #define PG8_LDA(dst, b, h) do { _Pragma("unroll") for (int m = 0; m < 4; ++m) _Pragma("unroll") for (int k = 0; k < 2; ++k) dst[m][k] = *(const LAS bf16x8*)(lds + PG8_SA(b, h) + aoff + m * 2048 + k * 1024); } while (0)
; #define PG8_MMA(ai, bj, At, Bt) do { __builtin_amdgcn_s_setprio(1); _Pragma("unroll") for (int m = 0; m < 4; ++m) _Pragma("unroll") for (int n = 0; n < 2; ++n) _Pragma("unroll") for (int k = 0; k < 2; ++k) \
;         acc[ai][bj][m][n] = __builtin_amdgcn_mfma_f32_16x16x32_bf16(Bt[n][k], At[m][k], acc[ai][bj][m][n], 0, 0, 0); __builtin_amdgcn_s_setprio(0); } while (0)
; #define PG8_WAIT_V(n) asm volatile("s_waitcnt vmcnt(" #n ")" ::: "memory")
; #define PG8_WAIT_L(n) asm volatile("s_waitcnt lgkmcnt(" #n ")" ::: "memory")
; #define PG8_BAR __builtin_amdgcn_s_barrier()
; #define PG8_SCHED __builtin_amdgcn_sched_barrier(0)
; template <class Epi>
; __device__ __forceinline__ void gemm_phase(LAS unsigned char* lds, const Gemm g, int G, int c, const Epi& E) {
;     ...
;             PG8_LDA(At, 1, 1); PG8_STAGE(PG8_SB(1, 0), b3, voffB); PG8_STAGE(PG8_SB(1, 1), b3 + hstepB, voffB); PG8_STAGE(PG8_SA(1, 0), a3, voffA);
;             PG8_WAIT_V(8); PG8_WAIT_L(0); PG8_BAR; PG8_MMA(1, 0, At, B0); PG8_MMA(1, 1, At, B1); PG8_BAR; PG8_SCHED;
;         }
	s_add_i32 s33, s33, s46
	v_lshl_add_u64 v[216:217], v[216:217], 0, s[12:13]
	s_mov_b32 m0, s33
	ds_read_b128 v[184:187], v150 offset:49152
	ds_read_b128 v[188:191], v150 offset:50176
	ds_read_b128 v[192:195], v150 offset:51200
	ds_read_b128 v[196:199], v150 offset:52224
	ds_read_b128 v[200:203], v150 offset:53248
	ds_read_b128 v[204:207], v150 offset:54272
	ds_read_b128 v[208:211], v150 offset:55296
	ds_read_b128 v[212:215], v150 offset:56320
	global_load_lds_dwordx4 v[216:217], off
	s_add_i32 m0, s33, 0x2000
	s_add_u32 s38, s38, 0x40080
	v_lshl_add_u64 v[216:217], v[218:219], 0, s[12:13]
	s_addc_u32 s39, s39, 0
	s_add_i32 s33, s69, s46
	global_load_lds_dwordx4 v[216:217], off
	v_lshl_add_u64 v[216:217], s[38:39], 0, v[134:135]
	s_mov_b32 m0, s33
	s_nop 0
	global_load_lds_dwordx4 v[216:217], off
	v_lshl_add_u64 v[216:217], s[38:39], 0, v[130:131]
	s_add_i32 m0, s33, 0x2000
	s_nop 0
	global_load_lds_dwordx4 v[216:217], off
	v_lshl_add_u64 v[216:217], v[220:221], 0, s[12:13]
	s_mov_b32 m0, s53
	s_nop 0
	global_load_lds_dwordx4 v[216:217], off
	v_lshl_add_u64 v[216:217], v[222:223], 0, s[12:13]
	s_mov_b32 m0, s54
	s_nop 0
	global_load_lds_dwordx4 v[216:217], off
	s_waitcnt vmcnt(8)
	s_waitcnt lgkmcnt(0)
	s_barrier
	s_setprio 0
	v_mfma_f32_16x16x32_bf16 v[62:65], v[152:155], v[184:187], v[62:65]
	v_mfma_f32_16x16x32_bf16 v[58:61], v[160:163], v[184:187], v[58:61]
	v_mfma_f32_16x16x32_bf16 v[46:49], v[152:155], v[192:195], v[46:49]
	v_mfma_f32_16x16x32_bf16 v[42:45], v[160:163], v[192:195], v[42:45]
	v_mfma_f32_16x16x32_bf16 v[30:33], v[152:155], v[200:203], v[30:33]
	v_mfma_f32_16x16x32_bf16 v[26:29], v[160:163], v[200:203], v[26:29]
	v_mfma_f32_16x16x32_bf16 v[14:17], v[152:155], v[208:211], v[14:17]
	v_mfma_f32_16x16x32_bf16 v[10:13], v[160:163], v[208:211], v[10:13]
	v_mfma_f32_16x16x32_bf16 v[62:65], v[156:159], v[188:191], v[62:65]
	v_mfma_f32_16x16x32_bf16 v[58:61], v[164:167], v[188:191], v[58:61]
	v_mfma_f32_16x16x32_bf16 v[46:49], v[156:159], v[196:199], v[46:49]
	v_mfma_f32_16x16x32_bf16 v[42:45], v[164:167], v[196:199], v[42:45]
	v_mfma_f32_16x16x32_bf16 v[30:33], v[156:159], v[204:207], v[30:33]
	v_mfma_f32_16x16x32_bf16 v[26:29], v[164:167], v[204:207], v[26:29]
	v_mfma_f32_16x16x32_bf16 v[14:17], v[156:159], v[212:215], v[14:17]
	v_mfma_f32_16x16x32_bf16 v[10:13], v[164:167], v[212:215], v[10:13]
	s_setprio 2
	s_setprio 0
	v_mfma_f32_16x16x32_bf16 v[54:57], v[168:171], v[184:187], v[54:57]
	v_mfma_f32_16x16x32_bf16 v[50:53], v[176:179], v[184:187], v[50:53]
	v_mfma_f32_16x16x32_bf16 v[38:41], v[168:171], v[192:195], v[38:41]
	v_mfma_f32_16x16x32_bf16 v[34:37], v[176:179], v[192:195], v[34:37]
	v_mfma_f32_16x16x32_bf16 v[22:25], v[168:171], v[200:203], v[22:25]
	v_mfma_f32_16x16x32_bf16 v[18:21], v[176:179], v[200:203], v[18:21]
	v_mfma_f32_16x16x32_bf16 v[6:9], v[168:171], v[208:211], v[6:9]
	v_mfma_f32_16x16x32_bf16 v[2:5], v[176:179], v[208:211], v[2:5]
	v_mfma_f32_16x16x32_bf16 v[54:57], v[172:175], v[188:191], v[54:57]
	v_mfma_f32_16x16x32_bf16 v[50:53], v[180:183], v[188:191], v[50:53]
	v_mfma_f32_16x16x32_bf16 v[38:41], v[172:175], v[196:199], v[38:41]
	v_mfma_f32_16x16x32_bf16 v[34:37], v[180:183], v[196:199], v[34:37]
	v_mfma_f32_16x16x32_bf16 v[22:25], v[172:175], v[204:207], v[22:25]
	v_mfma_f32_16x16x32_bf16 v[18:21], v[180:183], v[204:207], v[18:21]
	v_mfma_f32_16x16x32_bf16 v[6:9], v[172:175], v[212:215], v[6:9]
	v_mfma_f32_16x16x32_bf16 v[2:5], v[180:183], v[212:215], v[2:5]
	s_setprio 2
	s_barrier
	s_add_i32 s68, s68, 2
	s_add_u32 s4, s4, 0x100
	s_addc_u32 s5, s5, 0
	s_add_u32 s66, s66, 0x100
	s_addc_u32 s67, s67, 0
	s_cmp_gt_u32 s68, 13
	s_cbranch_scc0 .LBB0_2084
